# v83 + GEMM K-loops: 128 s_nop wait states removed by moving the m0 write ahead of the DMA address add
# speedup vs baseline: 1.0021x; 1.0021x over previous
.LBB0_228:
	s_ashr_i32 s39, s38, 31
	s_lshl_b64 s[40:41], s[38:39], 19
	v_readlane_b32 s42, v238, 7
	v_readlane_b32 s43, v238, 8
	s_add_u32 s40, s42, s40
	s_addc_u32 s41, s43, s41
	s_and_b64 s[42:43], s[2:3], exec
	s_cselect_b32 s5, s41, s1
	s_cselect_b32 s7, s40, s0
	s_ashr_i32 s37, s36, 31
	s_lshl_b64 s[42:43], s[36:37], 19
	s_add_u32 s42, s64, s42
	s_addc_u32 s43, s65, s43
	s_and_b64 s[44:45], s[2:3], exec
	s_cselect_b32 s33, s43, s9
	s_cselect_b32 s37, s42, s8
	s_add_u32 s0, s0, 0x40080
	s_addc_u32 s1, s1, 0
	s_add_u32 s39, s8, 0x100
	s_addc_u32 s46, s9, 0
	s_mov_b32 s47, -2
	ds_read_b128 v[144:147], v170
	ds_read_b128 v[148:151], v170 offset:1024
	ds_read_b128 v[152:155], v170 offset:2048
	ds_read_b128 v[156:159], v170 offset:3072
	ds_read_b128 v[162:165], v171
	ds_read_b128 v[174:177], v171 offset:1024
	ds_read_b128 v[178:181], v171 offset:2048
	ds_read_b128 v[182:185], v171 offset:3072
	s_add_u32 s8, s0, 0xfffc0080
	s_addc_u32 s9, s1, -1
	s_cmp_eq_u32 s47, 12
	s_cselect_b32 s45, s5, s9
	s_cselect_b32 s44, s7, s8
	s_cselect_b32 s9, s33, s46
	s_cselect_b32 s8, s37, s39
	v_lshl_add_u64 v[218:219], s[0:1], 0, v[136:137]
	s_add_i32 m0, s67, 0xc000
	ds_read_b128 v[186:189], v172
	ds_read_b128 v[190:193], v172 offset:1024
	ds_read_b128 v[194:197], v172 offset:2048
	ds_read_b128 v[198:201], v172 offset:3072
	ds_read_b128 v[202:205], v172 offset:4096
	ds_read_b128 v[206:209], v172 offset:5120
	ds_read_b128 v[210:213], v172 offset:6144
	ds_read_b128 v[214:217], v172 offset:7168
	global_load_lds_dwordx4 v[218:219], off
	s_add_i32 m0, s67, 0xe000
	v_lshl_add_u64 v[218:219], s[0:1], 0, v[138:139]
	global_load_lds_dwordx4 v[218:219], off
	s_waitcnt vmcnt(8) lgkmcnt(0)
	s_barrier
	v_mfma_f32_16x16x32_bf16 v[124:127], v[144:147], v[186:189], 0
	v_mfma_f32_16x16x32_bf16 v[120:123], v[152:155], v[186:189], 0
	v_mfma_f32_16x16x32_bf16 v[108:111], v[144:147], v[194:197], 0
	v_mfma_f32_16x16x32_bf16 v[104:107], v[152:155], v[194:197], 0
	v_mfma_f32_16x16x32_bf16 v[92:95], v[144:147], v[202:205], 0
	v_mfma_f32_16x16x32_bf16 v[88:91], v[152:155], v[202:205], 0
	v_mfma_f32_16x16x32_bf16 v[76:79], v[144:147], v[210:213], 0
	v_mfma_f32_16x16x32_bf16 v[72:75], v[152:155], v[210:213], 0
	v_mfma_f32_16x16x32_bf16 v[124:127], v[148:151], v[190:193], v[124:127]
	v_mfma_f32_16x16x32_bf16 v[120:123], v[156:159], v[190:193], v[120:123]
	v_mfma_f32_16x16x32_bf16 v[108:111], v[148:151], v[198:201], v[108:111]
	v_mfma_f32_16x16x32_bf16 v[104:107], v[156:159], v[198:201], v[104:107]
	v_mfma_f32_16x16x32_bf16 v[92:95], v[148:151], v[206:209], v[92:95]
	v_mfma_f32_16x16x32_bf16 v[88:91], v[156:159], v[206:209], v[88:91]
	v_mfma_f32_16x16x32_bf16 v[76:79], v[148:151], v[214:217], v[76:79]
	v_mfma_f32_16x16x32_bf16 v[72:75], v[156:159], v[214:217], v[72:75]
	v_mfma_f32_16x16x32_bf16 v[116:119], v[162:165], v[186:189], 0
	v_mfma_f32_16x16x32_bf16 v[112:115], v[178:181], v[186:189], 0
	v_mfma_f32_16x16x32_bf16 v[100:103], v[162:165], v[194:197], 0
	v_mfma_f32_16x16x32_bf16 v[96:99], v[178:181], v[194:197], 0
	v_mfma_f32_16x16x32_bf16 v[84:87], v[162:165], v[202:205], 0
	v_mfma_f32_16x16x32_bf16 v[80:83], v[178:181], v[202:205], 0
	v_mfma_f32_16x16x32_bf16 v[68:71], v[162:165], v[210:213], 0
	v_mfma_f32_16x16x32_bf16 v[64:67], v[178:181], v[210:213], 0
	v_mfma_f32_16x16x32_bf16 v[116:119], v[174:177], v[190:193], v[116:119]
	v_mfma_f32_16x16x32_bf16 v[112:115], v[182:185], v[190:193], v[112:115]
	v_mfma_f32_16x16x32_bf16 v[100:103], v[174:177], v[198:201], v[100:103]
	v_mfma_f32_16x16x32_bf16 v[96:99], v[182:185], v[198:201], v[96:99]
	v_mfma_f32_16x16x32_bf16 v[84:87], v[174:177], v[206:209], v[84:87]
	v_mfma_f32_16x16x32_bf16 v[80:83], v[182:185], v[206:209], v[80:83]
	v_mfma_f32_16x16x32_bf16 v[68:71], v[174:177], v[214:217], v[68:71]
	v_mfma_f32_16x16x32_bf16 v[64:67], v[182:185], v[214:217], v[64:67]
	s_barrier
	s_add_i32 s52, s79, s66
	v_lshl_add_u64 v[218:219], s[8:9], 0, v[130:131]
	s_mov_b32 m0, s52
	ds_read_b128 v[186:189], v172 offset:16384
	ds_read_b128 v[190:193], v172 offset:17408
	ds_read_b128 v[194:197], v172 offset:18432
	ds_read_b128 v[198:201], v172 offset:19456
	ds_read_b128 v[202:205], v172 offset:20480
	ds_read_b128 v[206:209], v172 offset:21504
	ds_read_b128 v[210:213], v172 offset:22528
	ds_read_b128 v[214:217], v172 offset:23552
	global_load_lds_dwordx4 v[218:219], off
	s_add_i32 m0, s52, 0x2000
	s_add_u32 s52, s8, 0x40000
	v_lshl_add_u64 v[220:221], s[8:9], 0, v[134:135]
	s_addc_u32 s53, s9, 0
	s_add_i32 s56, s85, s66
	global_load_lds_dwordx4 v[220:221], off
	v_lshl_add_u64 v[222:223], s[52:53], 0, v[130:131]
	s_mov_b32 m0, s56
	v_lshl_add_u64 v[224:225], s[44:45], 0, v[132:133]
	global_load_lds_dwordx4 v[222:223], off
	s_add_i32 m0, s56, 0x2000
	v_lshl_add_u64 v[222:223], s[52:53], 0, v[134:135]
	global_load_lds_dwordx4 v[222:223], off
	s_mov_b32 m0, s67
	v_lshl_add_u64 v[222:223], s[44:45], 0, v[128:129]
	global_load_lds_dwordx4 v[222:223], off
	s_mov_b32 m0, s72
	s_nop 0
	global_load_lds_dwordx4 v[224:225], off
	s_waitcnt vmcnt(8) lgkmcnt(0)
	s_barrier
	v_mfma_f32_16x16x32_bf16 v[60:63], v[144:147], v[186:189], 0
	v_mfma_f32_16x16x32_bf16 v[56:59], v[152:155], v[186:189], 0
	v_mfma_f32_16x16x32_bf16 v[44:47], v[144:147], v[194:197], 0
	v_mfma_f32_16x16x32_bf16 v[40:43], v[152:155], v[194:197], 0
	v_mfma_f32_16x16x32_bf16 v[28:31], v[144:147], v[202:205], 0
	v_mfma_f32_16x16x32_bf16 v[24:27], v[152:155], v[202:205], 0
	v_mfma_f32_16x16x32_bf16 v[12:15], v[144:147], v[210:213], 0
	v_mfma_f32_16x16x32_bf16 v[8:11], v[152:155], v[210:213], 0
	v_mfma_f32_16x16x32_bf16 v[60:63], v[148:151], v[190:193], v[60:63]
	v_mfma_f32_16x16x32_bf16 v[56:59], v[156:159], v[190:193], v[56:59]
	v_mfma_f32_16x16x32_bf16 v[44:47], v[148:151], v[198:201], v[44:47]
	v_mfma_f32_16x16x32_bf16 v[40:43], v[156:159], v[198:201], v[40:43]
	v_mfma_f32_16x16x32_bf16 v[28:31], v[148:151], v[206:209], v[28:31]
	v_mfma_f32_16x16x32_bf16 v[24:27], v[156:159], v[206:209], v[24:27]
	v_mfma_f32_16x16x32_bf16 v[12:15], v[148:151], v[214:217], v[12:15]
	v_mfma_f32_16x16x32_bf16 v[8:11], v[156:159], v[214:217], v[8:11]
	v_mfma_f32_16x16x32_bf16 v[52:55], v[162:165], v[186:189], 0
	v_mfma_f32_16x16x32_bf16 v[48:51], v[178:181], v[186:189], 0
	v_mfma_f32_16x16x32_bf16 v[36:39], v[162:165], v[194:197], 0
	v_mfma_f32_16x16x32_bf16 v[32:35], v[178:181], v[194:197], 0
	v_mfma_f32_16x16x32_bf16 v[20:23], v[162:165], v[202:205], 0
	v_mfma_f32_16x16x32_bf16 v[16:19], v[178:181], v[202:205], 0
	v_mfma_f32_16x16x32_bf16 v[4:7], v[162:165], v[210:213], 0
	v_mfma_f32_16x16x32_bf16 v[0:3], v[178:181], v[210:213], 0
	v_mfma_f32_16x16x32_bf16 v[52:55], v[174:177], v[190:193], v[52:55]
	v_mfma_f32_16x16x32_bf16 v[48:51], v[182:185], v[190:193], v[48:51]
	v_mfma_f32_16x16x32_bf16 v[36:39], v[174:177], v[198:201], v[36:39]
	v_mfma_f32_16x16x32_bf16 v[32:35], v[182:185], v[198:201], v[32:35]
	v_mfma_f32_16x16x32_bf16 v[20:23], v[174:177], v[206:209], v[20:23]
	v_mfma_f32_16x16x32_bf16 v[16:19], v[182:185], v[206:209], v[16:19]
	v_mfma_f32_16x16x32_bf16 v[4:7], v[174:177], v[214:217], v[4:7]
	v_mfma_f32_16x16x32_bf16 v[0:3], v[182:185], v[214:217], v[0:3]
	s_barrier
	s_add_i32 s52, 0, 0x18000
	s_add_i32 s53, 0, 0x1c000
	v_add_u32_e32 v156, s52, v168
	v_add_u32_e32 v173, s53, v168
	ds_read_b128 v[144:147], v156
	ds_read_b128 v[148:151], v156 offset:1024
	ds_read_b128 v[152:155], v156 offset:2048
	ds_read_b128 v[156:159], v156 offset:3072
	ds_read_b128 v[162:165], v173
	ds_read_b128 v[174:177], v173 offset:1024
	ds_read_b128 v[178:181], v173 offset:2048
	ds_read_b128 v[182:185], v173 offset:3072
	s_add_u32 s44, s44, 0x40000
	s_addc_u32 s45, s45, 0
	s_mov_b32 m0, s73
	v_lshl_add_u64 v[226:227], s[44:45], 0, v[128:129]
	ds_read_b128 v[186:189], v172 offset:32768
	ds_read_b128 v[190:193], v172 offset:33792
	ds_read_b128 v[194:197], v172 offset:34816
	ds_read_b128 v[198:201], v172 offset:35840
	ds_read_b128 v[202:205], v172 offset:36864
	ds_read_b128 v[206:209], v172 offset:37888
	ds_read_b128 v[210:213], v172 offset:38912
	ds_read_b128 v[214:217], v172 offset:39936
	global_load_lds_dwordx4 v[226:227], off
	s_mov_b32 m0, s74
	v_lshl_add_u64 v[226:227], s[44:45], 0, v[132:133]
	global_load_lds_dwordx4 v[226:227], off
	s_waitcnt vmcnt(8) lgkmcnt(0)
	s_barrier
	v_mfma_f32_16x16x32_bf16 v[124:127], v[144:147], v[186:189], v[124:127]
	v_mfma_f32_16x16x32_bf16 v[120:123], v[152:155], v[186:189], v[120:123]
	v_mfma_f32_16x16x32_bf16 v[108:111], v[144:147], v[194:197], v[108:111]
	v_mfma_f32_16x16x32_bf16 v[104:107], v[152:155], v[194:197], v[104:107]
	v_mfma_f32_16x16x32_bf16 v[92:95], v[144:147], v[202:205], v[92:95]
	v_mfma_f32_16x16x32_bf16 v[88:91], v[152:155], v[202:205], v[88:91]
	v_mfma_f32_16x16x32_bf16 v[76:79], v[144:147], v[210:213], v[76:79]
	v_mfma_f32_16x16x32_bf16 v[72:75], v[152:155], v[210:213], v[72:75]
	v_mfma_f32_16x16x32_bf16 v[124:127], v[148:151], v[190:193], v[124:127]
	v_mfma_f32_16x16x32_bf16 v[120:123], v[156:159], v[190:193], v[120:123]
	v_mfma_f32_16x16x32_bf16 v[108:111], v[148:151], v[198:201], v[108:111]
	v_mfma_f32_16x16x32_bf16 v[104:107], v[156:159], v[198:201], v[104:107]
	v_mfma_f32_16x16x32_bf16 v[92:95], v[148:151], v[206:209], v[92:95]
	v_mfma_f32_16x16x32_bf16 v[88:91], v[156:159], v[206:209], v[88:91]
	v_mfma_f32_16x16x32_bf16 v[76:79], v[148:151], v[214:217], v[76:79]
	v_mfma_f32_16x16x32_bf16 v[72:75], v[156:159], v[214:217], v[72:75]
	v_mfma_f32_16x16x32_bf16 v[116:119], v[162:165], v[186:189], v[116:119]
	v_mfma_f32_16x16x32_bf16 v[112:115], v[178:181], v[186:189], v[112:115]
	v_mfma_f32_16x16x32_bf16 v[100:103], v[162:165], v[194:197], v[100:103]
	v_mfma_f32_16x16x32_bf16 v[96:99], v[178:181], v[194:197], v[96:99]
	v_mfma_f32_16x16x32_bf16 v[84:87], v[162:165], v[202:205], v[84:87]
	v_mfma_f32_16x16x32_bf16 v[80:83], v[178:181], v[202:205], v[80:83]
	v_mfma_f32_16x16x32_bf16 v[68:71], v[162:165], v[210:213], v[68:71]
	v_mfma_f32_16x16x32_bf16 v[64:67], v[178:181], v[210:213], v[64:67]
	v_mfma_f32_16x16x32_bf16 v[116:119], v[174:177], v[190:193], v[116:119]
	v_mfma_f32_16x16x32_bf16 v[112:115], v[182:185], v[190:193], v[112:115]
	v_mfma_f32_16x16x32_bf16 v[100:103], v[174:177], v[198:201], v[100:103]
	v_mfma_f32_16x16x32_bf16 v[96:99], v[182:185], v[198:201], v[96:99]
	v_mfma_f32_16x16x32_bf16 v[84:87], v[174:177], v[206:209], v[84:87]
	v_mfma_f32_16x16x32_bf16 v[80:83], v[182:185], v[206:209], v[80:83]
	v_mfma_f32_16x16x32_bf16 v[68:71], v[174:177], v[214:217], v[68:71]
	v_mfma_f32_16x16x32_bf16 v[64:67], v[182:185], v[214:217], v[64:67]
	s_barrier
	s_add_i32 s44, s52, s66
	v_lshl_add_u64 v[218:219], v[218:219], 0, s[30:31]
	s_mov_b32 m0, s44
	ds_read_b128 v[186:189], v172 offset:49152
	ds_read_b128 v[190:193], v172 offset:50176
	ds_read_b128 v[194:197], v172 offset:51200
	ds_read_b128 v[198:201], v172 offset:52224
	ds_read_b128 v[202:205], v172 offset:53248
	ds_read_b128 v[206:209], v172 offset:54272
	ds_read_b128 v[210:213], v172 offset:55296
	ds_read_b128 v[214:217], v172 offset:56320
	global_load_lds_dwordx4 v[218:219], off
	s_add_i32 m0, s44, 0x2000
	s_add_u32 s8, s8, 0x40080
	v_lshl_add_u64 v[218:219], v[220:221], 0, s[30:31]
	s_addc_u32 s9, s9, 0
	s_add_i32 s44, s53, s66
	global_load_lds_dwordx4 v[218:219], off
	s_mov_b32 m0, s44
	v_lshl_add_u64 v[218:219], s[8:9], 0, v[130:131]
	global_load_lds_dwordx4 v[218:219], off
	s_add_i32 m0, s44, 0x2000
	v_lshl_add_u64 v[218:219], s[8:9], 0, v[134:135]
	global_load_lds_dwordx4 v[218:219], off
	s_mov_b32 m0, s77
	v_lshl_add_u64 v[218:219], v[222:223], 0, s[30:31]
	global_load_lds_dwordx4 v[218:219], off
	s_mov_b32 m0, s78
	v_lshl_add_u64 v[218:219], v[224:225], 0, s[30:31]
	global_load_lds_dwordx4 v[218:219], off
	s_waitcnt vmcnt(8) lgkmcnt(0)
	s_barrier
	v_mfma_f32_16x16x32_bf16 v[60:63], v[144:147], v[186:189], v[60:63]
	v_mfma_f32_16x16x32_bf16 v[56:59], v[152:155], v[186:189], v[56:59]
	v_mfma_f32_16x16x32_bf16 v[44:47], v[144:147], v[194:197], v[44:47]
	v_mfma_f32_16x16x32_bf16 v[40:43], v[152:155], v[194:197], v[40:43]
	v_mfma_f32_16x16x32_bf16 v[28:31], v[144:147], v[202:205], v[28:31]
	v_mfma_f32_16x16x32_bf16 v[24:27], v[152:155], v[202:205], v[24:27]
	v_mfma_f32_16x16x32_bf16 v[12:15], v[144:147], v[210:213], v[12:15]
	v_mfma_f32_16x16x32_bf16 v[8:11], v[152:155], v[210:213], v[8:11]
	v_mfma_f32_16x16x32_bf16 v[60:63], v[148:151], v[190:193], v[60:63]
	v_mfma_f32_16x16x32_bf16 v[56:59], v[156:159], v[190:193], v[56:59]
	v_mfma_f32_16x16x32_bf16 v[44:47], v[148:151], v[198:201], v[44:47]
	v_mfma_f32_16x16x32_bf16 v[40:43], v[156:159], v[198:201], v[40:43]
	v_mfma_f32_16x16x32_bf16 v[28:31], v[148:151], v[206:209], v[28:31]
	v_mfma_f32_16x16x32_bf16 v[24:27], v[156:159], v[206:209], v[24:27]
	v_mfma_f32_16x16x32_bf16 v[12:15], v[148:151], v[214:217], v[12:15]
	v_mfma_f32_16x16x32_bf16 v[8:11], v[156:159], v[214:217], v[8:11]
	v_mfma_f32_16x16x32_bf16 v[52:55], v[162:165], v[186:189], v[52:55]
	v_mfma_f32_16x16x32_bf16 v[48:51], v[178:181], v[186:189], v[48:51]
	v_mfma_f32_16x16x32_bf16 v[36:39], v[162:165], v[194:197], v[36:39]
	v_mfma_f32_16x16x32_bf16 v[32:35], v[178:181], v[194:197], v[32:35]
	v_mfma_f32_16x16x32_bf16 v[20:23], v[162:165], v[202:205], v[20:23]
	v_mfma_f32_16x16x32_bf16 v[16:19], v[178:181], v[202:205], v[16:19]
	v_mfma_f32_16x16x32_bf16 v[4:7], v[162:165], v[210:213], v[4:7]
	v_mfma_f32_16x16x32_bf16 v[0:3], v[178:181], v[210:213], v[0:3]
	v_mfma_f32_16x16x32_bf16 v[52:55], v[174:177], v[190:193], v[52:55]
	v_mfma_f32_16x16x32_bf16 v[48:51], v[182:185], v[190:193], v[48:51]
	v_mfma_f32_16x16x32_bf16 v[36:39], v[174:177], v[198:201], v[36:39]
	v_mfma_f32_16x16x32_bf16 v[32:35], v[182:185], v[198:201], v[32:35]
	v_mfma_f32_16x16x32_bf16 v[20:23], v[174:177], v[206:209], v[20:23]
	v_mfma_f32_16x16x32_bf16 v[16:19], v[182:185], v[206:209], v[16:19]
	v_mfma_f32_16x16x32_bf16 v[4:7], v[174:177], v[214:217], v[4:7]
	v_mfma_f32_16x16x32_bf16 v[0:3], v[182:185], v[214:217], v[0:3]
	s_barrier
	s_add_i32 s47, s47, 2
	s_add_u32 s0, s0, 0x100
	s_addc_u32 s1, s1, 0
	s_add_u32 s39, s39, 0x100
	s_addc_u32 s46, s46, 0
	s_cmp_gt_u32 s47, 13
	s_cbranch_scc0 .LBB0_229
	s_branch .Lpeel_exit_1
.LBB0_229:
	ds_read_b128 v[144:147], v170
	ds_read_b128 v[148:151], v170 offset:1024
	ds_read_b128 v[152:155], v170 offset:2048
	ds_read_b128 v[156:159], v170 offset:3072
	ds_read_b128 v[162:165], v171
	ds_read_b128 v[174:177], v171 offset:1024
	ds_read_b128 v[178:181], v171 offset:2048
	ds_read_b128 v[182:185], v171 offset:3072
	s_add_u32 s8, s0, 0xfffc0080
	s_addc_u32 s9, s1, -1
	s_cmp_eq_u32 s47, 12
	s_cselect_b32 s45, s5, s9
	s_cselect_b32 s44, s7, s8
	s_cselect_b32 s9, s33, s46
	s_cselect_b32 s8, s37, s39
	v_lshl_add_u64 v[218:219], s[0:1], 0, v[136:137]
	s_add_i32 m0, s67, 0xc000
	ds_read_b128 v[186:189], v172
	ds_read_b128 v[190:193], v172 offset:1024
	ds_read_b128 v[194:197], v172 offset:2048
	ds_read_b128 v[198:201], v172 offset:3072
	ds_read_b128 v[202:205], v172 offset:4096
	ds_read_b128 v[206:209], v172 offset:5120
	ds_read_b128 v[210:213], v172 offset:6144
	ds_read_b128 v[214:217], v172 offset:7168
	global_load_lds_dwordx4 v[218:219], off
	s_add_i32 m0, s67, 0xe000
	v_lshl_add_u64 v[218:219], s[0:1], 0, v[138:139]
	global_load_lds_dwordx4 v[218:219], off
	s_waitcnt vmcnt(8) lgkmcnt(0)
	s_barrier
	v_mfma_f32_16x16x32_bf16 v[124:127], v[144:147], v[186:189], v[124:127]
	v_mfma_f32_16x16x32_bf16 v[120:123], v[152:155], v[186:189], v[120:123]
	v_mfma_f32_16x16x32_bf16 v[108:111], v[144:147], v[194:197], v[108:111]
	v_mfma_f32_16x16x32_bf16 v[104:107], v[152:155], v[194:197], v[104:107]
	v_mfma_f32_16x16x32_bf16 v[92:95], v[144:147], v[202:205], v[92:95]
	v_mfma_f32_16x16x32_bf16 v[88:91], v[152:155], v[202:205], v[88:91]
	v_mfma_f32_16x16x32_bf16 v[76:79], v[144:147], v[210:213], v[76:79]
	v_mfma_f32_16x16x32_bf16 v[72:75], v[152:155], v[210:213], v[72:75]
	v_mfma_f32_16x16x32_bf16 v[124:127], v[148:151], v[190:193], v[124:127]
	v_mfma_f32_16x16x32_bf16 v[120:123], v[156:159], v[190:193], v[120:123]
	v_mfma_f32_16x16x32_bf16 v[108:111], v[148:151], v[198:201], v[108:111]
	v_mfma_f32_16x16x32_bf16 v[104:107], v[156:159], v[198:201], v[104:107]
	v_mfma_f32_16x16x32_bf16 v[92:95], v[148:151], v[206:209], v[92:95]
	v_mfma_f32_16x16x32_bf16 v[88:91], v[156:159], v[206:209], v[88:91]
	v_mfma_f32_16x16x32_bf16 v[76:79], v[148:151], v[214:217], v[76:79]
	v_mfma_f32_16x16x32_bf16 v[72:75], v[156:159], v[214:217], v[72:75]
	v_mfma_f32_16x16x32_bf16 v[116:119], v[162:165], v[186:189], v[116:119]
	v_mfma_f32_16x16x32_bf16 v[112:115], v[178:181], v[186:189], v[112:115]
	v_mfma_f32_16x16x32_bf16 v[100:103], v[162:165], v[194:197], v[100:103]
	v_mfma_f32_16x16x32_bf16 v[96:99], v[178:181], v[194:197], v[96:99]
	v_mfma_f32_16x16x32_bf16 v[84:87], v[162:165], v[202:205], v[84:87]
	v_mfma_f32_16x16x32_bf16 v[80:83], v[178:181], v[202:205], v[80:83]
	v_mfma_f32_16x16x32_bf16 v[68:71], v[162:165], v[210:213], v[68:71]
	v_mfma_f32_16x16x32_bf16 v[64:67], v[178:181], v[210:213], v[64:67]
	v_mfma_f32_16x16x32_bf16 v[116:119], v[174:177], v[190:193], v[116:119]
	v_mfma_f32_16x16x32_bf16 v[112:115], v[182:185], v[190:193], v[112:115]
	v_mfma_f32_16x16x32_bf16 v[100:103], v[174:177], v[198:201], v[100:103]
	v_mfma_f32_16x16x32_bf16 v[96:99], v[182:185], v[198:201], v[96:99]
	v_mfma_f32_16x16x32_bf16 v[84:87], v[174:177], v[206:209], v[84:87]
	v_mfma_f32_16x16x32_bf16 v[80:83], v[182:185], v[206:209], v[80:83]
	v_mfma_f32_16x16x32_bf16 v[68:71], v[174:177], v[214:217], v[68:71]
	v_mfma_f32_16x16x32_bf16 v[64:67], v[182:185], v[214:217], v[64:67]
	s_barrier
	s_add_i32 s52, s79, s66
	v_lshl_add_u64 v[218:219], s[8:9], 0, v[130:131]
	s_mov_b32 m0, s52
	ds_read_b128 v[186:189], v172 offset:16384
	ds_read_b128 v[190:193], v172 offset:17408
	ds_read_b128 v[194:197], v172 offset:18432
	ds_read_b128 v[198:201], v172 offset:19456
	ds_read_b128 v[202:205], v172 offset:20480
	ds_read_b128 v[206:209], v172 offset:21504
	ds_read_b128 v[210:213], v172 offset:22528
	ds_read_b128 v[214:217], v172 offset:23552
	global_load_lds_dwordx4 v[218:219], off
	s_add_i32 m0, s52, 0x2000
	s_add_u32 s52, s8, 0x40000
	v_lshl_add_u64 v[220:221], s[8:9], 0, v[134:135]
	s_addc_u32 s53, s9, 0
	s_add_i32 s56, s85, s66
	global_load_lds_dwordx4 v[220:221], off
	v_lshl_add_u64 v[222:223], s[52:53], 0, v[130:131]
	s_mov_b32 m0, s56
	v_lshl_add_u64 v[224:225], s[44:45], 0, v[132:133]
	global_load_lds_dwordx4 v[222:223], off
	s_add_i32 m0, s56, 0x2000
	v_lshl_add_u64 v[222:223], s[52:53], 0, v[134:135]
	global_load_lds_dwordx4 v[222:223], off
	s_mov_b32 m0, s67
	v_lshl_add_u64 v[222:223], s[44:45], 0, v[128:129]
	global_load_lds_dwordx4 v[222:223], off
	s_mov_b32 m0, s72
	s_nop 0
	global_load_lds_dwordx4 v[224:225], off
	s_waitcnt vmcnt(8) lgkmcnt(0)
	s_barrier
	v_mfma_f32_16x16x32_bf16 v[60:63], v[144:147], v[186:189], v[60:63]
	v_mfma_f32_16x16x32_bf16 v[56:59], v[152:155], v[186:189], v[56:59]
	v_mfma_f32_16x16x32_bf16 v[44:47], v[144:147], v[194:197], v[44:47]
	v_mfma_f32_16x16x32_bf16 v[40:43], v[152:155], v[194:197], v[40:43]
	v_mfma_f32_16x16x32_bf16 v[28:31], v[144:147], v[202:205], v[28:31]
	v_mfma_f32_16x16x32_bf16 v[24:27], v[152:155], v[202:205], v[24:27]
	v_mfma_f32_16x16x32_bf16 v[12:15], v[144:147], v[210:213], v[12:15]
	v_mfma_f32_16x16x32_bf16 v[8:11], v[152:155], v[210:213], v[8:11]
	v_mfma_f32_16x16x32_bf16 v[60:63], v[148:151], v[190:193], v[60:63]
	v_mfma_f32_16x16x32_bf16 v[56:59], v[156:159], v[190:193], v[56:59]
	v_mfma_f32_16x16x32_bf16 v[44:47], v[148:151], v[198:201], v[44:47]
	v_mfma_f32_16x16x32_bf16 v[40:43], v[156:159], v[198:201], v[40:43]
	v_mfma_f32_16x16x32_bf16 v[28:31], v[148:151], v[206:209], v[28:31]
	v_mfma_f32_16x16x32_bf16 v[24:27], v[156:159], v[206:209], v[24:27]
	v_mfma_f32_16x16x32_bf16 v[12:15], v[148:151], v[214:217], v[12:15]
	v_mfma_f32_16x16x32_bf16 v[8:11], v[156:159], v[214:217], v[8:11]
	v_mfma_f32_16x16x32_bf16 v[52:55], v[162:165], v[186:189], v[52:55]
	v_mfma_f32_16x16x32_bf16 v[48:51], v[178:181], v[186:189], v[48:51]
	v_mfma_f32_16x16x32_bf16 v[36:39], v[162:165], v[194:197], v[36:39]
	v_mfma_f32_16x16x32_bf16 v[32:35], v[178:181], v[194:197], v[32:35]
	v_mfma_f32_16x16x32_bf16 v[20:23], v[162:165], v[202:205], v[20:23]
	v_mfma_f32_16x16x32_bf16 v[16:19], v[178:181], v[202:205], v[16:19]
	v_mfma_f32_16x16x32_bf16 v[4:7], v[162:165], v[210:213], v[4:7]
	v_mfma_f32_16x16x32_bf16 v[0:3], v[178:181], v[210:213], v[0:3]
	v_mfma_f32_16x16x32_bf16 v[52:55], v[174:177], v[190:193], v[52:55]
	v_mfma_f32_16x16x32_bf16 v[48:51], v[182:185], v[190:193], v[48:51]
	v_mfma_f32_16x16x32_bf16 v[36:39], v[174:177], v[198:201], v[36:39]
	v_mfma_f32_16x16x32_bf16 v[32:35], v[182:185], v[198:201], v[32:35]
	v_mfma_f32_16x16x32_bf16 v[20:23], v[174:177], v[206:209], v[20:23]
	v_mfma_f32_16x16x32_bf16 v[16:19], v[182:185], v[206:209], v[16:19]
	v_mfma_f32_16x16x32_bf16 v[4:7], v[174:177], v[214:217], v[4:7]
	v_mfma_f32_16x16x32_bf16 v[0:3], v[182:185], v[214:217], v[0:3]
	s_barrier
	s_add_i32 s52, 0, 0x18000
	s_add_i32 s53, 0, 0x1c000
	v_add_u32_e32 v156, s52, v168
	v_add_u32_e32 v173, s53, v168
	ds_read_b128 v[144:147], v156
	ds_read_b128 v[148:151], v156 offset:1024
	ds_read_b128 v[152:155], v156 offset:2048
	ds_read_b128 v[156:159], v156 offset:3072
	ds_read_b128 v[162:165], v173
	ds_read_b128 v[174:177], v173 offset:1024
	ds_read_b128 v[178:181], v173 offset:2048
	ds_read_b128 v[182:185], v173 offset:3072
	s_add_u32 s44, s44, 0x40000
	s_addc_u32 s45, s45, 0
	s_mov_b32 m0, s73
	v_lshl_add_u64 v[226:227], s[44:45], 0, v[128:129]
	ds_read_b128 v[186:189], v172 offset:32768
	ds_read_b128 v[190:193], v172 offset:33792
	ds_read_b128 v[194:197], v172 offset:34816
	ds_read_b128 v[198:201], v172 offset:35840
	ds_read_b128 v[202:205], v172 offset:36864
	ds_read_b128 v[206:209], v172 offset:37888
	ds_read_b128 v[210:213], v172 offset:38912
	ds_read_b128 v[214:217], v172 offset:39936
	global_load_lds_dwordx4 v[226:227], off
	s_mov_b32 m0, s74
	v_lshl_add_u64 v[226:227], s[44:45], 0, v[132:133]
	global_load_lds_dwordx4 v[226:227], off
	s_waitcnt vmcnt(8) lgkmcnt(0)
	s_barrier
	v_mfma_f32_16x16x32_bf16 v[124:127], v[144:147], v[186:189], v[124:127]
	v_mfma_f32_16x16x32_bf16 v[120:123], v[152:155], v[186:189], v[120:123]
	v_mfma_f32_16x16x32_bf16 v[108:111], v[144:147], v[194:197], v[108:111]
	v_mfma_f32_16x16x32_bf16 v[104:107], v[152:155], v[194:197], v[104:107]
	v_mfma_f32_16x16x32_bf16 v[92:95], v[144:147], v[202:205], v[92:95]
	v_mfma_f32_16x16x32_bf16 v[88:91], v[152:155], v[202:205], v[88:91]
	v_mfma_f32_16x16x32_bf16 v[76:79], v[144:147], v[210:213], v[76:79]
	v_mfma_f32_16x16x32_bf16 v[72:75], v[152:155], v[210:213], v[72:75]
	v_mfma_f32_16x16x32_bf16 v[124:127], v[148:151], v[190:193], v[124:127]
	v_mfma_f32_16x16x32_bf16 v[120:123], v[156:159], v[190:193], v[120:123]
	v_mfma_f32_16x16x32_bf16 v[108:111], v[148:151], v[198:201], v[108:111]
	v_mfma_f32_16x16x32_bf16 v[104:107], v[156:159], v[198:201], v[104:107]
	v_mfma_f32_16x16x32_bf16 v[92:95], v[148:151], v[206:209], v[92:95]
	v_mfma_f32_16x16x32_bf16 v[88:91], v[156:159], v[206:209], v[88:91]
	v_mfma_f32_16x16x32_bf16 v[76:79], v[148:151], v[214:217], v[76:79]
	v_mfma_f32_16x16x32_bf16 v[72:75], v[156:159], v[214:217], v[72:75]
	v_mfma_f32_16x16x32_bf16 v[116:119], v[162:165], v[186:189], v[116:119]
	v_mfma_f32_16x16x32_bf16 v[112:115], v[178:181], v[186:189], v[112:115]
	v_mfma_f32_16x16x32_bf16 v[100:103], v[162:165], v[194:197], v[100:103]
	v_mfma_f32_16x16x32_bf16 v[96:99], v[178:181], v[194:197], v[96:99]
	v_mfma_f32_16x16x32_bf16 v[84:87], v[162:165], v[202:205], v[84:87]
	v_mfma_f32_16x16x32_bf16 v[80:83], v[178:181], v[202:205], v[80:83]
	v_mfma_f32_16x16x32_bf16 v[68:71], v[162:165], v[210:213], v[68:71]
	v_mfma_f32_16x16x32_bf16 v[64:67], v[178:181], v[210:213], v[64:67]
	v_mfma_f32_16x16x32_bf16 v[116:119], v[174:177], v[190:193], v[116:119]
	v_mfma_f32_16x16x32_bf16 v[112:115], v[182:185], v[190:193], v[112:115]
	v_mfma_f32_16x16x32_bf16 v[100:103], v[174:177], v[198:201], v[100:103]
	v_mfma_f32_16x16x32_bf16 v[96:99], v[182:185], v[198:201], v[96:99]
	v_mfma_f32_16x16x32_bf16 v[84:87], v[174:177], v[206:209], v[84:87]
	v_mfma_f32_16x16x32_bf16 v[80:83], v[182:185], v[206:209], v[80:83]
	v_mfma_f32_16x16x32_bf16 v[68:71], v[174:177], v[214:217], v[68:71]
	v_mfma_f32_16x16x32_bf16 v[64:67], v[182:185], v[214:217], v[64:67]
	s_barrier
	s_add_i32 s44, s52, s66
	v_lshl_add_u64 v[218:219], v[218:219], 0, s[30:31]
	s_mov_b32 m0, s44
	ds_read_b128 v[186:189], v172 offset:49152
	ds_read_b128 v[190:193], v172 offset:50176
	ds_read_b128 v[194:197], v172 offset:51200
	ds_read_b128 v[198:201], v172 offset:52224
	ds_read_b128 v[202:205], v172 offset:53248
	ds_read_b128 v[206:209], v172 offset:54272
	ds_read_b128 v[210:213], v172 offset:55296
	ds_read_b128 v[214:217], v172 offset:56320
	global_load_lds_dwordx4 v[218:219], off
	s_add_i32 m0, s44, 0x2000
	s_add_u32 s8, s8, 0x40080
	v_lshl_add_u64 v[218:219], v[220:221], 0, s[30:31]
	s_addc_u32 s9, s9, 0
	s_add_i32 s44, s53, s66
	global_load_lds_dwordx4 v[218:219], off
	s_mov_b32 m0, s44
	v_lshl_add_u64 v[218:219], s[8:9], 0, v[130:131]
	global_load_lds_dwordx4 v[218:219], off
	s_add_i32 m0, s44, 0x2000
	v_lshl_add_u64 v[218:219], s[8:9], 0, v[134:135]
	global_load_lds_dwordx4 v[218:219], off
	s_mov_b32 m0, s77
	v_lshl_add_u64 v[218:219], v[222:223], 0, s[30:31]
	global_load_lds_dwordx4 v[218:219], off
	s_mov_b32 m0, s78
	v_lshl_add_u64 v[218:219], v[224:225], 0, s[30:31]
	global_load_lds_dwordx4 v[218:219], off
	s_waitcnt vmcnt(8) lgkmcnt(0)
	s_barrier
	v_mfma_f32_16x16x32_bf16 v[60:63], v[144:147], v[186:189], v[60:63]
	v_mfma_f32_16x16x32_bf16 v[56:59], v[152:155], v[186:189], v[56:59]
	v_mfma_f32_16x16x32_bf16 v[44:47], v[144:147], v[194:197], v[44:47]
	v_mfma_f32_16x16x32_bf16 v[40:43], v[152:155], v[194:197], v[40:43]
	v_mfma_f32_16x16x32_bf16 v[28:31], v[144:147], v[202:205], v[28:31]
	v_mfma_f32_16x16x32_bf16 v[24:27], v[152:155], v[202:205], v[24:27]
	v_mfma_f32_16x16x32_bf16 v[12:15], v[144:147], v[210:213], v[12:15]
	v_mfma_f32_16x16x32_bf16 v[8:11], v[152:155], v[210:213], v[8:11]
	v_mfma_f32_16x16x32_bf16 v[60:63], v[148:151], v[190:193], v[60:63]
	v_mfma_f32_16x16x32_bf16 v[56:59], v[156:159], v[190:193], v[56:59]
	v_mfma_f32_16x16x32_bf16 v[44:47], v[148:151], v[198:201], v[44:47]
	v_mfma_f32_16x16x32_bf16 v[40:43], v[156:159], v[198:201], v[40:43]
	v_mfma_f32_16x16x32_bf16 v[28:31], v[148:151], v[206:209], v[28:31]
	v_mfma_f32_16x16x32_bf16 v[24:27], v[156:159], v[206:209], v[24:27]
	v_mfma_f32_16x16x32_bf16 v[12:15], v[148:151], v[214:217], v[12:15]
	v_mfma_f32_16x16x32_bf16 v[8:11], v[156:159], v[214:217], v[8:11]
	v_mfma_f32_16x16x32_bf16 v[52:55], v[162:165], v[186:189], v[52:55]
	v_mfma_f32_16x16x32_bf16 v[48:51], v[178:181], v[186:189], v[48:51]
	v_mfma_f32_16x16x32_bf16 v[36:39], v[162:165], v[194:197], v[36:39]
	v_mfma_f32_16x16x32_bf16 v[32:35], v[178:181], v[194:197], v[32:35]
	v_mfma_f32_16x16x32_bf16 v[20:23], v[162:165], v[202:205], v[20:23]
	v_mfma_f32_16x16x32_bf16 v[16:19], v[178:181], v[202:205], v[16:19]
	v_mfma_f32_16x16x32_bf16 v[4:7], v[162:165], v[210:213], v[4:7]
	v_mfma_f32_16x16x32_bf16 v[0:3], v[178:181], v[210:213], v[0:3]
	v_mfma_f32_16x16x32_bf16 v[52:55], v[174:177], v[190:193], v[52:55]
	v_mfma_f32_16x16x32_bf16 v[48:51], v[182:185], v[190:193], v[48:51]
	v_mfma_f32_16x16x32_bf16 v[36:39], v[174:177], v[198:201], v[36:39]
	v_mfma_f32_16x16x32_bf16 v[32:35], v[182:185], v[198:201], v[32:35]
	v_mfma_f32_16x16x32_bf16 v[20:23], v[174:177], v[206:209], v[20:23]
	v_mfma_f32_16x16x32_bf16 v[16:19], v[182:185], v[206:209], v[16:19]
	v_mfma_f32_16x16x32_bf16 v[4:7], v[174:177], v[214:217], v[4:7]
	v_mfma_f32_16x16x32_bf16 v[0:3], v[182:185], v[214:217], v[0:3]
	s_barrier
	s_add_i32 s47, s47, 2
	s_add_u32 s0, s0, 0x100
	s_addc_u32 s1, s1, 0
	s_add_u32 s39, s39, 0x100
	s_addc_u32 s46, s46, 0
	s_cmp_gt_u32 s47, 13
	s_cbranch_scc0 .LBB0_229

.LBB0_550:
	s_add_u32 s59, s16, 0x100
	s_addc_u32 s60, s17, 0
	s_mov_b32 s61, -2
	s_waitcnt lgkmcnt(0)
	ds_read_b128 v[128:131], v188
	ds_read_b128 v[132:135], v188 offset:1024
	ds_read_b128 v[136:139], v188 offset:2048
	ds_read_b128 v[140:143], v188 offset:3072
	ds_read_b128 v[144:147], v189
	ds_read_b128 v[148:151], v189 offset:1024
	ds_read_b128 v[152:155], v189 offset:2048
	ds_read_b128 v[156:159], v189 offset:3072
	s_add_u32 s16, s0, 0x100
	s_addc_u32 s17, s1, 0
	s_cmp_eq_u32 s61, 16
	s_cselect_b32 s35, s7, s17
	s_cselect_b32 s34, s6, s16
	s_cselect_b32 s29, s15, s60
	s_cselect_b32 s28, s14, s59
	v_lshl_add_u64 v[220:221], s[0:1], 0, v[170:171]
	s_add_i32 m0, s39, 0xc000
	ds_read_b128 v[178:181], v190
	ds_read_b128 v[192:195], v190 offset:1024
	ds_read_b128 v[196:199], v190 offset:2048
	ds_read_b128 v[200:203], v190 offset:3072
	ds_read_b128 v[204:207], v190 offset:4096
	ds_read_b128 v[208:211], v190 offset:5120
	ds_read_b128 v[212:215], v190 offset:6144
	ds_read_b128 v[216:219], v190 offset:7168
	global_load_lds_dwordx4 v[220:221], off
	s_add_i32 m0, s39, 0xe000
	v_lshl_add_u64 v[220:221], s[0:1], 0, v[172:173]
	global_load_lds_dwordx4 v[220:221], off
	s_waitcnt vmcnt(8) lgkmcnt(0)
	s_barrier
	v_mfma_f32_16x16x32_bf16 v[124:127], v[128:131], v[178:181], 0
	v_mfma_f32_16x16x32_bf16 v[120:123], v[136:139], v[178:181], 0
	v_mfma_f32_16x16x32_bf16 v[108:111], v[128:131], v[196:199], 0
	v_mfma_f32_16x16x32_bf16 v[104:107], v[136:139], v[196:199], 0
	v_mfma_f32_16x16x32_bf16 v[92:95], v[128:131], v[204:207], 0
	v_mfma_f32_16x16x32_bf16 v[88:91], v[136:139], v[204:207], 0
	v_mfma_f32_16x16x32_bf16 v[76:79], v[128:131], v[212:215], 0
	v_mfma_f32_16x16x32_bf16 v[72:75], v[136:139], v[212:215], 0
	v_mfma_f32_16x16x32_bf16 v[124:127], v[132:135], v[192:195], v[124:127]
	v_mfma_f32_16x16x32_bf16 v[120:123], v[140:143], v[192:195], v[120:123]
	v_mfma_f32_16x16x32_bf16 v[108:111], v[132:135], v[200:203], v[108:111]
	v_mfma_f32_16x16x32_bf16 v[104:107], v[140:143], v[200:203], v[104:107]
	v_mfma_f32_16x16x32_bf16 v[92:95], v[132:135], v[208:211], v[92:95]
	v_mfma_f32_16x16x32_bf16 v[88:91], v[140:143], v[208:211], v[88:91]
	v_mfma_f32_16x16x32_bf16 v[76:79], v[132:135], v[216:219], v[76:79]
	v_mfma_f32_16x16x32_bf16 v[72:75], v[140:143], v[216:219], v[72:75]
	v_mfma_f32_16x16x32_bf16 v[116:119], v[144:147], v[178:181], 0
	v_mfma_f32_16x16x32_bf16 v[112:115], v[152:155], v[178:181], 0
	v_mfma_f32_16x16x32_bf16 v[100:103], v[144:147], v[196:199], 0
	v_mfma_f32_16x16x32_bf16 v[96:99], v[152:155], v[196:199], 0
	v_mfma_f32_16x16x32_bf16 v[84:87], v[144:147], v[204:207], 0
	v_mfma_f32_16x16x32_bf16 v[80:83], v[152:155], v[204:207], 0
	v_mfma_f32_16x16x32_bf16 v[68:71], v[144:147], v[212:215], 0
	v_mfma_f32_16x16x32_bf16 v[64:67], v[152:155], v[212:215], 0
	v_mfma_f32_16x16x32_bf16 v[116:119], v[148:151], v[192:195], v[116:119]
	v_mfma_f32_16x16x32_bf16 v[112:115], v[156:159], v[192:195], v[112:115]
	v_mfma_f32_16x16x32_bf16 v[100:103], v[148:151], v[200:203], v[100:103]
	v_mfma_f32_16x16x32_bf16 v[96:99], v[156:159], v[200:203], v[96:99]
	v_mfma_f32_16x16x32_bf16 v[84:87], v[148:151], v[208:211], v[84:87]
	v_mfma_f32_16x16x32_bf16 v[80:83], v[156:159], v[208:211], v[80:83]
	v_mfma_f32_16x16x32_bf16 v[68:71], v[148:151], v[216:219], v[68:71]
	v_mfma_f32_16x16x32_bf16 v[64:67], v[156:159], v[216:219], v[64:67]
	s_barrier
	s_add_i32 s0, s50, s38
	v_lshl_add_u64 v[220:221], s[28:29], 0, v[164:165]
	s_mov_b32 m0, s0
	ds_read_b128 v[178:181], v190 offset:16384
	ds_read_b128 v[192:195], v190 offset:17408
	ds_read_b128 v[196:199], v190 offset:18432
	ds_read_b128 v[200:203], v190 offset:19456
	ds_read_b128 v[204:207], v190 offset:20480
	ds_read_b128 v[208:211], v190 offset:21504
	ds_read_b128 v[212:215], v190 offset:22528
	ds_read_b128 v[216:219], v190 offset:23552
	global_load_lds_dwordx4 v[220:221], off
	s_add_i32 m0, s0, 0x2000
	s_add_u32 s0, s28, 0x50000
	v_lshl_add_u64 v[222:223], s[28:29], 0, v[168:169]
	s_addc_u32 s1, s29, 0
	s_add_i32 s62, s51, s38
	global_load_lds_dwordx4 v[222:223], off
	v_lshl_add_u64 v[224:225], s[0:1], 0, v[164:165]
	s_mov_b32 m0, s62
	v_lshl_add_u64 v[226:227], s[34:35], 0, v[166:167]
	global_load_lds_dwordx4 v[224:225], off
	s_add_i32 m0, s62, 0x2000
	v_lshl_add_u64 v[224:225], s[0:1], 0, v[168:169]
	global_load_lds_dwordx4 v[224:225], off
	s_mov_b32 m0, s39
	v_lshl_add_u64 v[224:225], s[34:35], 0, v[162:163]
	global_load_lds_dwordx4 v[224:225], off
	s_mov_b32 m0, s40
	s_nop 0
	global_load_lds_dwordx4 v[226:227], off
	s_waitcnt vmcnt(8) lgkmcnt(0)
	s_barrier
	v_mfma_f32_16x16x32_bf16 v[60:63], v[128:131], v[178:181], 0
	v_mfma_f32_16x16x32_bf16 v[56:59], v[136:139], v[178:181], 0
	v_mfma_f32_16x16x32_bf16 v[44:47], v[128:131], v[196:199], 0
	v_mfma_f32_16x16x32_bf16 v[40:43], v[136:139], v[196:199], 0
	v_mfma_f32_16x16x32_bf16 v[28:31], v[128:131], v[204:207], 0
	v_mfma_f32_16x16x32_bf16 v[24:27], v[136:139], v[204:207], 0
	v_mfma_f32_16x16x32_bf16 v[12:15], v[128:131], v[212:215], 0
	v_mfma_f32_16x16x32_bf16 v[8:11], v[136:139], v[212:215], 0
	v_mfma_f32_16x16x32_bf16 v[60:63], v[132:135], v[192:195], v[60:63]
	v_mfma_f32_16x16x32_bf16 v[56:59], v[140:143], v[192:195], v[56:59]
	v_mfma_f32_16x16x32_bf16 v[44:47], v[132:135], v[200:203], v[44:47]
	v_mfma_f32_16x16x32_bf16 v[40:43], v[140:143], v[200:203], v[40:43]
	v_mfma_f32_16x16x32_bf16 v[28:31], v[132:135], v[208:211], v[28:31]
	v_mfma_f32_16x16x32_bf16 v[24:27], v[140:143], v[208:211], v[24:27]
	v_mfma_f32_16x16x32_bf16 v[12:15], v[132:135], v[216:219], v[12:15]
	v_mfma_f32_16x16x32_bf16 v[8:11], v[140:143], v[216:219], v[8:11]
	v_mfma_f32_16x16x32_bf16 v[52:55], v[144:147], v[178:181], 0
	v_mfma_f32_16x16x32_bf16 v[48:51], v[152:155], v[178:181], 0
	v_mfma_f32_16x16x32_bf16 v[36:39], v[144:147], v[196:199], 0
	v_mfma_f32_16x16x32_bf16 v[32:35], v[152:155], v[196:199], 0
	v_mfma_f32_16x16x32_bf16 v[20:23], v[144:147], v[204:207], 0
	v_mfma_f32_16x16x32_bf16 v[16:19], v[152:155], v[204:207], 0
	v_mfma_f32_16x16x32_bf16 v[4:7], v[144:147], v[212:215], 0
	v_mfma_f32_16x16x32_bf16 v[0:3], v[152:155], v[212:215], 0
	v_mfma_f32_16x16x32_bf16 v[52:55], v[148:151], v[192:195], v[52:55]
	v_mfma_f32_16x16x32_bf16 v[48:51], v[156:159], v[192:195], v[48:51]
	v_mfma_f32_16x16x32_bf16 v[36:39], v[148:151], v[200:203], v[36:39]
	v_mfma_f32_16x16x32_bf16 v[32:35], v[156:159], v[200:203], v[32:35]
	v_mfma_f32_16x16x32_bf16 v[20:23], v[148:151], v[208:211], v[20:23]
	v_mfma_f32_16x16x32_bf16 v[16:19], v[156:159], v[208:211], v[16:19]
	v_mfma_f32_16x16x32_bf16 v[4:7], v[148:151], v[216:219], v[4:7]
	v_mfma_f32_16x16x32_bf16 v[0:3], v[156:159], v[216:219], v[0:3]
	s_barrier
	s_add_i32 s62, 0, 0x18000
	s_add_i32 s63, 0, 0x1c000
	v_add_u32_e32 v140, s62, v183
	v_add_u32_e32 v156, s63, v183
	ds_read_b128 v[128:131], v140
	ds_read_b128 v[132:135], v140 offset:1024
	ds_read_b128 v[136:139], v140 offset:2048
	ds_read_b128 v[140:143], v140 offset:3072
	ds_read_b128 v[144:147], v156
	ds_read_b128 v[148:151], v156 offset:1024
	ds_read_b128 v[152:155], v156 offset:2048
	ds_read_b128 v[156:159], v156 offset:3072
	s_add_u32 s0, s34, 0x50000
	s_addc_u32 s1, s35, 0
	s_mov_b32 m0, s41
	v_lshl_add_u64 v[228:229], s[0:1], 0, v[162:163]
	ds_read_b128 v[178:181], v190 offset:32768
	ds_read_b128 v[192:195], v190 offset:33792
	ds_read_b128 v[196:199], v190 offset:34816
	ds_read_b128 v[200:203], v190 offset:35840
	ds_read_b128 v[204:207], v190 offset:36864
	ds_read_b128 v[208:211], v190 offset:37888
	ds_read_b128 v[212:215], v190 offset:38912
	ds_read_b128 v[216:219], v190 offset:39936
	global_load_lds_dwordx4 v[228:229], off
	s_mov_b32 m0, s42
	v_lshl_add_u64 v[228:229], s[0:1], 0, v[166:167]
	global_load_lds_dwordx4 v[228:229], off
	s_waitcnt vmcnt(8) lgkmcnt(0)
	s_barrier
	v_mfma_f32_16x16x32_bf16 v[124:127], v[128:131], v[178:181], v[124:127]
	v_mfma_f32_16x16x32_bf16 v[120:123], v[136:139], v[178:181], v[120:123]
	v_mfma_f32_16x16x32_bf16 v[108:111], v[128:131], v[196:199], v[108:111]
	v_mfma_f32_16x16x32_bf16 v[104:107], v[136:139], v[196:199], v[104:107]
	v_mfma_f32_16x16x32_bf16 v[92:95], v[128:131], v[204:207], v[92:95]
	v_mfma_f32_16x16x32_bf16 v[88:91], v[136:139], v[204:207], v[88:91]
	v_mfma_f32_16x16x32_bf16 v[76:79], v[128:131], v[212:215], v[76:79]
	v_mfma_f32_16x16x32_bf16 v[72:75], v[136:139], v[212:215], v[72:75]
	v_mfma_f32_16x16x32_bf16 v[124:127], v[132:135], v[192:195], v[124:127]
	v_mfma_f32_16x16x32_bf16 v[120:123], v[140:143], v[192:195], v[120:123]
	v_mfma_f32_16x16x32_bf16 v[108:111], v[132:135], v[200:203], v[108:111]
	v_mfma_f32_16x16x32_bf16 v[104:107], v[140:143], v[200:203], v[104:107]
	v_mfma_f32_16x16x32_bf16 v[92:95], v[132:135], v[208:211], v[92:95]
	v_mfma_f32_16x16x32_bf16 v[88:91], v[140:143], v[208:211], v[88:91]
	v_mfma_f32_16x16x32_bf16 v[76:79], v[132:135], v[216:219], v[76:79]
	v_mfma_f32_16x16x32_bf16 v[72:75], v[140:143], v[216:219], v[72:75]
	v_mfma_f32_16x16x32_bf16 v[116:119], v[144:147], v[178:181], v[116:119]
	v_mfma_f32_16x16x32_bf16 v[112:115], v[152:155], v[178:181], v[112:115]
	v_mfma_f32_16x16x32_bf16 v[100:103], v[144:147], v[196:199], v[100:103]
	v_mfma_f32_16x16x32_bf16 v[96:99], v[152:155], v[196:199], v[96:99]
	v_mfma_f32_16x16x32_bf16 v[84:87], v[144:147], v[204:207], v[84:87]
	v_mfma_f32_16x16x32_bf16 v[80:83], v[152:155], v[204:207], v[80:83]
	v_mfma_f32_16x16x32_bf16 v[68:71], v[144:147], v[212:215], v[68:71]
	v_mfma_f32_16x16x32_bf16 v[64:67], v[152:155], v[212:215], v[64:67]
	v_mfma_f32_16x16x32_bf16 v[116:119], v[148:151], v[192:195], v[116:119]
	v_mfma_f32_16x16x32_bf16 v[112:115], v[156:159], v[192:195], v[112:115]
	v_mfma_f32_16x16x32_bf16 v[100:103], v[148:151], v[200:203], v[100:103]
	v_mfma_f32_16x16x32_bf16 v[96:99], v[156:159], v[200:203], v[96:99]
	v_mfma_f32_16x16x32_bf16 v[84:87], v[148:151], v[208:211], v[84:87]
	v_mfma_f32_16x16x32_bf16 v[80:83], v[156:159], v[208:211], v[80:83]
	v_mfma_f32_16x16x32_bf16 v[68:71], v[148:151], v[216:219], v[68:71]
	v_mfma_f32_16x16x32_bf16 v[64:67], v[156:159], v[216:219], v[64:67]
	s_barrier
	s_add_i32 s0, s62, s38
	v_lshl_add_u64 v[220:221], v[220:221], 0, s[10:11]
	s_mov_b32 m0, s0
	ds_read_b128 v[178:181], v190 offset:49152
	ds_read_b128 v[192:195], v190 offset:50176
	ds_read_b128 v[196:199], v190 offset:51200
	ds_read_b128 v[200:203], v190 offset:52224
	ds_read_b128 v[204:207], v190 offset:53248
	ds_read_b128 v[208:211], v190 offset:54272
	ds_read_b128 v[212:215], v190 offset:55296
	ds_read_b128 v[216:219], v190 offset:56320
	global_load_lds_dwordx4 v[220:221], off
	s_add_i32 m0, s0, 0x2000
	s_add_u32 s0, s28, 0x50080
	v_lshl_add_u64 v[220:221], v[222:223], 0, s[10:11]
	s_addc_u32 s1, s29, 0
	s_add_i32 s28, s63, s38
	global_load_lds_dwordx4 v[220:221], off
	s_mov_b32 m0, s28
	v_lshl_add_u64 v[220:221], s[0:1], 0, v[164:165]
	global_load_lds_dwordx4 v[220:221], off
	s_add_i32 m0, s28, 0x2000
	v_lshl_add_u64 v[220:221], s[0:1], 0, v[168:169]
	global_load_lds_dwordx4 v[220:221], off
	s_mov_b32 m0, s45
	v_lshl_add_u64 v[220:221], v[224:225], 0, s[10:11]
	global_load_lds_dwordx4 v[220:221], off
	s_mov_b32 m0, s46
	v_lshl_add_u64 v[220:221], v[226:227], 0, s[10:11]
	global_load_lds_dwordx4 v[220:221], off
	s_waitcnt vmcnt(8) lgkmcnt(0)
	s_barrier
	v_mfma_f32_16x16x32_bf16 v[60:63], v[128:131], v[178:181], v[60:63]
	v_mfma_f32_16x16x32_bf16 v[56:59], v[136:139], v[178:181], v[56:59]
	v_mfma_f32_16x16x32_bf16 v[44:47], v[128:131], v[196:199], v[44:47]
	v_mfma_f32_16x16x32_bf16 v[40:43], v[136:139], v[196:199], v[40:43]
	v_mfma_f32_16x16x32_bf16 v[28:31], v[128:131], v[204:207], v[28:31]
	v_mfma_f32_16x16x32_bf16 v[24:27], v[136:139], v[204:207], v[24:27]
	v_mfma_f32_16x16x32_bf16 v[12:15], v[128:131], v[212:215], v[12:15]
	v_mfma_f32_16x16x32_bf16 v[8:11], v[136:139], v[212:215], v[8:11]
	v_mfma_f32_16x16x32_bf16 v[60:63], v[132:135], v[192:195], v[60:63]
	v_mfma_f32_16x16x32_bf16 v[56:59], v[140:143], v[192:195], v[56:59]
	v_mfma_f32_16x16x32_bf16 v[44:47], v[132:135], v[200:203], v[44:47]
	v_mfma_f32_16x16x32_bf16 v[40:43], v[140:143], v[200:203], v[40:43]
	v_mfma_f32_16x16x32_bf16 v[28:31], v[132:135], v[208:211], v[28:31]
	v_mfma_f32_16x16x32_bf16 v[24:27], v[140:143], v[208:211], v[24:27]
	v_mfma_f32_16x16x32_bf16 v[12:15], v[132:135], v[216:219], v[12:15]
	v_mfma_f32_16x16x32_bf16 v[8:11], v[140:143], v[216:219], v[8:11]
	v_mfma_f32_16x16x32_bf16 v[52:55], v[144:147], v[178:181], v[52:55]
	v_mfma_f32_16x16x32_bf16 v[48:51], v[152:155], v[178:181], v[48:51]
	v_mfma_f32_16x16x32_bf16 v[36:39], v[144:147], v[196:199], v[36:39]
	v_mfma_f32_16x16x32_bf16 v[32:35], v[152:155], v[196:199], v[32:35]
	v_mfma_f32_16x16x32_bf16 v[20:23], v[144:147], v[204:207], v[20:23]
	v_mfma_f32_16x16x32_bf16 v[16:19], v[152:155], v[204:207], v[16:19]
	v_mfma_f32_16x16x32_bf16 v[4:7], v[144:147], v[212:215], v[4:7]
	v_mfma_f32_16x16x32_bf16 v[0:3], v[152:155], v[212:215], v[0:3]
	v_mfma_f32_16x16x32_bf16 v[52:55], v[148:151], v[192:195], v[52:55]
	v_mfma_f32_16x16x32_bf16 v[48:51], v[156:159], v[192:195], v[48:51]
	v_mfma_f32_16x16x32_bf16 v[36:39], v[148:151], v[200:203], v[36:39]
	v_mfma_f32_16x16x32_bf16 v[32:35], v[156:159], v[200:203], v[32:35]
	v_mfma_f32_16x16x32_bf16 v[20:23], v[148:151], v[208:211], v[20:23]
	v_mfma_f32_16x16x32_bf16 v[16:19], v[156:159], v[208:211], v[16:19]
	v_mfma_f32_16x16x32_bf16 v[4:7], v[148:151], v[216:219], v[4:7]
	v_mfma_f32_16x16x32_bf16 v[0:3], v[156:159], v[216:219], v[0:3]
	s_barrier
	s_add_i32 s61, s61, 2
	s_add_u32 s59, s59, 0x100
	s_addc_u32 s60, s60, 0
	s_cmp_gt_u32 s61, 17
	s_mov_b64 s[0:1], s[16:17]
	s_cbranch_scc0 .LBB0_551
	s_branch .Lpeel_exit_2
.LBB0_551:
	ds_read_b128 v[128:131], v188
	ds_read_b128 v[132:135], v188 offset:1024
	ds_read_b128 v[136:139], v188 offset:2048
	ds_read_b128 v[140:143], v188 offset:3072
	ds_read_b128 v[144:147], v189
	ds_read_b128 v[148:151], v189 offset:1024
	ds_read_b128 v[152:155], v189 offset:2048
	ds_read_b128 v[156:159], v189 offset:3072
	s_add_u32 s16, s0, 0x100
	s_addc_u32 s17, s1, 0
	s_cmp_eq_u32 s61, 16
	s_cselect_b32 s35, s7, s17
	s_cselect_b32 s34, s6, s16
	s_cselect_b32 s29, s15, s60
	s_cselect_b32 s28, s14, s59
	v_lshl_add_u64 v[220:221], s[0:1], 0, v[170:171]
	s_add_i32 m0, s39, 0xc000
	ds_read_b128 v[178:181], v190
	ds_read_b128 v[192:195], v190 offset:1024
	ds_read_b128 v[196:199], v190 offset:2048
	ds_read_b128 v[200:203], v190 offset:3072
	ds_read_b128 v[204:207], v190 offset:4096
	ds_read_b128 v[208:211], v190 offset:5120
	ds_read_b128 v[212:215], v190 offset:6144
	ds_read_b128 v[216:219], v190 offset:7168
	global_load_lds_dwordx4 v[220:221], off
	s_add_i32 m0, s39, 0xe000
	v_lshl_add_u64 v[220:221], s[0:1], 0, v[172:173]
	global_load_lds_dwordx4 v[220:221], off
	s_waitcnt vmcnt(8) lgkmcnt(0)
	s_barrier
	v_mfma_f32_16x16x32_bf16 v[124:127], v[128:131], v[178:181], v[124:127]
	v_mfma_f32_16x16x32_bf16 v[120:123], v[136:139], v[178:181], v[120:123]
	v_mfma_f32_16x16x32_bf16 v[108:111], v[128:131], v[196:199], v[108:111]
	v_mfma_f32_16x16x32_bf16 v[104:107], v[136:139], v[196:199], v[104:107]
	v_mfma_f32_16x16x32_bf16 v[92:95], v[128:131], v[204:207], v[92:95]
	v_mfma_f32_16x16x32_bf16 v[88:91], v[136:139], v[204:207], v[88:91]
	v_mfma_f32_16x16x32_bf16 v[76:79], v[128:131], v[212:215], v[76:79]
	v_mfma_f32_16x16x32_bf16 v[72:75], v[136:139], v[212:215], v[72:75]
	v_mfma_f32_16x16x32_bf16 v[124:127], v[132:135], v[192:195], v[124:127]
	v_mfma_f32_16x16x32_bf16 v[120:123], v[140:143], v[192:195], v[120:123]
	v_mfma_f32_16x16x32_bf16 v[108:111], v[132:135], v[200:203], v[108:111]
	v_mfma_f32_16x16x32_bf16 v[104:107], v[140:143], v[200:203], v[104:107]
	v_mfma_f32_16x16x32_bf16 v[92:95], v[132:135], v[208:211], v[92:95]
	v_mfma_f32_16x16x32_bf16 v[88:91], v[140:143], v[208:211], v[88:91]
	v_mfma_f32_16x16x32_bf16 v[76:79], v[132:135], v[216:219], v[76:79]
	v_mfma_f32_16x16x32_bf16 v[72:75], v[140:143], v[216:219], v[72:75]
	v_mfma_f32_16x16x32_bf16 v[116:119], v[144:147], v[178:181], v[116:119]
	v_mfma_f32_16x16x32_bf16 v[112:115], v[152:155], v[178:181], v[112:115]
	v_mfma_f32_16x16x32_bf16 v[100:103], v[144:147], v[196:199], v[100:103]
	v_mfma_f32_16x16x32_bf16 v[96:99], v[152:155], v[196:199], v[96:99]
	v_mfma_f32_16x16x32_bf16 v[84:87], v[144:147], v[204:207], v[84:87]
	v_mfma_f32_16x16x32_bf16 v[80:83], v[152:155], v[204:207], v[80:83]
	v_mfma_f32_16x16x32_bf16 v[68:71], v[144:147], v[212:215], v[68:71]
	v_mfma_f32_16x16x32_bf16 v[64:67], v[152:155], v[212:215], v[64:67]
	v_mfma_f32_16x16x32_bf16 v[116:119], v[148:151], v[192:195], v[116:119]
	v_mfma_f32_16x16x32_bf16 v[112:115], v[156:159], v[192:195], v[112:115]
	v_mfma_f32_16x16x32_bf16 v[100:103], v[148:151], v[200:203], v[100:103]
	v_mfma_f32_16x16x32_bf16 v[96:99], v[156:159], v[200:203], v[96:99]
	v_mfma_f32_16x16x32_bf16 v[84:87], v[148:151], v[208:211], v[84:87]
	v_mfma_f32_16x16x32_bf16 v[80:83], v[156:159], v[208:211], v[80:83]
	v_mfma_f32_16x16x32_bf16 v[68:71], v[148:151], v[216:219], v[68:71]
	v_mfma_f32_16x16x32_bf16 v[64:67], v[156:159], v[216:219], v[64:67]
	s_barrier
	s_add_i32 s0, s50, s38
	v_lshl_add_u64 v[220:221], s[28:29], 0, v[164:165]
	s_mov_b32 m0, s0
	ds_read_b128 v[178:181], v190 offset:16384
	ds_read_b128 v[192:195], v190 offset:17408
	ds_read_b128 v[196:199], v190 offset:18432
	ds_read_b128 v[200:203], v190 offset:19456
	ds_read_b128 v[204:207], v190 offset:20480
	ds_read_b128 v[208:211], v190 offset:21504
	ds_read_b128 v[212:215], v190 offset:22528
	ds_read_b128 v[216:219], v190 offset:23552
	global_load_lds_dwordx4 v[220:221], off
	s_add_i32 m0, s0, 0x2000
	s_add_u32 s0, s28, 0x50000
	v_lshl_add_u64 v[222:223], s[28:29], 0, v[168:169]
	s_addc_u32 s1, s29, 0
	s_add_i32 s62, s51, s38
	global_load_lds_dwordx4 v[222:223], off
	v_lshl_add_u64 v[224:225], s[0:1], 0, v[164:165]
	s_mov_b32 m0, s62
	v_lshl_add_u64 v[226:227], s[34:35], 0, v[166:167]
	global_load_lds_dwordx4 v[224:225], off
	s_add_i32 m0, s62, 0x2000
	v_lshl_add_u64 v[224:225], s[0:1], 0, v[168:169]
	global_load_lds_dwordx4 v[224:225], off
	s_mov_b32 m0, s39
	v_lshl_add_u64 v[224:225], s[34:35], 0, v[162:163]
	global_load_lds_dwordx4 v[224:225], off
	s_mov_b32 m0, s40
	s_nop 0
	global_load_lds_dwordx4 v[226:227], off
	s_waitcnt vmcnt(8) lgkmcnt(0)
	s_barrier
	v_mfma_f32_16x16x32_bf16 v[60:63], v[128:131], v[178:181], v[60:63]
	v_mfma_f32_16x16x32_bf16 v[56:59], v[136:139], v[178:181], v[56:59]
	v_mfma_f32_16x16x32_bf16 v[44:47], v[128:131], v[196:199], v[44:47]
	v_mfma_f32_16x16x32_bf16 v[40:43], v[136:139], v[196:199], v[40:43]
	v_mfma_f32_16x16x32_bf16 v[28:31], v[128:131], v[204:207], v[28:31]
	v_mfma_f32_16x16x32_bf16 v[24:27], v[136:139], v[204:207], v[24:27]
	v_mfma_f32_16x16x32_bf16 v[12:15], v[128:131], v[212:215], v[12:15]
	v_mfma_f32_16x16x32_bf16 v[8:11], v[136:139], v[212:215], v[8:11]
	v_mfma_f32_16x16x32_bf16 v[60:63], v[132:135], v[192:195], v[60:63]
	v_mfma_f32_16x16x32_bf16 v[56:59], v[140:143], v[192:195], v[56:59]
	v_mfma_f32_16x16x32_bf16 v[44:47], v[132:135], v[200:203], v[44:47]
	v_mfma_f32_16x16x32_bf16 v[40:43], v[140:143], v[200:203], v[40:43]
	v_mfma_f32_16x16x32_bf16 v[28:31], v[132:135], v[208:211], v[28:31]
	v_mfma_f32_16x16x32_bf16 v[24:27], v[140:143], v[208:211], v[24:27]
	v_mfma_f32_16x16x32_bf16 v[12:15], v[132:135], v[216:219], v[12:15]
	v_mfma_f32_16x16x32_bf16 v[8:11], v[140:143], v[216:219], v[8:11]
	v_mfma_f32_16x16x32_bf16 v[52:55], v[144:147], v[178:181], v[52:55]
	v_mfma_f32_16x16x32_bf16 v[48:51], v[152:155], v[178:181], v[48:51]
	v_mfma_f32_16x16x32_bf16 v[36:39], v[144:147], v[196:199], v[36:39]
	v_mfma_f32_16x16x32_bf16 v[32:35], v[152:155], v[196:199], v[32:35]
	v_mfma_f32_16x16x32_bf16 v[20:23], v[144:147], v[204:207], v[20:23]
	v_mfma_f32_16x16x32_bf16 v[16:19], v[152:155], v[204:207], v[16:19]
	v_mfma_f32_16x16x32_bf16 v[4:7], v[144:147], v[212:215], v[4:7]
	v_mfma_f32_16x16x32_bf16 v[0:3], v[152:155], v[212:215], v[0:3]
	v_mfma_f32_16x16x32_bf16 v[52:55], v[148:151], v[192:195], v[52:55]
	v_mfma_f32_16x16x32_bf16 v[48:51], v[156:159], v[192:195], v[48:51]
	v_mfma_f32_16x16x32_bf16 v[36:39], v[148:151], v[200:203], v[36:39]
	v_mfma_f32_16x16x32_bf16 v[32:35], v[156:159], v[200:203], v[32:35]
	v_mfma_f32_16x16x32_bf16 v[20:23], v[148:151], v[208:211], v[20:23]
	v_mfma_f32_16x16x32_bf16 v[16:19], v[156:159], v[208:211], v[16:19]
	v_mfma_f32_16x16x32_bf16 v[4:7], v[148:151], v[216:219], v[4:7]
	v_mfma_f32_16x16x32_bf16 v[0:3], v[156:159], v[216:219], v[0:3]
	s_barrier
	s_add_i32 s62, 0, 0x18000
	s_add_i32 s63, 0, 0x1c000
	v_add_u32_e32 v140, s62, v183
	v_add_u32_e32 v156, s63, v183
	ds_read_b128 v[128:131], v140
	ds_read_b128 v[132:135], v140 offset:1024
	ds_read_b128 v[136:139], v140 offset:2048
	ds_read_b128 v[140:143], v140 offset:3072
	ds_read_b128 v[144:147], v156
	ds_read_b128 v[148:151], v156 offset:1024
	ds_read_b128 v[152:155], v156 offset:2048
	ds_read_b128 v[156:159], v156 offset:3072
	s_add_u32 s0, s34, 0x50000
	s_addc_u32 s1, s35, 0
	s_mov_b32 m0, s41
	v_lshl_add_u64 v[228:229], s[0:1], 0, v[162:163]
	ds_read_b128 v[178:181], v190 offset:32768
	ds_read_b128 v[192:195], v190 offset:33792
	ds_read_b128 v[196:199], v190 offset:34816
	ds_read_b128 v[200:203], v190 offset:35840
	ds_read_b128 v[204:207], v190 offset:36864
	ds_read_b128 v[208:211], v190 offset:37888
	ds_read_b128 v[212:215], v190 offset:38912
	ds_read_b128 v[216:219], v190 offset:39936
	global_load_lds_dwordx4 v[228:229], off
	s_mov_b32 m0, s42
	v_lshl_add_u64 v[228:229], s[0:1], 0, v[166:167]
	global_load_lds_dwordx4 v[228:229], off
	s_waitcnt vmcnt(8) lgkmcnt(0)
	s_barrier
	v_mfma_f32_16x16x32_bf16 v[124:127], v[128:131], v[178:181], v[124:127]
	v_mfma_f32_16x16x32_bf16 v[120:123], v[136:139], v[178:181], v[120:123]
	v_mfma_f32_16x16x32_bf16 v[108:111], v[128:131], v[196:199], v[108:111]
	v_mfma_f32_16x16x32_bf16 v[104:107], v[136:139], v[196:199], v[104:107]
	v_mfma_f32_16x16x32_bf16 v[92:95], v[128:131], v[204:207], v[92:95]
	v_mfma_f32_16x16x32_bf16 v[88:91], v[136:139], v[204:207], v[88:91]
	v_mfma_f32_16x16x32_bf16 v[76:79], v[128:131], v[212:215], v[76:79]
	v_mfma_f32_16x16x32_bf16 v[72:75], v[136:139], v[212:215], v[72:75]
	v_mfma_f32_16x16x32_bf16 v[124:127], v[132:135], v[192:195], v[124:127]
	v_mfma_f32_16x16x32_bf16 v[120:123], v[140:143], v[192:195], v[120:123]
	v_mfma_f32_16x16x32_bf16 v[108:111], v[132:135], v[200:203], v[108:111]
	v_mfma_f32_16x16x32_bf16 v[104:107], v[140:143], v[200:203], v[104:107]
	v_mfma_f32_16x16x32_bf16 v[92:95], v[132:135], v[208:211], v[92:95]
	v_mfma_f32_16x16x32_bf16 v[88:91], v[140:143], v[208:211], v[88:91]
	v_mfma_f32_16x16x32_bf16 v[76:79], v[132:135], v[216:219], v[76:79]
	v_mfma_f32_16x16x32_bf16 v[72:75], v[140:143], v[216:219], v[72:75]
	v_mfma_f32_16x16x32_bf16 v[116:119], v[144:147], v[178:181], v[116:119]
	v_mfma_f32_16x16x32_bf16 v[112:115], v[152:155], v[178:181], v[112:115]
	v_mfma_f32_16x16x32_bf16 v[100:103], v[144:147], v[196:199], v[100:103]
	v_mfma_f32_16x16x32_bf16 v[96:99], v[152:155], v[196:199], v[96:99]
	v_mfma_f32_16x16x32_bf16 v[84:87], v[144:147], v[204:207], v[84:87]
	v_mfma_f32_16x16x32_bf16 v[80:83], v[152:155], v[204:207], v[80:83]
	v_mfma_f32_16x16x32_bf16 v[68:71], v[144:147], v[212:215], v[68:71]
	v_mfma_f32_16x16x32_bf16 v[64:67], v[152:155], v[212:215], v[64:67]
	v_mfma_f32_16x16x32_bf16 v[116:119], v[148:151], v[192:195], v[116:119]
	v_mfma_f32_16x16x32_bf16 v[112:115], v[156:159], v[192:195], v[112:115]
	v_mfma_f32_16x16x32_bf16 v[100:103], v[148:151], v[200:203], v[100:103]
	v_mfma_f32_16x16x32_bf16 v[96:99], v[156:159], v[200:203], v[96:99]
	v_mfma_f32_16x16x32_bf16 v[84:87], v[148:151], v[208:211], v[84:87]
	v_mfma_f32_16x16x32_bf16 v[80:83], v[156:159], v[208:211], v[80:83]
	v_mfma_f32_16x16x32_bf16 v[68:71], v[148:151], v[216:219], v[68:71]
	v_mfma_f32_16x16x32_bf16 v[64:67], v[156:159], v[216:219], v[64:67]
	s_barrier
	s_add_i32 s0, s62, s38
	v_lshl_add_u64 v[220:221], v[220:221], 0, s[10:11]
	s_mov_b32 m0, s0
	ds_read_b128 v[178:181], v190 offset:49152
	ds_read_b128 v[192:195], v190 offset:50176
	ds_read_b128 v[196:199], v190 offset:51200
	ds_read_b128 v[200:203], v190 offset:52224
	ds_read_b128 v[204:207], v190 offset:53248
	ds_read_b128 v[208:211], v190 offset:54272
	ds_read_b128 v[212:215], v190 offset:55296
	ds_read_b128 v[216:219], v190 offset:56320
	global_load_lds_dwordx4 v[220:221], off
	s_add_i32 m0, s0, 0x2000
	s_add_u32 s0, s28, 0x50080
	v_lshl_add_u64 v[220:221], v[222:223], 0, s[10:11]
	s_addc_u32 s1, s29, 0
	s_add_i32 s28, s63, s38
	global_load_lds_dwordx4 v[220:221], off
	s_mov_b32 m0, s28
	v_lshl_add_u64 v[220:221], s[0:1], 0, v[164:165]
	global_load_lds_dwordx4 v[220:221], off
	s_add_i32 m0, s28, 0x2000
	v_lshl_add_u64 v[220:221], s[0:1], 0, v[168:169]
	global_load_lds_dwordx4 v[220:221], off
	s_mov_b32 m0, s45
	v_lshl_add_u64 v[220:221], v[224:225], 0, s[10:11]
	global_load_lds_dwordx4 v[220:221], off
	s_mov_b32 m0, s46
	v_lshl_add_u64 v[220:221], v[226:227], 0, s[10:11]
	global_load_lds_dwordx4 v[220:221], off
	s_waitcnt vmcnt(8) lgkmcnt(0)
	s_barrier
	v_mfma_f32_16x16x32_bf16 v[60:63], v[128:131], v[178:181], v[60:63]
	v_mfma_f32_16x16x32_bf16 v[56:59], v[136:139], v[178:181], v[56:59]
	v_mfma_f32_16x16x32_bf16 v[44:47], v[128:131], v[196:199], v[44:47]
	v_mfma_f32_16x16x32_bf16 v[40:43], v[136:139], v[196:199], v[40:43]
	v_mfma_f32_16x16x32_bf16 v[28:31], v[128:131], v[204:207], v[28:31]
	v_mfma_f32_16x16x32_bf16 v[24:27], v[136:139], v[204:207], v[24:27]
	v_mfma_f32_16x16x32_bf16 v[12:15], v[128:131], v[212:215], v[12:15]
	v_mfma_f32_16x16x32_bf16 v[8:11], v[136:139], v[212:215], v[8:11]
	v_mfma_f32_16x16x32_bf16 v[60:63], v[132:135], v[192:195], v[60:63]
	v_mfma_f32_16x16x32_bf16 v[56:59], v[140:143], v[192:195], v[56:59]
	v_mfma_f32_16x16x32_bf16 v[44:47], v[132:135], v[200:203], v[44:47]
	v_mfma_f32_16x16x32_bf16 v[40:43], v[140:143], v[200:203], v[40:43]
	v_mfma_f32_16x16x32_bf16 v[28:31], v[132:135], v[208:211], v[28:31]
	v_mfma_f32_16x16x32_bf16 v[24:27], v[140:143], v[208:211], v[24:27]
	v_mfma_f32_16x16x32_bf16 v[12:15], v[132:135], v[216:219], v[12:15]
	v_mfma_f32_16x16x32_bf16 v[8:11], v[140:143], v[216:219], v[8:11]
	v_mfma_f32_16x16x32_bf16 v[52:55], v[144:147], v[178:181], v[52:55]
	v_mfma_f32_16x16x32_bf16 v[48:51], v[152:155], v[178:181], v[48:51]
	v_mfma_f32_16x16x32_bf16 v[36:39], v[144:147], v[196:199], v[36:39]
	v_mfma_f32_16x16x32_bf16 v[32:35], v[152:155], v[196:199], v[32:35]
	v_mfma_f32_16x16x32_bf16 v[20:23], v[144:147], v[204:207], v[20:23]
	v_mfma_f32_16x16x32_bf16 v[16:19], v[152:155], v[204:207], v[16:19]
	v_mfma_f32_16x16x32_bf16 v[4:7], v[144:147], v[212:215], v[4:7]
	v_mfma_f32_16x16x32_bf16 v[0:3], v[152:155], v[212:215], v[0:3]
	v_mfma_f32_16x16x32_bf16 v[52:55], v[148:151], v[192:195], v[52:55]
	v_mfma_f32_16x16x32_bf16 v[48:51], v[156:159], v[192:195], v[48:51]
	v_mfma_f32_16x16x32_bf16 v[36:39], v[148:151], v[200:203], v[36:39]
	v_mfma_f32_16x16x32_bf16 v[32:35], v[156:159], v[200:203], v[32:35]
	v_mfma_f32_16x16x32_bf16 v[20:23], v[148:151], v[208:211], v[20:23]
	v_mfma_f32_16x16x32_bf16 v[16:19], v[156:159], v[208:211], v[16:19]
	v_mfma_f32_16x16x32_bf16 v[4:7], v[148:151], v[216:219], v[4:7]
	v_mfma_f32_16x16x32_bf16 v[0:3], v[156:159], v[216:219], v[0:3]
	s_barrier
	s_add_i32 s61, s61, 2
	s_add_u32 s59, s59, 0x100
	s_addc_u32 s60, s60, 0
	s_cmp_gt_u32 s61, 17
	s_mov_b64 s[0:1], s[16:17]
	s_cbranch_scc0 .LBB0_551

.LBB0_635:
	s_ashr_i32 s13, s12, 31
	s_lshl_b64 s[14:15], s[12:13], 19
	s_add_u32 s14, s64, s14
	s_addc_u32 s15, s65, s15
	s_and_b64 s[16:17], s[2:3], exec
	s_cselect_b32 s13, s15, s1
	s_cselect_b32 s48, s14, s0
	s_ashr_i32 s11, s10, 31
	s_lshl_b64 s[16:17], s[10:11], 19
	s_add_u32 s16, s36, s16
	s_addc_u32 s17, s37, s17
	s_and_b64 s[34:35], s[2:3], exec
	s_cselect_b32 s11, s17, s31
	s_cselect_b32 s49, s16, s30
	s_add_u32 s0, s0, 0x40080
	s_addc_u32 s1, s1, 0
	s_add_u32 s50, s30, 0x100
	s_addc_u32 s51, s31, 0
	s_mov_b32 s52, -2
	v_lshl_add_u32 v248, s28, 8, v156
	v_ashrrev_i32_e32 v249, 31, v248
	v_lshl_add_u64 v[248:249], v[248:249], 2, s[26:27]
	global_load_dword v240, v[248:249], off
	global_load_dword v241, v[248:249], off offset:64
	global_load_dword v242, v[248:249], off offset:128
	global_load_dword v243, v[248:249], off offset:192
	global_load_dword v244, v[248:249], off offset:512
	global_load_dword v245, v[248:249], off offset:576
	global_load_dword v246, v[248:249], off offset:640
	global_load_dword v247, v[248:249], off offset:704
	ds_read_b128 v[144:147], v159
	ds_read_b128 v[148:151], v159 offset:1024
	ds_read_b128 v[152:155], v159 offset:2048
	ds_read_b128 v[166:169], v159 offset:3072
	ds_read_b128 v[170:173], v162
	ds_read_b128 v[174:177], v162 offset:1024
	ds_read_b128 v[178:181], v162 offset:2048
	ds_read_b128 v[182:185], v162 offset:3072
	s_add_u32 s30, s0, 0xfffc0080
	s_addc_u32 s31, s1, -1
	s_cmp_eq_u32 s52, 12
	s_cselect_b32 s35, s13, s31
	s_cselect_b32 s34, s48, s30
	s_cselect_b32 s31, s11, s51
	s_cselect_b32 s30, s49, s50
	v_lshl_add_u64 v[218:219], s[0:1], 0, v[136:137]
	s_add_i32 m0, s29, 0xc000
	ds_read_b128 v[186:189], v163
	ds_read_b128 v[190:193], v163 offset:1024
	ds_read_b128 v[194:197], v163 offset:2048
	ds_read_b128 v[198:201], v163 offset:3072
	ds_read_b128 v[202:205], v163 offset:4096
	ds_read_b128 v[206:209], v163 offset:5120
	ds_read_b128 v[210:213], v163 offset:6144
	ds_read_b128 v[214:217], v163 offset:7168
	global_load_lds_dwordx4 v[218:219], off
	s_add_i32 m0, s29, 0xe000
	v_lshl_add_u64 v[218:219], s[0:1], 0, v[138:139]
	global_load_lds_dwordx4 v[218:219], off
	s_waitcnt vmcnt(8) lgkmcnt(0)
	s_barrier
	v_mfma_f32_16x16x32_bf16 v[124:127], v[144:147], v[186:189], 0
	v_mfma_f32_16x16x32_bf16 v[120:123], v[152:155], v[186:189], 0
	v_mfma_f32_16x16x32_bf16 v[116:119], v[144:147], v[194:197], 0
	v_mfma_f32_16x16x32_bf16 v[104:107], v[152:155], v[194:197], 0
	v_mfma_f32_16x16x32_bf16 v[92:95], v[144:147], v[202:205], 0
	v_mfma_f32_16x16x32_bf16 v[88:91], v[152:155], v[202:205], 0
	v_mfma_f32_16x16x32_bf16 v[76:79], v[144:147], v[210:213], 0
	v_mfma_f32_16x16x32_bf16 v[72:75], v[152:155], v[210:213], 0
	v_mfma_f32_16x16x32_bf16 v[124:127], v[148:151], v[190:193], v[124:127]
	v_mfma_f32_16x16x32_bf16 v[120:123], v[166:169], v[190:193], v[120:123]
	v_mfma_f32_16x16x32_bf16 v[116:119], v[148:151], v[198:201], v[116:119]
	v_mfma_f32_16x16x32_bf16 v[104:107], v[166:169], v[198:201], v[104:107]
	v_mfma_f32_16x16x32_bf16 v[92:95], v[148:151], v[206:209], v[92:95]
	v_mfma_f32_16x16x32_bf16 v[88:91], v[166:169], v[206:209], v[88:91]
	v_mfma_f32_16x16x32_bf16 v[76:79], v[148:151], v[214:217], v[76:79]
	v_mfma_f32_16x16x32_bf16 v[72:75], v[166:169], v[214:217], v[72:75]
	v_mfma_f32_16x16x32_bf16 v[112:115], v[170:173], v[186:189], 0
	v_mfma_f32_16x16x32_bf16 v[108:111], v[178:181], v[186:189], 0
	v_mfma_f32_16x16x32_bf16 v[100:103], v[170:173], v[194:197], 0
	v_mfma_f32_16x16x32_bf16 v[96:99], v[178:181], v[194:197], 0
	v_mfma_f32_16x16x32_bf16 v[84:87], v[170:173], v[202:205], 0
	v_mfma_f32_16x16x32_bf16 v[80:83], v[178:181], v[202:205], 0
	v_mfma_f32_16x16x32_bf16 v[68:71], v[170:173], v[210:213], 0
	v_mfma_f32_16x16x32_bf16 v[64:67], v[178:181], v[210:213], 0
	v_mfma_f32_16x16x32_bf16 v[112:115], v[174:177], v[190:193], v[112:115]
	v_mfma_f32_16x16x32_bf16 v[108:111], v[182:185], v[190:193], v[108:111]
	v_mfma_f32_16x16x32_bf16 v[100:103], v[174:177], v[198:201], v[100:103]
	v_mfma_f32_16x16x32_bf16 v[96:99], v[182:185], v[198:201], v[96:99]
	v_mfma_f32_16x16x32_bf16 v[84:87], v[174:177], v[206:209], v[84:87]
	v_mfma_f32_16x16x32_bf16 v[80:83], v[182:185], v[206:209], v[80:83]
	v_mfma_f32_16x16x32_bf16 v[68:71], v[174:177], v[214:217], v[68:71]
	v_mfma_f32_16x16x32_bf16 v[64:67], v[182:185], v[214:217], v[64:67]
	s_barrier
	s_add_i32 s53, s46, s38
	v_lshl_add_u64 v[218:219], s[30:31], 0, v[132:133]
	s_mov_b32 m0, s53
	ds_read_b128 v[186:189], v163 offset:16384
	ds_read_b128 v[190:193], v163 offset:17408
	ds_read_b128 v[194:197], v163 offset:18432
	ds_read_b128 v[198:201], v163 offset:19456
	ds_read_b128 v[202:205], v163 offset:20480
	ds_read_b128 v[206:209], v163 offset:21504
	ds_read_b128 v[210:213], v163 offset:22528
	ds_read_b128 v[214:217], v163 offset:23552
	global_load_lds_dwordx4 v[218:219], off
	s_add_i32 m0, s53, 0x2000
	s_add_u32 s54, s30, 0x40000
	v_lshl_add_u64 v[220:221], s[30:31], 0, v[128:129]
	s_addc_u32 s55, s31, 0
	s_add_i32 s53, s47, s38
	global_load_lds_dwordx4 v[220:221], off
	v_lshl_add_u64 v[222:223], s[54:55], 0, v[132:133]
	s_mov_b32 m0, s53
	v_lshl_add_u64 v[224:225], s[34:35], 0, v[130:131]
	global_load_lds_dwordx4 v[222:223], off
	s_add_i32 m0, s53, 0x2000
	v_lshl_add_u64 v[222:223], s[54:55], 0, v[128:129]
	global_load_lds_dwordx4 v[222:223], off
	s_mov_b32 m0, s29
	v_lshl_add_u64 v[222:223], s[34:35], 0, v[134:135]
	global_load_lds_dwordx4 v[222:223], off
	s_mov_b32 m0, s40
	s_nop 0
	global_load_lds_dwordx4 v[224:225], off
	s_waitcnt vmcnt(8) lgkmcnt(0)
	s_barrier
	v_mfma_f32_16x16x32_bf16 v[60:63], v[144:147], v[186:189], 0
	v_mfma_f32_16x16x32_bf16 v[56:59], v[152:155], v[186:189], 0
	v_mfma_f32_16x16x32_bf16 v[44:47], v[144:147], v[194:197], 0
	v_mfma_f32_16x16x32_bf16 v[40:43], v[152:155], v[194:197], 0
	v_mfma_f32_16x16x32_bf16 v[28:31], v[144:147], v[202:205], 0
	v_mfma_f32_16x16x32_bf16 v[24:27], v[152:155], v[202:205], 0
	v_mfma_f32_16x16x32_bf16 v[12:15], v[144:147], v[210:213], 0
	v_mfma_f32_16x16x32_bf16 v[8:11], v[152:155], v[210:213], 0
	v_mfma_f32_16x16x32_bf16 v[60:63], v[148:151], v[190:193], v[60:63]
	v_mfma_f32_16x16x32_bf16 v[56:59], v[166:169], v[190:193], v[56:59]
	v_mfma_f32_16x16x32_bf16 v[44:47], v[148:151], v[198:201], v[44:47]
	v_mfma_f32_16x16x32_bf16 v[40:43], v[166:169], v[198:201], v[40:43]
	v_mfma_f32_16x16x32_bf16 v[28:31], v[148:151], v[206:209], v[28:31]
	v_mfma_f32_16x16x32_bf16 v[24:27], v[166:169], v[206:209], v[24:27]
	v_mfma_f32_16x16x32_bf16 v[12:15], v[148:151], v[214:217], v[12:15]
	v_mfma_f32_16x16x32_bf16 v[8:11], v[166:169], v[214:217], v[8:11]
	v_mfma_f32_16x16x32_bf16 v[52:55], v[170:173], v[186:189], 0
	v_mfma_f32_16x16x32_bf16 v[48:51], v[178:181], v[186:189], 0
	v_mfma_f32_16x16x32_bf16 v[36:39], v[170:173], v[194:197], 0
	v_mfma_f32_16x16x32_bf16 v[32:35], v[178:181], v[194:197], 0
	v_mfma_f32_16x16x32_bf16 v[20:23], v[170:173], v[202:205], 0
	v_mfma_f32_16x16x32_bf16 v[16:19], v[178:181], v[202:205], 0
	v_mfma_f32_16x16x32_bf16 v[4:7], v[170:173], v[210:213], 0
	v_mfma_f32_16x16x32_bf16 v[0:3], v[178:181], v[210:213], 0
	v_mfma_f32_16x16x32_bf16 v[52:55], v[174:177], v[190:193], v[52:55]
	v_mfma_f32_16x16x32_bf16 v[48:51], v[182:185], v[190:193], v[48:51]
	v_mfma_f32_16x16x32_bf16 v[36:39], v[174:177], v[198:201], v[36:39]
	v_mfma_f32_16x16x32_bf16 v[32:35], v[182:185], v[198:201], v[32:35]
	v_mfma_f32_16x16x32_bf16 v[20:23], v[174:177], v[206:209], v[20:23]
	v_mfma_f32_16x16x32_bf16 v[16:19], v[182:185], v[206:209], v[16:19]
	v_mfma_f32_16x16x32_bf16 v[4:7], v[174:177], v[214:217], v[4:7]
	v_mfma_f32_16x16x32_bf16 v[0:3], v[182:185], v[214:217], v[0:3]
	s_barrier
	s_add_i32 s53, 0, 0x18000
	v_add_u32_e32 v165, s53, v157
	s_add_i32 s54, 0, 0x1c000
	ds_read_b128 v[144:147], v165
	ds_read_b128 v[148:151], v165 offset:1024
	ds_read_b128 v[152:155], v165 offset:2048
	ds_read_b128 v[166:169], v165 offset:3072
	v_add_u32_e32 v165, s54, v157
	ds_read_b128 v[170:173], v165
	ds_read_b128 v[174:177], v165 offset:1024
	ds_read_b128 v[178:181], v165 offset:2048
	ds_read_b128 v[182:185], v165 offset:3072
	s_add_u32 s34, s34, 0x40000
	s_addc_u32 s35, s35, 0
	s_mov_b32 m0, s41
	v_lshl_add_u64 v[226:227], s[34:35], 0, v[134:135]
	ds_read_b128 v[186:189], v163 offset:32768
	ds_read_b128 v[190:193], v163 offset:33792
	ds_read_b128 v[194:197], v163 offset:34816
	ds_read_b128 v[198:201], v163 offset:35840
	ds_read_b128 v[202:205], v163 offset:36864
	ds_read_b128 v[206:209], v163 offset:37888
	ds_read_b128 v[210:213], v163 offset:38912
	ds_read_b128 v[214:217], v163 offset:39936
	global_load_lds_dwordx4 v[226:227], off
	s_mov_b32 m0, s42
	v_lshl_add_u64 v[226:227], s[34:35], 0, v[130:131]
	global_load_lds_dwordx4 v[226:227], off
	s_waitcnt vmcnt(8) lgkmcnt(0)
	s_barrier
	v_mfma_f32_16x16x32_bf16 v[124:127], v[144:147], v[186:189], v[124:127]
	v_mfma_f32_16x16x32_bf16 v[120:123], v[152:155], v[186:189], v[120:123]
	v_mfma_f32_16x16x32_bf16 v[116:119], v[144:147], v[194:197], v[116:119]
	v_mfma_f32_16x16x32_bf16 v[104:107], v[152:155], v[194:197], v[104:107]
	v_mfma_f32_16x16x32_bf16 v[92:95], v[144:147], v[202:205], v[92:95]
	v_mfma_f32_16x16x32_bf16 v[88:91], v[152:155], v[202:205], v[88:91]
	v_mfma_f32_16x16x32_bf16 v[76:79], v[144:147], v[210:213], v[76:79]
	v_mfma_f32_16x16x32_bf16 v[72:75], v[152:155], v[210:213], v[72:75]
	v_mfma_f32_16x16x32_bf16 v[124:127], v[148:151], v[190:193], v[124:127]
	v_mfma_f32_16x16x32_bf16 v[120:123], v[166:169], v[190:193], v[120:123]
	v_mfma_f32_16x16x32_bf16 v[116:119], v[148:151], v[198:201], v[116:119]
	v_mfma_f32_16x16x32_bf16 v[104:107], v[166:169], v[198:201], v[104:107]
	v_mfma_f32_16x16x32_bf16 v[92:95], v[148:151], v[206:209], v[92:95]
	v_mfma_f32_16x16x32_bf16 v[88:91], v[166:169], v[206:209], v[88:91]
	v_mfma_f32_16x16x32_bf16 v[76:79], v[148:151], v[214:217], v[76:79]
	v_mfma_f32_16x16x32_bf16 v[72:75], v[166:169], v[214:217], v[72:75]
	v_mfma_f32_16x16x32_bf16 v[112:115], v[170:173], v[186:189], v[112:115]
	v_mfma_f32_16x16x32_bf16 v[108:111], v[178:181], v[186:189], v[108:111]
	v_mfma_f32_16x16x32_bf16 v[100:103], v[170:173], v[194:197], v[100:103]
	v_mfma_f32_16x16x32_bf16 v[96:99], v[178:181], v[194:197], v[96:99]
	v_mfma_f32_16x16x32_bf16 v[84:87], v[170:173], v[202:205], v[84:87]
	v_mfma_f32_16x16x32_bf16 v[80:83], v[178:181], v[202:205], v[80:83]
	v_mfma_f32_16x16x32_bf16 v[68:71], v[170:173], v[210:213], v[68:71]
	v_mfma_f32_16x16x32_bf16 v[64:67], v[178:181], v[210:213], v[64:67]
	v_mfma_f32_16x16x32_bf16 v[112:115], v[174:177], v[190:193], v[112:115]
	v_mfma_f32_16x16x32_bf16 v[108:111], v[182:185], v[190:193], v[108:111]
	v_mfma_f32_16x16x32_bf16 v[100:103], v[174:177], v[198:201], v[100:103]
	v_mfma_f32_16x16x32_bf16 v[96:99], v[182:185], v[198:201], v[96:99]
	v_mfma_f32_16x16x32_bf16 v[84:87], v[174:177], v[206:209], v[84:87]
	v_mfma_f32_16x16x32_bf16 v[80:83], v[182:185], v[206:209], v[80:83]
	v_mfma_f32_16x16x32_bf16 v[68:71], v[174:177], v[214:217], v[68:71]
	v_mfma_f32_16x16x32_bf16 v[64:67], v[182:185], v[214:217], v[64:67]
	s_barrier
	s_add_i32 s34, s53, s38
	v_lshl_add_u64 v[218:219], v[218:219], 0, s[6:7]
	s_mov_b32 m0, s34
	ds_read_b128 v[186:189], v163 offset:49152
	ds_read_b128 v[190:193], v163 offset:50176
	ds_read_b128 v[194:197], v163 offset:51200
	ds_read_b128 v[198:201], v163 offset:52224
	ds_read_b128 v[202:205], v163 offset:53248
	ds_read_b128 v[206:209], v163 offset:54272
	ds_read_b128 v[210:213], v163 offset:55296
	ds_read_b128 v[214:217], v163 offset:56320
	global_load_lds_dwordx4 v[218:219], off
	s_add_i32 m0, s34, 0x2000
	s_add_u32 s30, s30, 0x40080
	v_lshl_add_u64 v[218:219], v[220:221], 0, s[6:7]
	s_addc_u32 s31, s31, 0
	s_add_i32 s34, s54, s38
	global_load_lds_dwordx4 v[218:219], off
	s_mov_b32 m0, s34
	v_lshl_add_u64 v[218:219], s[30:31], 0, v[132:133]
	global_load_lds_dwordx4 v[218:219], off
	s_add_i32 m0, s34, 0x2000
	v_lshl_add_u64 v[218:219], s[30:31], 0, v[128:129]
	global_load_lds_dwordx4 v[218:219], off
	s_mov_b32 m0, s44
	v_lshl_add_u64 v[218:219], v[222:223], 0, s[6:7]
	global_load_lds_dwordx4 v[218:219], off
	s_mov_b32 m0, s45
	v_lshl_add_u64 v[218:219], v[224:225], 0, s[6:7]
	global_load_lds_dwordx4 v[218:219], off
	s_waitcnt vmcnt(8) lgkmcnt(0)
	s_barrier
	v_mfma_f32_16x16x32_bf16 v[60:63], v[144:147], v[186:189], v[60:63]
	v_mfma_f32_16x16x32_bf16 v[56:59], v[152:155], v[186:189], v[56:59]
	v_mfma_f32_16x16x32_bf16 v[44:47], v[144:147], v[194:197], v[44:47]
	v_mfma_f32_16x16x32_bf16 v[40:43], v[152:155], v[194:197], v[40:43]
	v_mfma_f32_16x16x32_bf16 v[28:31], v[144:147], v[202:205], v[28:31]
	v_mfma_f32_16x16x32_bf16 v[24:27], v[152:155], v[202:205], v[24:27]
	v_mfma_f32_16x16x32_bf16 v[12:15], v[144:147], v[210:213], v[12:15]
	v_mfma_f32_16x16x32_bf16 v[8:11], v[152:155], v[210:213], v[8:11]
	v_mfma_f32_16x16x32_bf16 v[60:63], v[148:151], v[190:193], v[60:63]
	v_mfma_f32_16x16x32_bf16 v[56:59], v[166:169], v[190:193], v[56:59]
	v_mfma_f32_16x16x32_bf16 v[44:47], v[148:151], v[198:201], v[44:47]
	v_mfma_f32_16x16x32_bf16 v[40:43], v[166:169], v[198:201], v[40:43]
	v_mfma_f32_16x16x32_bf16 v[28:31], v[148:151], v[206:209], v[28:31]
	v_mfma_f32_16x16x32_bf16 v[24:27], v[166:169], v[206:209], v[24:27]
	v_mfma_f32_16x16x32_bf16 v[12:15], v[148:151], v[214:217], v[12:15]
	v_mfma_f32_16x16x32_bf16 v[8:11], v[166:169], v[214:217], v[8:11]
	v_mfma_f32_16x16x32_bf16 v[52:55], v[170:173], v[186:189], v[52:55]
	v_mfma_f32_16x16x32_bf16 v[48:51], v[178:181], v[186:189], v[48:51]
	v_mfma_f32_16x16x32_bf16 v[36:39], v[170:173], v[194:197], v[36:39]
	v_mfma_f32_16x16x32_bf16 v[32:35], v[178:181], v[194:197], v[32:35]
	v_mfma_f32_16x16x32_bf16 v[20:23], v[170:173], v[202:205], v[20:23]
	v_mfma_f32_16x16x32_bf16 v[16:19], v[178:181], v[202:205], v[16:19]
	v_mfma_f32_16x16x32_bf16 v[4:7], v[170:173], v[210:213], v[4:7]
	v_mfma_f32_16x16x32_bf16 v[0:3], v[178:181], v[210:213], v[0:3]
	v_mfma_f32_16x16x32_bf16 v[52:55], v[174:177], v[190:193], v[52:55]
	v_mfma_f32_16x16x32_bf16 v[48:51], v[182:185], v[190:193], v[48:51]
	v_mfma_f32_16x16x32_bf16 v[36:39], v[174:177], v[198:201], v[36:39]
	v_mfma_f32_16x16x32_bf16 v[32:35], v[182:185], v[198:201], v[32:35]
	v_mfma_f32_16x16x32_bf16 v[20:23], v[174:177], v[206:209], v[20:23]
	v_mfma_f32_16x16x32_bf16 v[16:19], v[182:185], v[206:209], v[16:19]
	v_mfma_f32_16x16x32_bf16 v[4:7], v[174:177], v[214:217], v[4:7]
	v_mfma_f32_16x16x32_bf16 v[0:3], v[182:185], v[214:217], v[0:3]
	s_barrier
	s_add_i32 s52, s52, 2
	s_add_u32 s0, s0, 0x100
	s_addc_u32 s1, s1, 0
	s_add_u32 s50, s50, 0x100
	s_addc_u32 s51, s51, 0
	s_cmp_gt_u32 s52, 13
	s_cbranch_scc0 .LBB0_636
	s_branch .Lpeel_exit_3
.LBB0_636:
	ds_read_b128 v[144:147], v159
	ds_read_b128 v[148:151], v159 offset:1024
	ds_read_b128 v[152:155], v159 offset:2048
	ds_read_b128 v[166:169], v159 offset:3072
	ds_read_b128 v[170:173], v162
	ds_read_b128 v[174:177], v162 offset:1024
	ds_read_b128 v[178:181], v162 offset:2048
	ds_read_b128 v[182:185], v162 offset:3072
	s_add_u32 s30, s0, 0xfffc0080
	s_addc_u32 s31, s1, -1
	s_cmp_eq_u32 s52, 12
	s_cselect_b32 s35, s13, s31
	s_cselect_b32 s34, s48, s30
	s_cselect_b32 s31, s11, s51
	s_cselect_b32 s30, s49, s50
	v_lshl_add_u64 v[218:219], s[0:1], 0, v[136:137]
	s_add_i32 m0, s29, 0xc000
	ds_read_b128 v[186:189], v163
	ds_read_b128 v[190:193], v163 offset:1024
	ds_read_b128 v[194:197], v163 offset:2048
	ds_read_b128 v[198:201], v163 offset:3072
	ds_read_b128 v[202:205], v163 offset:4096
	ds_read_b128 v[206:209], v163 offset:5120
	ds_read_b128 v[210:213], v163 offset:6144
	ds_read_b128 v[214:217], v163 offset:7168
	global_load_lds_dwordx4 v[218:219], off
	s_add_i32 m0, s29, 0xe000
	v_lshl_add_u64 v[218:219], s[0:1], 0, v[138:139]
	global_load_lds_dwordx4 v[218:219], off
	s_waitcnt vmcnt(8) lgkmcnt(0)
	s_barrier
	v_mfma_f32_16x16x32_bf16 v[124:127], v[144:147], v[186:189], v[124:127]
	v_mfma_f32_16x16x32_bf16 v[120:123], v[152:155], v[186:189], v[120:123]
	v_mfma_f32_16x16x32_bf16 v[116:119], v[144:147], v[194:197], v[116:119]
	v_mfma_f32_16x16x32_bf16 v[104:107], v[152:155], v[194:197], v[104:107]
	v_mfma_f32_16x16x32_bf16 v[92:95], v[144:147], v[202:205], v[92:95]
	v_mfma_f32_16x16x32_bf16 v[88:91], v[152:155], v[202:205], v[88:91]
	v_mfma_f32_16x16x32_bf16 v[76:79], v[144:147], v[210:213], v[76:79]
	v_mfma_f32_16x16x32_bf16 v[72:75], v[152:155], v[210:213], v[72:75]
	v_mfma_f32_16x16x32_bf16 v[124:127], v[148:151], v[190:193], v[124:127]
	v_mfma_f32_16x16x32_bf16 v[120:123], v[166:169], v[190:193], v[120:123]
	v_mfma_f32_16x16x32_bf16 v[116:119], v[148:151], v[198:201], v[116:119]
	v_mfma_f32_16x16x32_bf16 v[104:107], v[166:169], v[198:201], v[104:107]
	v_mfma_f32_16x16x32_bf16 v[92:95], v[148:151], v[206:209], v[92:95]
	v_mfma_f32_16x16x32_bf16 v[88:91], v[166:169], v[206:209], v[88:91]
	v_mfma_f32_16x16x32_bf16 v[76:79], v[148:151], v[214:217], v[76:79]
	v_mfma_f32_16x16x32_bf16 v[72:75], v[166:169], v[214:217], v[72:75]
	v_mfma_f32_16x16x32_bf16 v[112:115], v[170:173], v[186:189], v[112:115]
	v_mfma_f32_16x16x32_bf16 v[108:111], v[178:181], v[186:189], v[108:111]
	v_mfma_f32_16x16x32_bf16 v[100:103], v[170:173], v[194:197], v[100:103]
	v_mfma_f32_16x16x32_bf16 v[96:99], v[178:181], v[194:197], v[96:99]
	v_mfma_f32_16x16x32_bf16 v[84:87], v[170:173], v[202:205], v[84:87]
	v_mfma_f32_16x16x32_bf16 v[80:83], v[178:181], v[202:205], v[80:83]
	v_mfma_f32_16x16x32_bf16 v[68:71], v[170:173], v[210:213], v[68:71]
	v_mfma_f32_16x16x32_bf16 v[64:67], v[178:181], v[210:213], v[64:67]
	v_mfma_f32_16x16x32_bf16 v[112:115], v[174:177], v[190:193], v[112:115]
	v_mfma_f32_16x16x32_bf16 v[108:111], v[182:185], v[190:193], v[108:111]
	v_mfma_f32_16x16x32_bf16 v[100:103], v[174:177], v[198:201], v[100:103]
	v_mfma_f32_16x16x32_bf16 v[96:99], v[182:185], v[198:201], v[96:99]
	v_mfma_f32_16x16x32_bf16 v[84:87], v[174:177], v[206:209], v[84:87]
	v_mfma_f32_16x16x32_bf16 v[80:83], v[182:185], v[206:209], v[80:83]
	v_mfma_f32_16x16x32_bf16 v[68:71], v[174:177], v[214:217], v[68:71]
	v_mfma_f32_16x16x32_bf16 v[64:67], v[182:185], v[214:217], v[64:67]
	s_barrier
	s_add_i32 s53, s46, s38
	v_lshl_add_u64 v[218:219], s[30:31], 0, v[132:133]
	s_mov_b32 m0, s53
	ds_read_b128 v[186:189], v163 offset:16384
	ds_read_b128 v[190:193], v163 offset:17408
	ds_read_b128 v[194:197], v163 offset:18432
	ds_read_b128 v[198:201], v163 offset:19456
	ds_read_b128 v[202:205], v163 offset:20480
	ds_read_b128 v[206:209], v163 offset:21504
	ds_read_b128 v[210:213], v163 offset:22528
	ds_read_b128 v[214:217], v163 offset:23552
	global_load_lds_dwordx4 v[218:219], off
	s_add_i32 m0, s53, 0x2000
	s_add_u32 s54, s30, 0x40000
	v_lshl_add_u64 v[220:221], s[30:31], 0, v[128:129]
	s_addc_u32 s55, s31, 0
	s_add_i32 s53, s47, s38
	global_load_lds_dwordx4 v[220:221], off
	v_lshl_add_u64 v[222:223], s[54:55], 0, v[132:133]
	s_mov_b32 m0, s53
	v_lshl_add_u64 v[224:225], s[34:35], 0, v[130:131]
	global_load_lds_dwordx4 v[222:223], off
	s_add_i32 m0, s53, 0x2000
	v_lshl_add_u64 v[222:223], s[54:55], 0, v[128:129]
	global_load_lds_dwordx4 v[222:223], off
	s_mov_b32 m0, s29
	v_lshl_add_u64 v[222:223], s[34:35], 0, v[134:135]
	global_load_lds_dwordx4 v[222:223], off
	s_mov_b32 m0, s40
	s_nop 0
	global_load_lds_dwordx4 v[224:225], off
	s_waitcnt vmcnt(8) lgkmcnt(0)
	s_barrier
	v_mfma_f32_16x16x32_bf16 v[60:63], v[144:147], v[186:189], v[60:63]
	v_mfma_f32_16x16x32_bf16 v[56:59], v[152:155], v[186:189], v[56:59]
	v_mfma_f32_16x16x32_bf16 v[44:47], v[144:147], v[194:197], v[44:47]
	v_mfma_f32_16x16x32_bf16 v[40:43], v[152:155], v[194:197], v[40:43]
	v_mfma_f32_16x16x32_bf16 v[28:31], v[144:147], v[202:205], v[28:31]
	v_mfma_f32_16x16x32_bf16 v[24:27], v[152:155], v[202:205], v[24:27]
	v_mfma_f32_16x16x32_bf16 v[12:15], v[144:147], v[210:213], v[12:15]
	v_mfma_f32_16x16x32_bf16 v[8:11], v[152:155], v[210:213], v[8:11]
	v_mfma_f32_16x16x32_bf16 v[60:63], v[148:151], v[190:193], v[60:63]
	v_mfma_f32_16x16x32_bf16 v[56:59], v[166:169], v[190:193], v[56:59]
	v_mfma_f32_16x16x32_bf16 v[44:47], v[148:151], v[198:201], v[44:47]
	v_mfma_f32_16x16x32_bf16 v[40:43], v[166:169], v[198:201], v[40:43]
	v_mfma_f32_16x16x32_bf16 v[28:31], v[148:151], v[206:209], v[28:31]
	v_mfma_f32_16x16x32_bf16 v[24:27], v[166:169], v[206:209], v[24:27]
	v_mfma_f32_16x16x32_bf16 v[12:15], v[148:151], v[214:217], v[12:15]
	v_mfma_f32_16x16x32_bf16 v[8:11], v[166:169], v[214:217], v[8:11]
	v_mfma_f32_16x16x32_bf16 v[52:55], v[170:173], v[186:189], v[52:55]
	v_mfma_f32_16x16x32_bf16 v[48:51], v[178:181], v[186:189], v[48:51]
	v_mfma_f32_16x16x32_bf16 v[36:39], v[170:173], v[194:197], v[36:39]
	v_mfma_f32_16x16x32_bf16 v[32:35], v[178:181], v[194:197], v[32:35]
	v_mfma_f32_16x16x32_bf16 v[20:23], v[170:173], v[202:205], v[20:23]
	v_mfma_f32_16x16x32_bf16 v[16:19], v[178:181], v[202:205], v[16:19]
	v_mfma_f32_16x16x32_bf16 v[4:7], v[170:173], v[210:213], v[4:7]
	v_mfma_f32_16x16x32_bf16 v[0:3], v[178:181], v[210:213], v[0:3]
	v_mfma_f32_16x16x32_bf16 v[52:55], v[174:177], v[190:193], v[52:55]
	v_mfma_f32_16x16x32_bf16 v[48:51], v[182:185], v[190:193], v[48:51]
	v_mfma_f32_16x16x32_bf16 v[36:39], v[174:177], v[198:201], v[36:39]
	v_mfma_f32_16x16x32_bf16 v[32:35], v[182:185], v[198:201], v[32:35]
	v_mfma_f32_16x16x32_bf16 v[20:23], v[174:177], v[206:209], v[20:23]
	v_mfma_f32_16x16x32_bf16 v[16:19], v[182:185], v[206:209], v[16:19]
	v_mfma_f32_16x16x32_bf16 v[4:7], v[174:177], v[214:217], v[4:7]
	v_mfma_f32_16x16x32_bf16 v[0:3], v[182:185], v[214:217], v[0:3]
	s_barrier
	s_add_i32 s53, 0, 0x18000
	v_add_u32_e32 v165, s53, v157
	s_add_i32 s54, 0, 0x1c000
	ds_read_b128 v[144:147], v165
	ds_read_b128 v[148:151], v165 offset:1024
	ds_read_b128 v[152:155], v165 offset:2048
	ds_read_b128 v[166:169], v165 offset:3072
	v_add_u32_e32 v165, s54, v157
	ds_read_b128 v[170:173], v165
	ds_read_b128 v[174:177], v165 offset:1024
	ds_read_b128 v[178:181], v165 offset:2048
	ds_read_b128 v[182:185], v165 offset:3072
	s_add_u32 s34, s34, 0x40000
	s_addc_u32 s35, s35, 0
	s_mov_b32 m0, s41
	v_lshl_add_u64 v[226:227], s[34:35], 0, v[134:135]
	ds_read_b128 v[186:189], v163 offset:32768
	ds_read_b128 v[190:193], v163 offset:33792
	ds_read_b128 v[194:197], v163 offset:34816
	ds_read_b128 v[198:201], v163 offset:35840
	ds_read_b128 v[202:205], v163 offset:36864
	ds_read_b128 v[206:209], v163 offset:37888
	ds_read_b128 v[210:213], v163 offset:38912
	ds_read_b128 v[214:217], v163 offset:39936
	global_load_lds_dwordx4 v[226:227], off
	s_mov_b32 m0, s42
	v_lshl_add_u64 v[226:227], s[34:35], 0, v[130:131]
	global_load_lds_dwordx4 v[226:227], off
	s_waitcnt vmcnt(8) lgkmcnt(0)
	s_barrier
	v_mfma_f32_16x16x32_bf16 v[124:127], v[144:147], v[186:189], v[124:127]
	v_mfma_f32_16x16x32_bf16 v[120:123], v[152:155], v[186:189], v[120:123]
	v_mfma_f32_16x16x32_bf16 v[116:119], v[144:147], v[194:197], v[116:119]
	v_mfma_f32_16x16x32_bf16 v[104:107], v[152:155], v[194:197], v[104:107]
	v_mfma_f32_16x16x32_bf16 v[92:95], v[144:147], v[202:205], v[92:95]
	v_mfma_f32_16x16x32_bf16 v[88:91], v[152:155], v[202:205], v[88:91]
	v_mfma_f32_16x16x32_bf16 v[76:79], v[144:147], v[210:213], v[76:79]
	v_mfma_f32_16x16x32_bf16 v[72:75], v[152:155], v[210:213], v[72:75]
	v_mfma_f32_16x16x32_bf16 v[124:127], v[148:151], v[190:193], v[124:127]
	v_mfma_f32_16x16x32_bf16 v[120:123], v[166:169], v[190:193], v[120:123]
	v_mfma_f32_16x16x32_bf16 v[116:119], v[148:151], v[198:201], v[116:119]
	v_mfma_f32_16x16x32_bf16 v[104:107], v[166:169], v[198:201], v[104:107]
	v_mfma_f32_16x16x32_bf16 v[92:95], v[148:151], v[206:209], v[92:95]
	v_mfma_f32_16x16x32_bf16 v[88:91], v[166:169], v[206:209], v[88:91]
	v_mfma_f32_16x16x32_bf16 v[76:79], v[148:151], v[214:217], v[76:79]
	v_mfma_f32_16x16x32_bf16 v[72:75], v[166:169], v[214:217], v[72:75]
	v_mfma_f32_16x16x32_bf16 v[112:115], v[170:173], v[186:189], v[112:115]
	v_mfma_f32_16x16x32_bf16 v[108:111], v[178:181], v[186:189], v[108:111]
	v_mfma_f32_16x16x32_bf16 v[100:103], v[170:173], v[194:197], v[100:103]
	v_mfma_f32_16x16x32_bf16 v[96:99], v[178:181], v[194:197], v[96:99]
	v_mfma_f32_16x16x32_bf16 v[84:87], v[170:173], v[202:205], v[84:87]
	v_mfma_f32_16x16x32_bf16 v[80:83], v[178:181], v[202:205], v[80:83]
	v_mfma_f32_16x16x32_bf16 v[68:71], v[170:173], v[210:213], v[68:71]
	v_mfma_f32_16x16x32_bf16 v[64:67], v[178:181], v[210:213], v[64:67]
	v_mfma_f32_16x16x32_bf16 v[112:115], v[174:177], v[190:193], v[112:115]
	v_mfma_f32_16x16x32_bf16 v[108:111], v[182:185], v[190:193], v[108:111]
	v_mfma_f32_16x16x32_bf16 v[100:103], v[174:177], v[198:201], v[100:103]
	v_mfma_f32_16x16x32_bf16 v[96:99], v[182:185], v[198:201], v[96:99]
	v_mfma_f32_16x16x32_bf16 v[84:87], v[174:177], v[206:209], v[84:87]
	v_mfma_f32_16x16x32_bf16 v[80:83], v[182:185], v[206:209], v[80:83]
	v_mfma_f32_16x16x32_bf16 v[68:71], v[174:177], v[214:217], v[68:71]
	v_mfma_f32_16x16x32_bf16 v[64:67], v[182:185], v[214:217], v[64:67]
	s_barrier
	s_add_i32 s34, s53, s38
	v_lshl_add_u64 v[218:219], v[218:219], 0, s[6:7]
	s_mov_b32 m0, s34
	ds_read_b128 v[186:189], v163 offset:49152
	ds_read_b128 v[190:193], v163 offset:50176
	ds_read_b128 v[194:197], v163 offset:51200
	ds_read_b128 v[198:201], v163 offset:52224
	ds_read_b128 v[202:205], v163 offset:53248
	ds_read_b128 v[206:209], v163 offset:54272
	ds_read_b128 v[210:213], v163 offset:55296
	ds_read_b128 v[214:217], v163 offset:56320
	global_load_lds_dwordx4 v[218:219], off
	s_add_i32 m0, s34, 0x2000
	s_add_u32 s30, s30, 0x40080
	v_lshl_add_u64 v[218:219], v[220:221], 0, s[6:7]
	s_addc_u32 s31, s31, 0
	s_add_i32 s34, s54, s38
	global_load_lds_dwordx4 v[218:219], off
	s_mov_b32 m0, s34
	v_lshl_add_u64 v[218:219], s[30:31], 0, v[132:133]
	global_load_lds_dwordx4 v[218:219], off
	s_add_i32 m0, s34, 0x2000
	v_lshl_add_u64 v[218:219], s[30:31], 0, v[128:129]
	global_load_lds_dwordx4 v[218:219], off
	s_mov_b32 m0, s44
	v_lshl_add_u64 v[218:219], v[222:223], 0, s[6:7]
	global_load_lds_dwordx4 v[218:219], off
	s_mov_b32 m0, s45
	v_lshl_add_u64 v[218:219], v[224:225], 0, s[6:7]
	global_load_lds_dwordx4 v[218:219], off
	s_waitcnt vmcnt(8) lgkmcnt(0)
	s_barrier
	v_mfma_f32_16x16x32_bf16 v[60:63], v[144:147], v[186:189], v[60:63]
	v_mfma_f32_16x16x32_bf16 v[56:59], v[152:155], v[186:189], v[56:59]
	v_mfma_f32_16x16x32_bf16 v[44:47], v[144:147], v[194:197], v[44:47]
	v_mfma_f32_16x16x32_bf16 v[40:43], v[152:155], v[194:197], v[40:43]
	v_mfma_f32_16x16x32_bf16 v[28:31], v[144:147], v[202:205], v[28:31]
	v_mfma_f32_16x16x32_bf16 v[24:27], v[152:155], v[202:205], v[24:27]
	v_mfma_f32_16x16x32_bf16 v[12:15], v[144:147], v[210:213], v[12:15]
	v_mfma_f32_16x16x32_bf16 v[8:11], v[152:155], v[210:213], v[8:11]
	v_mfma_f32_16x16x32_bf16 v[60:63], v[148:151], v[190:193], v[60:63]
	v_mfma_f32_16x16x32_bf16 v[56:59], v[166:169], v[190:193], v[56:59]
	v_mfma_f32_16x16x32_bf16 v[44:47], v[148:151], v[198:201], v[44:47]
	v_mfma_f32_16x16x32_bf16 v[40:43], v[166:169], v[198:201], v[40:43]
	v_mfma_f32_16x16x32_bf16 v[28:31], v[148:151], v[206:209], v[28:31]
	v_mfma_f32_16x16x32_bf16 v[24:27], v[166:169], v[206:209], v[24:27]
	v_mfma_f32_16x16x32_bf16 v[12:15], v[148:151], v[214:217], v[12:15]
	v_mfma_f32_16x16x32_bf16 v[8:11], v[166:169], v[214:217], v[8:11]
	v_mfma_f32_16x16x32_bf16 v[52:55], v[170:173], v[186:189], v[52:55]
	v_mfma_f32_16x16x32_bf16 v[48:51], v[178:181], v[186:189], v[48:51]
	v_mfma_f32_16x16x32_bf16 v[36:39], v[170:173], v[194:197], v[36:39]
	v_mfma_f32_16x16x32_bf16 v[32:35], v[178:181], v[194:197], v[32:35]
	v_mfma_f32_16x16x32_bf16 v[20:23], v[170:173], v[202:205], v[20:23]
	v_mfma_f32_16x16x32_bf16 v[16:19], v[178:181], v[202:205], v[16:19]
	v_mfma_f32_16x16x32_bf16 v[4:7], v[170:173], v[210:213], v[4:7]
	v_mfma_f32_16x16x32_bf16 v[0:3], v[178:181], v[210:213], v[0:3]
	v_mfma_f32_16x16x32_bf16 v[52:55], v[174:177], v[190:193], v[52:55]
	v_mfma_f32_16x16x32_bf16 v[48:51], v[182:185], v[190:193], v[48:51]
	v_mfma_f32_16x16x32_bf16 v[36:39], v[174:177], v[198:201], v[36:39]
	v_mfma_f32_16x16x32_bf16 v[32:35], v[182:185], v[198:201], v[32:35]
	v_mfma_f32_16x16x32_bf16 v[20:23], v[174:177], v[206:209], v[20:23]
	v_mfma_f32_16x16x32_bf16 v[16:19], v[182:185], v[206:209], v[16:19]
	v_mfma_f32_16x16x32_bf16 v[4:7], v[174:177], v[214:217], v[4:7]
	v_mfma_f32_16x16x32_bf16 v[0:3], v[182:185], v[214:217], v[0:3]
	s_barrier
	s_add_i32 s52, s52, 2
	s_add_u32 s0, s0, 0x100
	s_addc_u32 s1, s1, 0
	s_add_u32 s50, s50, 0x100
	s_addc_u32 s51, s51, 0
	s_cmp_gt_u32 s52, 13
	s_cbranch_scc0 .LBB0_636

.LBB0_710:
	s_ashr_i32 s17, s16, 31
	s_lshl_b64 s[26:27], s[16:17], 21
	s_add_u32 s26, s92, s26
	s_addc_u32 s27, s93, s27
	s_and_b64 s[28:29], s[6:7], exec
	s_cselect_b32 s17, s27, s1
	s_cselect_b32 s33, s26, s0
	s_ashr_i32 s15, s14, 31
	s_lshl_b64 s[28:29], s[14:15], 21
	s_add_u32 s28, s56, s28
	s_addc_u32 s29, s57, s29
	s_and_b64 s[38:39], s[6:7], exec
	s_cselect_b32 s15, s29, s37
	s_cselect_b32 s55, s28, s36
	s_add_u32 s0, s0, 0x100080
	s_addc_u32 s1, s1, 0
	s_add_u32 s58, s36, 0x100
	s_addc_u32 s59, s37, 0
	s_mov_b32 s60, -2
	s_waitcnt lgkmcnt(0)
	ds_read_b128 v[128:131], v188
	ds_read_b128 v[132:135], v188 offset:1024
	ds_read_b128 v[136:139], v188 offset:2048
	ds_read_b128 v[140:143], v188 offset:3072
	ds_read_b128 v[144:147], v189
	ds_read_b128 v[148:151], v189 offset:1024
	ds_read_b128 v[152:155], v189 offset:2048
	ds_read_b128 v[156:159], v189 offset:3072
	s_add_u32 s36, s0, 0xfff00080
	s_addc_u32 s37, s1, -1
	s_cmp_eq_u32 s60, 60
	s_cselect_b32 s39, s17, s37
	s_cselect_b32 s38, s33, s36
	s_cselect_b32 s37, s15, s59
	s_cselect_b32 s36, s55, s58
	v_lshl_add_u64 v[220:221], s[0:1], 0, v[170:171]
	s_add_i32 m0, s31, 0xc000
	ds_read_b128 v[178:181], v190
	ds_read_b128 v[192:195], v190 offset:1024
	ds_read_b128 v[196:199], v190 offset:2048
	ds_read_b128 v[200:203], v190 offset:3072
	ds_read_b128 v[204:207], v190 offset:4096
	ds_read_b128 v[208:211], v190 offset:5120
	ds_read_b128 v[212:215], v190 offset:6144
	ds_read_b128 v[216:219], v190 offset:7168
	global_load_lds_dwordx4 v[220:221], off
	s_add_i32 m0, s31, 0xe000
	v_lshl_add_u64 v[220:221], s[0:1], 0, v[172:173]
	global_load_lds_dwordx4 v[220:221], off
	s_waitcnt vmcnt(8) lgkmcnt(0)
	s_barrier
	v_mfma_f32_16x16x32_bf16 v[124:127], v[128:131], v[178:181], 0
	v_mfma_f32_16x16x32_bf16 v[120:123], v[136:139], v[178:181], 0
	v_mfma_f32_16x16x32_bf16 v[108:111], v[128:131], v[196:199], 0
	v_mfma_f32_16x16x32_bf16 v[104:107], v[136:139], v[196:199], 0
	v_mfma_f32_16x16x32_bf16 v[92:95], v[128:131], v[204:207], 0
	v_mfma_f32_16x16x32_bf16 v[88:91], v[136:139], v[204:207], 0
	v_mfma_f32_16x16x32_bf16 v[76:79], v[128:131], v[212:215], 0
	v_mfma_f32_16x16x32_bf16 v[72:75], v[136:139], v[212:215], 0
	v_mfma_f32_16x16x32_bf16 v[124:127], v[132:135], v[192:195], v[124:127]
	v_mfma_f32_16x16x32_bf16 v[120:123], v[140:143], v[192:195], v[120:123]
	v_mfma_f32_16x16x32_bf16 v[108:111], v[132:135], v[200:203], v[108:111]
	v_mfma_f32_16x16x32_bf16 v[104:107], v[140:143], v[200:203], v[104:107]
	v_mfma_f32_16x16x32_bf16 v[92:95], v[132:135], v[208:211], v[92:95]
	v_mfma_f32_16x16x32_bf16 v[88:91], v[140:143], v[208:211], v[88:91]
	v_mfma_f32_16x16x32_bf16 v[76:79], v[132:135], v[216:219], v[76:79]
	v_mfma_f32_16x16x32_bf16 v[72:75], v[140:143], v[216:219], v[72:75]
	v_mfma_f32_16x16x32_bf16 v[116:119], v[144:147], v[178:181], 0
	v_mfma_f32_16x16x32_bf16 v[112:115], v[152:155], v[178:181], 0
	v_mfma_f32_16x16x32_bf16 v[100:103], v[144:147], v[196:199], 0
	v_mfma_f32_16x16x32_bf16 v[96:99], v[152:155], v[196:199], 0
	v_mfma_f32_16x16x32_bf16 v[84:87], v[144:147], v[204:207], 0
	v_mfma_f32_16x16x32_bf16 v[80:83], v[152:155], v[204:207], 0
	v_mfma_f32_16x16x32_bf16 v[68:71], v[144:147], v[212:215], 0
	v_mfma_f32_16x16x32_bf16 v[64:67], v[152:155], v[212:215], 0
	v_mfma_f32_16x16x32_bf16 v[116:119], v[148:151], v[192:195], v[116:119]
	v_mfma_f32_16x16x32_bf16 v[112:115], v[156:159], v[192:195], v[112:115]
	v_mfma_f32_16x16x32_bf16 v[100:103], v[148:151], v[200:203], v[100:103]
	v_mfma_f32_16x16x32_bf16 v[96:99], v[156:159], v[200:203], v[96:99]
	v_mfma_f32_16x16x32_bf16 v[84:87], v[148:151], v[208:211], v[84:87]
	v_mfma_f32_16x16x32_bf16 v[80:83], v[156:159], v[208:211], v[80:83]
	v_mfma_f32_16x16x32_bf16 v[68:71], v[148:151], v[216:219], v[68:71]
	v_mfma_f32_16x16x32_bf16 v[64:67], v[156:159], v[216:219], v[64:67]
	s_barrier
	s_add_i32 s61, s49, s40
	v_lshl_add_u64 v[220:221], s[36:37], 0, v[164:165]
	s_mov_b32 m0, s61
	ds_read_b128 v[178:181], v190 offset:16384
	ds_read_b128 v[192:195], v190 offset:17408
	ds_read_b128 v[196:199], v190 offset:18432
	ds_read_b128 v[200:203], v190 offset:19456
	ds_read_b128 v[204:207], v190 offset:20480
	ds_read_b128 v[208:211], v190 offset:21504
	ds_read_b128 v[212:215], v190 offset:22528
	ds_read_b128 v[216:219], v190 offset:23552
	global_load_lds_dwordx4 v[220:221], off
	s_add_i32 m0, s61, 0x2000
	s_add_u32 s62, s36, 0x100000
	v_lshl_add_u64 v[222:223], s[36:37], 0, v[168:169]
	s_addc_u32 s63, s37, 0
	s_add_i32 s61, s50, s40
	global_load_lds_dwordx4 v[222:223], off
	v_lshl_add_u64 v[224:225], s[62:63], 0, v[164:165]
	s_mov_b32 m0, s61
	v_lshl_add_u64 v[226:227], s[38:39], 0, v[166:167]
	global_load_lds_dwordx4 v[224:225], off
	s_add_i32 m0, s61, 0x2000
	v_lshl_add_u64 v[224:225], s[62:63], 0, v[168:169]
	global_load_lds_dwordx4 v[224:225], off
	s_mov_b32 m0, s31
	v_lshl_add_u64 v[224:225], s[38:39], 0, v[162:163]
	global_load_lds_dwordx4 v[224:225], off
	s_mov_b32 m0, s35
	s_nop 0
	global_load_lds_dwordx4 v[226:227], off
	s_waitcnt vmcnt(8) lgkmcnt(0)
	s_barrier
	v_mfma_f32_16x16x32_bf16 v[60:63], v[128:131], v[178:181], 0
	v_mfma_f32_16x16x32_bf16 v[56:59], v[136:139], v[178:181], 0
	v_mfma_f32_16x16x32_bf16 v[44:47], v[128:131], v[196:199], 0
	v_mfma_f32_16x16x32_bf16 v[40:43], v[136:139], v[196:199], 0
	v_mfma_f32_16x16x32_bf16 v[28:31], v[128:131], v[204:207], 0
	v_mfma_f32_16x16x32_bf16 v[24:27], v[136:139], v[204:207], 0
	v_mfma_f32_16x16x32_bf16 v[12:15], v[128:131], v[212:215], 0
	v_mfma_f32_16x16x32_bf16 v[8:11], v[136:139], v[212:215], 0
	v_mfma_f32_16x16x32_bf16 v[60:63], v[132:135], v[192:195], v[60:63]
	v_mfma_f32_16x16x32_bf16 v[56:59], v[140:143], v[192:195], v[56:59]
	v_mfma_f32_16x16x32_bf16 v[44:47], v[132:135], v[200:203], v[44:47]
	v_mfma_f32_16x16x32_bf16 v[40:43], v[140:143], v[200:203], v[40:43]
	v_mfma_f32_16x16x32_bf16 v[28:31], v[132:135], v[208:211], v[28:31]
	v_mfma_f32_16x16x32_bf16 v[24:27], v[140:143], v[208:211], v[24:27]
	v_mfma_f32_16x16x32_bf16 v[12:15], v[132:135], v[216:219], v[12:15]
	v_mfma_f32_16x16x32_bf16 v[8:11], v[140:143], v[216:219], v[8:11]
	v_mfma_f32_16x16x32_bf16 v[52:55], v[144:147], v[178:181], 0
	v_mfma_f32_16x16x32_bf16 v[48:51], v[152:155], v[178:181], 0
	v_mfma_f32_16x16x32_bf16 v[36:39], v[144:147], v[196:199], 0
	v_mfma_f32_16x16x32_bf16 v[32:35], v[152:155], v[196:199], 0
	v_mfma_f32_16x16x32_bf16 v[20:23], v[144:147], v[204:207], 0
	v_mfma_f32_16x16x32_bf16 v[16:19], v[152:155], v[204:207], 0
	v_mfma_f32_16x16x32_bf16 v[4:7], v[144:147], v[212:215], 0
	v_mfma_f32_16x16x32_bf16 v[0:3], v[152:155], v[212:215], 0
	v_mfma_f32_16x16x32_bf16 v[52:55], v[148:151], v[192:195], v[52:55]
	v_mfma_f32_16x16x32_bf16 v[48:51], v[156:159], v[192:195], v[48:51]
	v_mfma_f32_16x16x32_bf16 v[36:39], v[148:151], v[200:203], v[36:39]
	v_mfma_f32_16x16x32_bf16 v[32:35], v[156:159], v[200:203], v[32:35]
	v_mfma_f32_16x16x32_bf16 v[20:23], v[148:151], v[208:211], v[20:23]
	v_mfma_f32_16x16x32_bf16 v[16:19], v[156:159], v[208:211], v[16:19]
	v_mfma_f32_16x16x32_bf16 v[4:7], v[148:151], v[216:219], v[4:7]
	v_mfma_f32_16x16x32_bf16 v[0:3], v[156:159], v[216:219], v[0:3]
	s_barrier
	s_add_i32 s61, 0, 0x18000
	s_add_i32 s62, 0, 0x1c000
	v_add_u32_e32 v140, s61, v183
	v_add_u32_e32 v156, s62, v183
	ds_read_b128 v[128:131], v140
	ds_read_b128 v[132:135], v140 offset:1024
	ds_read_b128 v[136:139], v140 offset:2048
	ds_read_b128 v[140:143], v140 offset:3072
	ds_read_b128 v[144:147], v156
	ds_read_b128 v[148:151], v156 offset:1024
	ds_read_b128 v[152:155], v156 offset:2048
	ds_read_b128 v[156:159], v156 offset:3072
	s_add_u32 s38, s38, 0x100000
	s_addc_u32 s39, s39, 0
	s_mov_b32 m0, s41
	v_lshl_add_u64 v[228:229], s[38:39], 0, v[162:163]
	ds_read_b128 v[178:181], v190 offset:32768
	ds_read_b128 v[192:195], v190 offset:33792
	ds_read_b128 v[196:199], v190 offset:34816
	ds_read_b128 v[200:203], v190 offset:35840
	ds_read_b128 v[204:207], v190 offset:36864
	ds_read_b128 v[208:211], v190 offset:37888
	ds_read_b128 v[212:215], v190 offset:38912
	ds_read_b128 v[216:219], v190 offset:39936
	global_load_lds_dwordx4 v[228:229], off
	s_mov_b32 m0, s42
	v_lshl_add_u64 v[228:229], s[38:39], 0, v[166:167]
	global_load_lds_dwordx4 v[228:229], off
	s_waitcnt vmcnt(8) lgkmcnt(0)
	s_barrier
	v_mfma_f32_16x16x32_bf16 v[124:127], v[128:131], v[178:181], v[124:127]
	v_mfma_f32_16x16x32_bf16 v[120:123], v[136:139], v[178:181], v[120:123]
	v_mfma_f32_16x16x32_bf16 v[108:111], v[128:131], v[196:199], v[108:111]
	v_mfma_f32_16x16x32_bf16 v[104:107], v[136:139], v[196:199], v[104:107]
	v_mfma_f32_16x16x32_bf16 v[92:95], v[128:131], v[204:207], v[92:95]
	v_mfma_f32_16x16x32_bf16 v[88:91], v[136:139], v[204:207], v[88:91]
	v_mfma_f32_16x16x32_bf16 v[76:79], v[128:131], v[212:215], v[76:79]
	v_mfma_f32_16x16x32_bf16 v[72:75], v[136:139], v[212:215], v[72:75]
	v_mfma_f32_16x16x32_bf16 v[124:127], v[132:135], v[192:195], v[124:127]
	v_mfma_f32_16x16x32_bf16 v[120:123], v[140:143], v[192:195], v[120:123]
	v_mfma_f32_16x16x32_bf16 v[108:111], v[132:135], v[200:203], v[108:111]
	v_mfma_f32_16x16x32_bf16 v[104:107], v[140:143], v[200:203], v[104:107]
	v_mfma_f32_16x16x32_bf16 v[92:95], v[132:135], v[208:211], v[92:95]
	v_mfma_f32_16x16x32_bf16 v[88:91], v[140:143], v[208:211], v[88:91]
	v_mfma_f32_16x16x32_bf16 v[76:79], v[132:135], v[216:219], v[76:79]
	v_mfma_f32_16x16x32_bf16 v[72:75], v[140:143], v[216:219], v[72:75]
	v_mfma_f32_16x16x32_bf16 v[116:119], v[144:147], v[178:181], v[116:119]
	v_mfma_f32_16x16x32_bf16 v[112:115], v[152:155], v[178:181], v[112:115]
	v_mfma_f32_16x16x32_bf16 v[100:103], v[144:147], v[196:199], v[100:103]
	v_mfma_f32_16x16x32_bf16 v[96:99], v[152:155], v[196:199], v[96:99]
	v_mfma_f32_16x16x32_bf16 v[84:87], v[144:147], v[204:207], v[84:87]
	v_mfma_f32_16x16x32_bf16 v[80:83], v[152:155], v[204:207], v[80:83]
	v_mfma_f32_16x16x32_bf16 v[68:71], v[144:147], v[212:215], v[68:71]
	v_mfma_f32_16x16x32_bf16 v[64:67], v[152:155], v[212:215], v[64:67]
	v_mfma_f32_16x16x32_bf16 v[116:119], v[148:151], v[192:195], v[116:119]
	v_mfma_f32_16x16x32_bf16 v[112:115], v[156:159], v[192:195], v[112:115]
	v_mfma_f32_16x16x32_bf16 v[100:103], v[148:151], v[200:203], v[100:103]
	v_mfma_f32_16x16x32_bf16 v[96:99], v[156:159], v[200:203], v[96:99]
	v_mfma_f32_16x16x32_bf16 v[84:87], v[148:151], v[208:211], v[84:87]
	v_mfma_f32_16x16x32_bf16 v[80:83], v[156:159], v[208:211], v[80:83]
	v_mfma_f32_16x16x32_bf16 v[68:71], v[148:151], v[216:219], v[68:71]
	v_mfma_f32_16x16x32_bf16 v[64:67], v[156:159], v[216:219], v[64:67]
	s_barrier
	s_add_i32 s38, s61, s40
	v_lshl_add_u64 v[220:221], v[220:221], 0, s[8:9]
	s_mov_b32 m0, s38
	ds_read_b128 v[178:181], v190 offset:49152
	ds_read_b128 v[192:195], v190 offset:50176
	ds_read_b128 v[196:199], v190 offset:51200
	ds_read_b128 v[200:203], v190 offset:52224
	ds_read_b128 v[204:207], v190 offset:53248
	ds_read_b128 v[208:211], v190 offset:54272
	ds_read_b128 v[212:215], v190 offset:55296
	ds_read_b128 v[216:219], v190 offset:56320
	global_load_lds_dwordx4 v[220:221], off
	s_add_i32 m0, s38, 0x2000
	s_add_u32 s36, s36, 0x100080
	v_lshl_add_u64 v[220:221], v[222:223], 0, s[8:9]
	s_addc_u32 s37, s37, 0
	s_add_i32 s38, s62, s40
	global_load_lds_dwordx4 v[220:221], off
	s_mov_b32 m0, s38
	v_lshl_add_u64 v[220:221], s[36:37], 0, v[164:165]
	global_load_lds_dwordx4 v[220:221], off
	s_add_i32 m0, s38, 0x2000
	v_lshl_add_u64 v[220:221], s[36:37], 0, v[168:169]
	global_load_lds_dwordx4 v[220:221], off
	s_mov_b32 m0, s45
	v_lshl_add_u64 v[220:221], v[224:225], 0, s[8:9]
	global_load_lds_dwordx4 v[220:221], off
	s_mov_b32 m0, s46
	v_lshl_add_u64 v[220:221], v[226:227], 0, s[8:9]
	global_load_lds_dwordx4 v[220:221], off
	s_waitcnt vmcnt(8) lgkmcnt(0)
	s_barrier
	v_mfma_f32_16x16x32_bf16 v[60:63], v[128:131], v[178:181], v[60:63]
	v_mfma_f32_16x16x32_bf16 v[56:59], v[136:139], v[178:181], v[56:59]
	v_mfma_f32_16x16x32_bf16 v[44:47], v[128:131], v[196:199], v[44:47]
	v_mfma_f32_16x16x32_bf16 v[40:43], v[136:139], v[196:199], v[40:43]
	v_mfma_f32_16x16x32_bf16 v[28:31], v[128:131], v[204:207], v[28:31]
	v_mfma_f32_16x16x32_bf16 v[24:27], v[136:139], v[204:207], v[24:27]
	v_mfma_f32_16x16x32_bf16 v[12:15], v[128:131], v[212:215], v[12:15]
	v_mfma_f32_16x16x32_bf16 v[8:11], v[136:139], v[212:215], v[8:11]
	v_mfma_f32_16x16x32_bf16 v[60:63], v[132:135], v[192:195], v[60:63]
	v_mfma_f32_16x16x32_bf16 v[56:59], v[140:143], v[192:195], v[56:59]
	v_mfma_f32_16x16x32_bf16 v[44:47], v[132:135], v[200:203], v[44:47]
	v_mfma_f32_16x16x32_bf16 v[40:43], v[140:143], v[200:203], v[40:43]
	v_mfma_f32_16x16x32_bf16 v[28:31], v[132:135], v[208:211], v[28:31]
	v_mfma_f32_16x16x32_bf16 v[24:27], v[140:143], v[208:211], v[24:27]
	v_mfma_f32_16x16x32_bf16 v[12:15], v[132:135], v[216:219], v[12:15]
	v_mfma_f32_16x16x32_bf16 v[8:11], v[140:143], v[216:219], v[8:11]
	v_mfma_f32_16x16x32_bf16 v[52:55], v[144:147], v[178:181], v[52:55]
	v_mfma_f32_16x16x32_bf16 v[48:51], v[152:155], v[178:181], v[48:51]
	v_mfma_f32_16x16x32_bf16 v[36:39], v[144:147], v[196:199], v[36:39]
	v_mfma_f32_16x16x32_bf16 v[32:35], v[152:155], v[196:199], v[32:35]
	v_mfma_f32_16x16x32_bf16 v[20:23], v[144:147], v[204:207], v[20:23]
	v_mfma_f32_16x16x32_bf16 v[16:19], v[152:155], v[204:207], v[16:19]
	v_mfma_f32_16x16x32_bf16 v[4:7], v[144:147], v[212:215], v[4:7]
	v_mfma_f32_16x16x32_bf16 v[0:3], v[152:155], v[212:215], v[0:3]
	v_mfma_f32_16x16x32_bf16 v[52:55], v[148:151], v[192:195], v[52:55]
	v_mfma_f32_16x16x32_bf16 v[48:51], v[156:159], v[192:195], v[48:51]
	v_mfma_f32_16x16x32_bf16 v[36:39], v[148:151], v[200:203], v[36:39]
	v_mfma_f32_16x16x32_bf16 v[32:35], v[156:159], v[200:203], v[32:35]
	v_mfma_f32_16x16x32_bf16 v[20:23], v[148:151], v[208:211], v[20:23]
	v_mfma_f32_16x16x32_bf16 v[16:19], v[156:159], v[208:211], v[16:19]
	v_mfma_f32_16x16x32_bf16 v[4:7], v[148:151], v[216:219], v[4:7]
	v_mfma_f32_16x16x32_bf16 v[0:3], v[156:159], v[216:219], v[0:3]
	s_barrier
	s_add_i32 s60, s60, 2
	s_add_u32 s0, s0, 0x100
	s_addc_u32 s1, s1, 0
	s_add_u32 s58, s58, 0x100
	s_addc_u32 s59, s59, 0
	s_cmp_gt_u32 s60, 61
	s_cbranch_scc0 .LBB0_711
	s_branch .Lpeel_exit_4
.LBB0_711:
	ds_read_b128 v[128:131], v188
	ds_read_b128 v[132:135], v188 offset:1024
	ds_read_b128 v[136:139], v188 offset:2048
	ds_read_b128 v[140:143], v188 offset:3072
	ds_read_b128 v[144:147], v189
	ds_read_b128 v[148:151], v189 offset:1024
	ds_read_b128 v[152:155], v189 offset:2048
	ds_read_b128 v[156:159], v189 offset:3072
	s_add_u32 s36, s0, 0xfff00080
	s_addc_u32 s37, s1, -1
	s_cmp_eq_u32 s60, 60
	s_cselect_b32 s39, s17, s37
	s_cselect_b32 s38, s33, s36
	s_cselect_b32 s37, s15, s59
	s_cselect_b32 s36, s55, s58
	v_lshl_add_u64 v[220:221], s[0:1], 0, v[170:171]
	s_add_i32 m0, s31, 0xc000
	ds_read_b128 v[178:181], v190
	ds_read_b128 v[192:195], v190 offset:1024
	ds_read_b128 v[196:199], v190 offset:2048
	ds_read_b128 v[200:203], v190 offset:3072
	ds_read_b128 v[204:207], v190 offset:4096
	ds_read_b128 v[208:211], v190 offset:5120
	ds_read_b128 v[212:215], v190 offset:6144
	ds_read_b128 v[216:219], v190 offset:7168
	global_load_lds_dwordx4 v[220:221], off
	s_add_i32 m0, s31, 0xe000
	v_lshl_add_u64 v[220:221], s[0:1], 0, v[172:173]
	global_load_lds_dwordx4 v[220:221], off
	s_waitcnt vmcnt(8) lgkmcnt(0)
	s_barrier
	v_mfma_f32_16x16x32_bf16 v[124:127], v[128:131], v[178:181], v[124:127]
	v_mfma_f32_16x16x32_bf16 v[120:123], v[136:139], v[178:181], v[120:123]
	v_mfma_f32_16x16x32_bf16 v[108:111], v[128:131], v[196:199], v[108:111]
	v_mfma_f32_16x16x32_bf16 v[104:107], v[136:139], v[196:199], v[104:107]
	v_mfma_f32_16x16x32_bf16 v[92:95], v[128:131], v[204:207], v[92:95]
	v_mfma_f32_16x16x32_bf16 v[88:91], v[136:139], v[204:207], v[88:91]
	v_mfma_f32_16x16x32_bf16 v[76:79], v[128:131], v[212:215], v[76:79]
	v_mfma_f32_16x16x32_bf16 v[72:75], v[136:139], v[212:215], v[72:75]
	v_mfma_f32_16x16x32_bf16 v[124:127], v[132:135], v[192:195], v[124:127]
	v_mfma_f32_16x16x32_bf16 v[120:123], v[140:143], v[192:195], v[120:123]
	v_mfma_f32_16x16x32_bf16 v[108:111], v[132:135], v[200:203], v[108:111]
	v_mfma_f32_16x16x32_bf16 v[104:107], v[140:143], v[200:203], v[104:107]
	v_mfma_f32_16x16x32_bf16 v[92:95], v[132:135], v[208:211], v[92:95]
	v_mfma_f32_16x16x32_bf16 v[88:91], v[140:143], v[208:211], v[88:91]
	v_mfma_f32_16x16x32_bf16 v[76:79], v[132:135], v[216:219], v[76:79]
	v_mfma_f32_16x16x32_bf16 v[72:75], v[140:143], v[216:219], v[72:75]
	v_mfma_f32_16x16x32_bf16 v[116:119], v[144:147], v[178:181], v[116:119]
	v_mfma_f32_16x16x32_bf16 v[112:115], v[152:155], v[178:181], v[112:115]
	v_mfma_f32_16x16x32_bf16 v[100:103], v[144:147], v[196:199], v[100:103]
	v_mfma_f32_16x16x32_bf16 v[96:99], v[152:155], v[196:199], v[96:99]
	v_mfma_f32_16x16x32_bf16 v[84:87], v[144:147], v[204:207], v[84:87]
	v_mfma_f32_16x16x32_bf16 v[80:83], v[152:155], v[204:207], v[80:83]
	v_mfma_f32_16x16x32_bf16 v[68:71], v[144:147], v[212:215], v[68:71]
	v_mfma_f32_16x16x32_bf16 v[64:67], v[152:155], v[212:215], v[64:67]
	v_mfma_f32_16x16x32_bf16 v[116:119], v[148:151], v[192:195], v[116:119]
	v_mfma_f32_16x16x32_bf16 v[112:115], v[156:159], v[192:195], v[112:115]
	v_mfma_f32_16x16x32_bf16 v[100:103], v[148:151], v[200:203], v[100:103]
	v_mfma_f32_16x16x32_bf16 v[96:99], v[156:159], v[200:203], v[96:99]
	v_mfma_f32_16x16x32_bf16 v[84:87], v[148:151], v[208:211], v[84:87]
	v_mfma_f32_16x16x32_bf16 v[80:83], v[156:159], v[208:211], v[80:83]
	v_mfma_f32_16x16x32_bf16 v[68:71], v[148:151], v[216:219], v[68:71]
	v_mfma_f32_16x16x32_bf16 v[64:67], v[156:159], v[216:219], v[64:67]
	s_barrier
	s_add_i32 s61, s49, s40
	v_lshl_add_u64 v[220:221], s[36:37], 0, v[164:165]
	s_mov_b32 m0, s61
	ds_read_b128 v[178:181], v190 offset:16384
	ds_read_b128 v[192:195], v190 offset:17408
	ds_read_b128 v[196:199], v190 offset:18432
	ds_read_b128 v[200:203], v190 offset:19456
	ds_read_b128 v[204:207], v190 offset:20480
	ds_read_b128 v[208:211], v190 offset:21504
	ds_read_b128 v[212:215], v190 offset:22528
	ds_read_b128 v[216:219], v190 offset:23552
	global_load_lds_dwordx4 v[220:221], off
	s_add_i32 m0, s61, 0x2000
	s_add_u32 s62, s36, 0x100000
	v_lshl_add_u64 v[222:223], s[36:37], 0, v[168:169]
	s_addc_u32 s63, s37, 0
	s_add_i32 s61, s50, s40
	global_load_lds_dwordx4 v[222:223], off
	v_lshl_add_u64 v[224:225], s[62:63], 0, v[164:165]
	s_mov_b32 m0, s61
	v_lshl_add_u64 v[226:227], s[38:39], 0, v[166:167]
	global_load_lds_dwordx4 v[224:225], off
	s_add_i32 m0, s61, 0x2000
	v_lshl_add_u64 v[224:225], s[62:63], 0, v[168:169]
	global_load_lds_dwordx4 v[224:225], off
	s_mov_b32 m0, s31
	v_lshl_add_u64 v[224:225], s[38:39], 0, v[162:163]
	global_load_lds_dwordx4 v[224:225], off
	s_mov_b32 m0, s35
	s_nop 0
	global_load_lds_dwordx4 v[226:227], off
	s_waitcnt vmcnt(8) lgkmcnt(0)
	s_barrier
	v_mfma_f32_16x16x32_bf16 v[60:63], v[128:131], v[178:181], v[60:63]
	v_mfma_f32_16x16x32_bf16 v[56:59], v[136:139], v[178:181], v[56:59]
	v_mfma_f32_16x16x32_bf16 v[44:47], v[128:131], v[196:199], v[44:47]
	v_mfma_f32_16x16x32_bf16 v[40:43], v[136:139], v[196:199], v[40:43]
	v_mfma_f32_16x16x32_bf16 v[28:31], v[128:131], v[204:207], v[28:31]
	v_mfma_f32_16x16x32_bf16 v[24:27], v[136:139], v[204:207], v[24:27]
	v_mfma_f32_16x16x32_bf16 v[12:15], v[128:131], v[212:215], v[12:15]
	v_mfma_f32_16x16x32_bf16 v[8:11], v[136:139], v[212:215], v[8:11]
	v_mfma_f32_16x16x32_bf16 v[60:63], v[132:135], v[192:195], v[60:63]
	v_mfma_f32_16x16x32_bf16 v[56:59], v[140:143], v[192:195], v[56:59]
	v_mfma_f32_16x16x32_bf16 v[44:47], v[132:135], v[200:203], v[44:47]
	v_mfma_f32_16x16x32_bf16 v[40:43], v[140:143], v[200:203], v[40:43]
	v_mfma_f32_16x16x32_bf16 v[28:31], v[132:135], v[208:211], v[28:31]
	v_mfma_f32_16x16x32_bf16 v[24:27], v[140:143], v[208:211], v[24:27]
	v_mfma_f32_16x16x32_bf16 v[12:15], v[132:135], v[216:219], v[12:15]
	v_mfma_f32_16x16x32_bf16 v[8:11], v[140:143], v[216:219], v[8:11]
	v_mfma_f32_16x16x32_bf16 v[52:55], v[144:147], v[178:181], v[52:55]
	v_mfma_f32_16x16x32_bf16 v[48:51], v[152:155], v[178:181], v[48:51]
	v_mfma_f32_16x16x32_bf16 v[36:39], v[144:147], v[196:199], v[36:39]
	v_mfma_f32_16x16x32_bf16 v[32:35], v[152:155], v[196:199], v[32:35]
	v_mfma_f32_16x16x32_bf16 v[20:23], v[144:147], v[204:207], v[20:23]
	v_mfma_f32_16x16x32_bf16 v[16:19], v[152:155], v[204:207], v[16:19]
	v_mfma_f32_16x16x32_bf16 v[4:7], v[144:147], v[212:215], v[4:7]
	v_mfma_f32_16x16x32_bf16 v[0:3], v[152:155], v[212:215], v[0:3]
	v_mfma_f32_16x16x32_bf16 v[52:55], v[148:151], v[192:195], v[52:55]
	v_mfma_f32_16x16x32_bf16 v[48:51], v[156:159], v[192:195], v[48:51]
	v_mfma_f32_16x16x32_bf16 v[36:39], v[148:151], v[200:203], v[36:39]
	v_mfma_f32_16x16x32_bf16 v[32:35], v[156:159], v[200:203], v[32:35]
	v_mfma_f32_16x16x32_bf16 v[20:23], v[148:151], v[208:211], v[20:23]
	v_mfma_f32_16x16x32_bf16 v[16:19], v[156:159], v[208:211], v[16:19]
	v_mfma_f32_16x16x32_bf16 v[4:7], v[148:151], v[216:219], v[4:7]
	v_mfma_f32_16x16x32_bf16 v[0:3], v[156:159], v[216:219], v[0:3]
	s_barrier
	s_add_i32 s61, 0, 0x18000
	s_add_i32 s62, 0, 0x1c000
	v_add_u32_e32 v140, s61, v183
	v_add_u32_e32 v156, s62, v183
	ds_read_b128 v[128:131], v140
	ds_read_b128 v[132:135], v140 offset:1024
	ds_read_b128 v[136:139], v140 offset:2048
	ds_read_b128 v[140:143], v140 offset:3072
	ds_read_b128 v[144:147], v156
	ds_read_b128 v[148:151], v156 offset:1024
	ds_read_b128 v[152:155], v156 offset:2048
	ds_read_b128 v[156:159], v156 offset:3072
	s_add_u32 s38, s38, 0x100000
	s_addc_u32 s39, s39, 0
	s_mov_b32 m0, s41
	v_lshl_add_u64 v[228:229], s[38:39], 0, v[162:163]
	ds_read_b128 v[178:181], v190 offset:32768
	ds_read_b128 v[192:195], v190 offset:33792
	ds_read_b128 v[196:199], v190 offset:34816
	ds_read_b128 v[200:203], v190 offset:35840
	ds_read_b128 v[204:207], v190 offset:36864
	ds_read_b128 v[208:211], v190 offset:37888
	ds_read_b128 v[212:215], v190 offset:38912
	ds_read_b128 v[216:219], v190 offset:39936
	global_load_lds_dwordx4 v[228:229], off
	s_mov_b32 m0, s42
	v_lshl_add_u64 v[228:229], s[38:39], 0, v[166:167]
	global_load_lds_dwordx4 v[228:229], off
	s_waitcnt vmcnt(8) lgkmcnt(0)
	s_barrier
	v_mfma_f32_16x16x32_bf16 v[124:127], v[128:131], v[178:181], v[124:127]
	v_mfma_f32_16x16x32_bf16 v[120:123], v[136:139], v[178:181], v[120:123]
	v_mfma_f32_16x16x32_bf16 v[108:111], v[128:131], v[196:199], v[108:111]
	v_mfma_f32_16x16x32_bf16 v[104:107], v[136:139], v[196:199], v[104:107]
	v_mfma_f32_16x16x32_bf16 v[92:95], v[128:131], v[204:207], v[92:95]
	v_mfma_f32_16x16x32_bf16 v[88:91], v[136:139], v[204:207], v[88:91]
	v_mfma_f32_16x16x32_bf16 v[76:79], v[128:131], v[212:215], v[76:79]
	v_mfma_f32_16x16x32_bf16 v[72:75], v[136:139], v[212:215], v[72:75]
	v_mfma_f32_16x16x32_bf16 v[124:127], v[132:135], v[192:195], v[124:127]
	v_mfma_f32_16x16x32_bf16 v[120:123], v[140:143], v[192:195], v[120:123]
	v_mfma_f32_16x16x32_bf16 v[108:111], v[132:135], v[200:203], v[108:111]
	v_mfma_f32_16x16x32_bf16 v[104:107], v[140:143], v[200:203], v[104:107]
	v_mfma_f32_16x16x32_bf16 v[92:95], v[132:135], v[208:211], v[92:95]
	v_mfma_f32_16x16x32_bf16 v[88:91], v[140:143], v[208:211], v[88:91]
	v_mfma_f32_16x16x32_bf16 v[76:79], v[132:135], v[216:219], v[76:79]
	v_mfma_f32_16x16x32_bf16 v[72:75], v[140:143], v[216:219], v[72:75]
	v_mfma_f32_16x16x32_bf16 v[116:119], v[144:147], v[178:181], v[116:119]
	v_mfma_f32_16x16x32_bf16 v[112:115], v[152:155], v[178:181], v[112:115]
	v_mfma_f32_16x16x32_bf16 v[100:103], v[144:147], v[196:199], v[100:103]
	v_mfma_f32_16x16x32_bf16 v[96:99], v[152:155], v[196:199], v[96:99]
	v_mfma_f32_16x16x32_bf16 v[84:87], v[144:147], v[204:207], v[84:87]
	v_mfma_f32_16x16x32_bf16 v[80:83], v[152:155], v[204:207], v[80:83]
	v_mfma_f32_16x16x32_bf16 v[68:71], v[144:147], v[212:215], v[68:71]
	v_mfma_f32_16x16x32_bf16 v[64:67], v[152:155], v[212:215], v[64:67]
	v_mfma_f32_16x16x32_bf16 v[116:119], v[148:151], v[192:195], v[116:119]
	v_mfma_f32_16x16x32_bf16 v[112:115], v[156:159], v[192:195], v[112:115]
	v_mfma_f32_16x16x32_bf16 v[100:103], v[148:151], v[200:203], v[100:103]
	v_mfma_f32_16x16x32_bf16 v[96:99], v[156:159], v[200:203], v[96:99]
	v_mfma_f32_16x16x32_bf16 v[84:87], v[148:151], v[208:211], v[84:87]
	v_mfma_f32_16x16x32_bf16 v[80:83], v[156:159], v[208:211], v[80:83]
	v_mfma_f32_16x16x32_bf16 v[68:71], v[148:151], v[216:219], v[68:71]
	v_mfma_f32_16x16x32_bf16 v[64:67], v[156:159], v[216:219], v[64:67]
	s_barrier
	s_add_i32 s38, s61, s40
	v_lshl_add_u64 v[220:221], v[220:221], 0, s[8:9]
	s_mov_b32 m0, s38
	ds_read_b128 v[178:181], v190 offset:49152
	ds_read_b128 v[192:195], v190 offset:50176
	ds_read_b128 v[196:199], v190 offset:51200
	ds_read_b128 v[200:203], v190 offset:52224
	ds_read_b128 v[204:207], v190 offset:53248
	ds_read_b128 v[208:211], v190 offset:54272
	ds_read_b128 v[212:215], v190 offset:55296
	ds_read_b128 v[216:219], v190 offset:56320
	global_load_lds_dwordx4 v[220:221], off
	s_add_i32 m0, s38, 0x2000
	s_add_u32 s36, s36, 0x100080
	v_lshl_add_u64 v[220:221], v[222:223], 0, s[8:9]
	s_addc_u32 s37, s37, 0
	s_add_i32 s38, s62, s40
	global_load_lds_dwordx4 v[220:221], off
	s_mov_b32 m0, s38
	v_lshl_add_u64 v[220:221], s[36:37], 0, v[164:165]
	global_load_lds_dwordx4 v[220:221], off
	s_add_i32 m0, s38, 0x2000
	v_lshl_add_u64 v[220:221], s[36:37], 0, v[168:169]
	global_load_lds_dwordx4 v[220:221], off
	s_mov_b32 m0, s45
	v_lshl_add_u64 v[220:221], v[224:225], 0, s[8:9]
	global_load_lds_dwordx4 v[220:221], off
	s_mov_b32 m0, s46
	v_lshl_add_u64 v[220:221], v[226:227], 0, s[8:9]
	global_load_lds_dwordx4 v[220:221], off
	s_waitcnt vmcnt(8) lgkmcnt(0)
	s_barrier
	v_mfma_f32_16x16x32_bf16 v[60:63], v[128:131], v[178:181], v[60:63]
	v_mfma_f32_16x16x32_bf16 v[56:59], v[136:139], v[178:181], v[56:59]
	v_mfma_f32_16x16x32_bf16 v[44:47], v[128:131], v[196:199], v[44:47]
	v_mfma_f32_16x16x32_bf16 v[40:43], v[136:139], v[196:199], v[40:43]
	v_mfma_f32_16x16x32_bf16 v[28:31], v[128:131], v[204:207], v[28:31]
	v_mfma_f32_16x16x32_bf16 v[24:27], v[136:139], v[204:207], v[24:27]
	v_mfma_f32_16x16x32_bf16 v[12:15], v[128:131], v[212:215], v[12:15]
	v_mfma_f32_16x16x32_bf16 v[8:11], v[136:139], v[212:215], v[8:11]
	v_mfma_f32_16x16x32_bf16 v[60:63], v[132:135], v[192:195], v[60:63]
	v_mfma_f32_16x16x32_bf16 v[56:59], v[140:143], v[192:195], v[56:59]
	v_mfma_f32_16x16x32_bf16 v[44:47], v[132:135], v[200:203], v[44:47]
	v_mfma_f32_16x16x32_bf16 v[40:43], v[140:143], v[200:203], v[40:43]
	v_mfma_f32_16x16x32_bf16 v[28:31], v[132:135], v[208:211], v[28:31]
	v_mfma_f32_16x16x32_bf16 v[24:27], v[140:143], v[208:211], v[24:27]
	v_mfma_f32_16x16x32_bf16 v[12:15], v[132:135], v[216:219], v[12:15]
	v_mfma_f32_16x16x32_bf16 v[8:11], v[140:143], v[216:219], v[8:11]
	v_mfma_f32_16x16x32_bf16 v[52:55], v[144:147], v[178:181], v[52:55]
	v_mfma_f32_16x16x32_bf16 v[48:51], v[152:155], v[178:181], v[48:51]
	v_mfma_f32_16x16x32_bf16 v[36:39], v[144:147], v[196:199], v[36:39]
	v_mfma_f32_16x16x32_bf16 v[32:35], v[152:155], v[196:199], v[32:35]
	v_mfma_f32_16x16x32_bf16 v[20:23], v[144:147], v[204:207], v[20:23]
	v_mfma_f32_16x16x32_bf16 v[16:19], v[152:155], v[204:207], v[16:19]
	v_mfma_f32_16x16x32_bf16 v[4:7], v[144:147], v[212:215], v[4:7]
	v_mfma_f32_16x16x32_bf16 v[0:3], v[152:155], v[212:215], v[0:3]
	v_mfma_f32_16x16x32_bf16 v[52:55], v[148:151], v[192:195], v[52:55]
	v_mfma_f32_16x16x32_bf16 v[48:51], v[156:159], v[192:195], v[48:51]
	v_mfma_f32_16x16x32_bf16 v[36:39], v[148:151], v[200:203], v[36:39]
	v_mfma_f32_16x16x32_bf16 v[32:35], v[156:159], v[200:203], v[32:35]
	v_mfma_f32_16x16x32_bf16 v[20:23], v[148:151], v[208:211], v[20:23]
	v_mfma_f32_16x16x32_bf16 v[16:19], v[156:159], v[208:211], v[16:19]
	v_mfma_f32_16x16x32_bf16 v[4:7], v[148:151], v[216:219], v[4:7]
	v_mfma_f32_16x16x32_bf16 v[0:3], v[156:159], v[216:219], v[0:3]
	s_barrier
	s_add_i32 s60, s60, 2
	s_add_u32 s0, s0, 0x100
	s_addc_u32 s1, s1, 0
	s_add_u32 s58, s58, 0x100
	s_addc_u32 s59, s59, 0
	s_cmp_gt_u32 s60, 61
	s_cbranch_scc0 .LBB0_711

.LBB0_798:
	s_ashr_i32 s29, s28, 31
	s_lshl_b64 s[30:31], s[28:29], 19
	s_add_u32 s30, s96, s30
	s_addc_u32 s31, s97, s31
	s_and_b64 s[34:35], s[4:5], exec
	s_cselect_b32 s3, s31, s1
	s_cselect_b32 s7, s30, s0
	s_ashr_i32 s27, s26, 31
	s_lshl_b64 s[34:35], s[26:27], 19
	s_add_u32 s34, s58, s34
	s_addc_u32 s35, s59, s35
	s_and_b64 s[36:37], s[4:5], exec
	s_cselect_b32 s27, s35, s9
	s_cselect_b32 s29, s34, s8
	s_add_u32 s0, s0, 0x40080
	s_addc_u32 s1, s1, 0
	s_add_u32 s33, s8, 0x100
	s_addc_u32 s38, s9, 0
	s_mov_b32 s39, -2
	ds_read_b128 v[128:131], v177
	ds_read_b128 v[154:157], v177 offset:1024
	ds_read_b128 v[162:165], v177 offset:2048
	ds_read_b128 v[166:169], v177 offset:3072
	ds_read_b128 v[182:185], v178
	ds_read_b128 v[186:189], v178 offset:1024
	ds_read_b128 v[190:193], v178 offset:2048
	ds_read_b128 v[194:197], v178 offset:3072
	s_add_u32 s8, s0, 0xfffc0080
	s_addc_u32 s9, s1, -1
	s_cmp_eq_u32 s39, 12
	s_cselect_b32 s37, s3, s9
	s_cselect_b32 s36, s7, s8
	s_cselect_b32 s9, s27, s38
	s_cselect_b32 s8, s29, s33
	v_lshl_add_u64 v[158:159], s[0:1], 0, v[146:147]
	s_add_i32 m0, s62, 0xc000
	ds_read_b128 v[198:201], v179
	ds_read_b128 v[202:205], v179 offset:1024
	ds_read_b128 v[206:209], v179 offset:2048
	ds_read_b128 v[210:213], v179 offset:3072
	ds_read_b128 v[214:217], v179 offset:4096
	ds_read_b128 v[218:221], v179 offset:5120
	ds_read_b128 v[222:225], v179 offset:6144
	ds_read_b128 v[226:229], v179 offset:7168
	global_load_lds_dwordx4 v[158:159], off
	s_add_i32 m0, s62, 0xe000
	v_lshl_add_u64 v[158:159], s[0:1], 0, v[148:149]
	global_load_lds_dwordx4 v[158:159], off
	s_waitcnt vmcnt(8) lgkmcnt(0)
	s_barrier
	v_mfma_f32_16x16x32_bf16 v[124:127], v[128:131], v[198:201], 0
	v_mfma_f32_16x16x32_bf16 v[120:123], v[162:165], v[198:201], 0
	v_mfma_f32_16x16x32_bf16 v[108:111], v[128:131], v[206:209], 0
	v_mfma_f32_16x16x32_bf16 v[104:107], v[162:165], v[206:209], 0
	v_mfma_f32_16x16x32_bf16 v[92:95], v[128:131], v[214:217], 0
	v_mfma_f32_16x16x32_bf16 v[88:91], v[162:165], v[214:217], 0
	v_mfma_f32_16x16x32_bf16 v[76:79], v[128:131], v[222:225], 0
	v_mfma_f32_16x16x32_bf16 v[72:75], v[162:165], v[222:225], 0
	v_mfma_f32_16x16x32_bf16 v[124:127], v[154:157], v[202:205], v[124:127]
	v_mfma_f32_16x16x32_bf16 v[120:123], v[166:169], v[202:205], v[120:123]
	v_mfma_f32_16x16x32_bf16 v[108:111], v[154:157], v[210:213], v[108:111]
	v_mfma_f32_16x16x32_bf16 v[104:107], v[166:169], v[210:213], v[104:107]
	v_mfma_f32_16x16x32_bf16 v[92:95], v[154:157], v[218:221], v[92:95]
	v_mfma_f32_16x16x32_bf16 v[88:91], v[166:169], v[218:221], v[88:91]
	v_mfma_f32_16x16x32_bf16 v[76:79], v[154:157], v[226:229], v[76:79]
	v_mfma_f32_16x16x32_bf16 v[72:75], v[166:169], v[226:229], v[72:75]
	v_mfma_f32_16x16x32_bf16 v[116:119], v[182:185], v[198:201], 0
	v_mfma_f32_16x16x32_bf16 v[112:115], v[190:193], v[198:201], 0
	v_mfma_f32_16x16x32_bf16 v[100:103], v[182:185], v[206:209], 0
	v_mfma_f32_16x16x32_bf16 v[96:99], v[190:193], v[206:209], 0
	v_mfma_f32_16x16x32_bf16 v[84:87], v[182:185], v[214:217], 0
	v_mfma_f32_16x16x32_bf16 v[80:83], v[190:193], v[214:217], 0
	v_mfma_f32_16x16x32_bf16 v[68:71], v[182:185], v[222:225], 0
	v_mfma_f32_16x16x32_bf16 v[64:67], v[190:193], v[222:225], 0
	v_mfma_f32_16x16x32_bf16 v[116:119], v[186:189], v[202:205], v[116:119]
	v_mfma_f32_16x16x32_bf16 v[112:115], v[194:197], v[202:205], v[112:115]
	v_mfma_f32_16x16x32_bf16 v[100:103], v[186:189], v[210:213], v[100:103]
	v_mfma_f32_16x16x32_bf16 v[96:99], v[194:197], v[210:213], v[96:99]
	v_mfma_f32_16x16x32_bf16 v[84:87], v[186:189], v[218:221], v[84:87]
	v_mfma_f32_16x16x32_bf16 v[80:83], v[194:197], v[218:221], v[80:83]
	v_mfma_f32_16x16x32_bf16 v[68:71], v[186:189], v[226:229], v[68:71]
	v_mfma_f32_16x16x32_bf16 v[64:67], v[194:197], v[226:229], v[64:67]
	s_barrier
	s_add_i32 s40, s78, s61
	v_lshl_add_u64 v[158:159], s[8:9], 0, v[134:135]
	s_mov_b32 m0, s40
	ds_read_b128 v[198:201], v179 offset:16384
	ds_read_b128 v[202:205], v179 offset:17408
	ds_read_b128 v[206:209], v179 offset:18432
	ds_read_b128 v[210:213], v179 offset:19456
	ds_read_b128 v[214:217], v179 offset:20480
	ds_read_b128 v[218:221], v179 offset:21504
	ds_read_b128 v[222:225], v179 offset:22528
	ds_read_b128 v[226:229], v179 offset:23552
	global_load_lds_dwordx4 v[158:159], off
	s_add_i32 m0, s40, 0x2000
	s_add_u32 s40, s8, 0x40000
	v_lshl_add_u64 v[230:231], s[8:9], 0, v[138:139]
	s_addc_u32 s41, s9, 0
	s_add_i32 s42, s79, s61
	global_load_lds_dwordx4 v[230:231], off
	v_lshl_add_u64 v[232:233], s[40:41], 0, v[134:135]
	s_mov_b32 m0, s42
	v_lshl_add_u64 v[234:235], s[36:37], 0, v[136:137]
	global_load_lds_dwordx4 v[232:233], off
	s_add_i32 m0, s42, 0x2000
	v_lshl_add_u64 v[232:233], s[40:41], 0, v[138:139]
	global_load_lds_dwordx4 v[232:233], off
	s_mov_b32 m0, s62
	v_lshl_add_u64 v[232:233], s[36:37], 0, v[132:133]
	global_load_lds_dwordx4 v[232:233], off
	s_mov_b32 m0, s63
	s_nop 0
	global_load_lds_dwordx4 v[234:235], off
	s_waitcnt vmcnt(8) lgkmcnt(0)
	s_barrier
	v_mfma_f32_16x16x32_bf16 v[60:63], v[128:131], v[198:201], 0
	v_mfma_f32_16x16x32_bf16 v[56:59], v[162:165], v[198:201], 0
	v_mfma_f32_16x16x32_bf16 v[44:47], v[128:131], v[206:209], 0
	v_mfma_f32_16x16x32_bf16 v[40:43], v[162:165], v[206:209], 0
	v_mfma_f32_16x16x32_bf16 v[28:31], v[128:131], v[214:217], 0
	v_mfma_f32_16x16x32_bf16 v[24:27], v[162:165], v[214:217], 0
	v_mfma_f32_16x16x32_bf16 v[12:15], v[128:131], v[222:225], 0
	v_mfma_f32_16x16x32_bf16 v[8:11], v[162:165], v[222:225], 0
	v_mfma_f32_16x16x32_bf16 v[60:63], v[154:157], v[202:205], v[60:63]
	v_mfma_f32_16x16x32_bf16 v[56:59], v[166:169], v[202:205], v[56:59]
	v_mfma_f32_16x16x32_bf16 v[44:47], v[154:157], v[210:213], v[44:47]
	v_mfma_f32_16x16x32_bf16 v[40:43], v[166:169], v[210:213], v[40:43]
	v_mfma_f32_16x16x32_bf16 v[28:31], v[154:157], v[218:221], v[28:31]
	v_mfma_f32_16x16x32_bf16 v[24:27], v[166:169], v[218:221], v[24:27]
	v_mfma_f32_16x16x32_bf16 v[12:15], v[154:157], v[226:229], v[12:15]
	v_mfma_f32_16x16x32_bf16 v[8:11], v[166:169], v[226:229], v[8:11]
	v_mfma_f32_16x16x32_bf16 v[52:55], v[182:185], v[198:201], 0
	v_mfma_f32_16x16x32_bf16 v[48:51], v[190:193], v[198:201], 0
	v_mfma_f32_16x16x32_bf16 v[36:39], v[182:185], v[206:209], 0
	v_mfma_f32_16x16x32_bf16 v[32:35], v[190:193], v[206:209], 0
	v_mfma_f32_16x16x32_bf16 v[20:23], v[182:185], v[214:217], 0
	v_mfma_f32_16x16x32_bf16 v[16:19], v[190:193], v[214:217], 0
	v_mfma_f32_16x16x32_bf16 v[4:7], v[182:185], v[222:225], 0
	v_mfma_f32_16x16x32_bf16 v[0:3], v[190:193], v[222:225], 0
	v_mfma_f32_16x16x32_bf16 v[52:55], v[186:189], v[202:205], v[52:55]
	v_mfma_f32_16x16x32_bf16 v[48:51], v[194:197], v[202:205], v[48:51]
	v_mfma_f32_16x16x32_bf16 v[36:39], v[186:189], v[210:213], v[36:39]
	v_mfma_f32_16x16x32_bf16 v[32:35], v[194:197], v[210:213], v[32:35]
	v_mfma_f32_16x16x32_bf16 v[20:23], v[186:189], v[218:221], v[20:23]
	v_mfma_f32_16x16x32_bf16 v[16:19], v[194:197], v[218:221], v[16:19]
	v_mfma_f32_16x16x32_bf16 v[4:7], v[186:189], v[226:229], v[4:7]
	v_mfma_f32_16x16x32_bf16 v[0:3], v[194:197], v[226:229], v[0:3]
	s_barrier
	s_add_i32 s40, 0, 0x18000
	v_add_u32_e32 v140, s40, v171
	s_add_i32 s41, 0, 0x1c000
	ds_read_b128 v[128:131], v140
	ds_read_b128 v[154:157], v140 offset:1024
	ds_read_b128 v[162:165], v140 offset:2048
	ds_read_b128 v[166:169], v140 offset:3072
	v_add_u32_e32 v140, s41, v171
	ds_read_b128 v[182:185], v140
	ds_read_b128 v[186:189], v140 offset:1024
	ds_read_b128 v[190:193], v140 offset:2048
	ds_read_b128 v[194:197], v140 offset:3072
	s_add_u32 s36, s36, 0x40000
	s_addc_u32 s37, s37, 0
	s_mov_b32 m0, s64
	v_lshl_add_u64 v[236:237], s[36:37], 0, v[132:133]
	ds_read_b128 v[198:201], v179 offset:32768
	ds_read_b128 v[202:205], v179 offset:33792
	ds_read_b128 v[206:209], v179 offset:34816
	ds_read_b128 v[210:213], v179 offset:35840
	ds_read_b128 v[214:217], v179 offset:36864
	ds_read_b128 v[218:221], v179 offset:37888
	ds_read_b128 v[222:225], v179 offset:38912
	ds_read_b128 v[226:229], v179 offset:39936
	global_load_lds_dwordx4 v[236:237], off
	s_mov_b32 m0, s65
	v_lshl_add_u64 v[236:237], s[36:37], 0, v[136:137]
	global_load_lds_dwordx4 v[236:237], off
	s_waitcnt vmcnt(8) lgkmcnt(0)
	s_barrier
	v_mfma_f32_16x16x32_bf16 v[124:127], v[128:131], v[198:201], v[124:127]
	v_mfma_f32_16x16x32_bf16 v[120:123], v[162:165], v[198:201], v[120:123]
	v_mfma_f32_16x16x32_bf16 v[108:111], v[128:131], v[206:209], v[108:111]
	v_mfma_f32_16x16x32_bf16 v[104:107], v[162:165], v[206:209], v[104:107]
	v_mfma_f32_16x16x32_bf16 v[92:95], v[128:131], v[214:217], v[92:95]
	v_mfma_f32_16x16x32_bf16 v[88:91], v[162:165], v[214:217], v[88:91]
	v_mfma_f32_16x16x32_bf16 v[76:79], v[128:131], v[222:225], v[76:79]
	v_mfma_f32_16x16x32_bf16 v[72:75], v[162:165], v[222:225], v[72:75]
	v_mfma_f32_16x16x32_bf16 v[124:127], v[154:157], v[202:205], v[124:127]
	v_mfma_f32_16x16x32_bf16 v[120:123], v[166:169], v[202:205], v[120:123]
	v_mfma_f32_16x16x32_bf16 v[108:111], v[154:157], v[210:213], v[108:111]
	v_mfma_f32_16x16x32_bf16 v[104:107], v[166:169], v[210:213], v[104:107]
	v_mfma_f32_16x16x32_bf16 v[92:95], v[154:157], v[218:221], v[92:95]
	v_mfma_f32_16x16x32_bf16 v[88:91], v[166:169], v[218:221], v[88:91]
	v_mfma_f32_16x16x32_bf16 v[76:79], v[154:157], v[226:229], v[76:79]
	v_mfma_f32_16x16x32_bf16 v[72:75], v[166:169], v[226:229], v[72:75]
	v_mfma_f32_16x16x32_bf16 v[116:119], v[182:185], v[198:201], v[116:119]
	v_mfma_f32_16x16x32_bf16 v[112:115], v[190:193], v[198:201], v[112:115]
	v_mfma_f32_16x16x32_bf16 v[100:103], v[182:185], v[206:209], v[100:103]
	v_mfma_f32_16x16x32_bf16 v[96:99], v[190:193], v[206:209], v[96:99]
	v_mfma_f32_16x16x32_bf16 v[84:87], v[182:185], v[214:217], v[84:87]
	v_mfma_f32_16x16x32_bf16 v[80:83], v[190:193], v[214:217], v[80:83]
	v_mfma_f32_16x16x32_bf16 v[68:71], v[182:185], v[222:225], v[68:71]
	v_mfma_f32_16x16x32_bf16 v[64:67], v[190:193], v[222:225], v[64:67]
	v_mfma_f32_16x16x32_bf16 v[116:119], v[186:189], v[202:205], v[116:119]
	v_mfma_f32_16x16x32_bf16 v[112:115], v[194:197], v[202:205], v[112:115]
	v_mfma_f32_16x16x32_bf16 v[100:103], v[186:189], v[210:213], v[100:103]
	v_mfma_f32_16x16x32_bf16 v[96:99], v[194:197], v[210:213], v[96:99]
	v_mfma_f32_16x16x32_bf16 v[84:87], v[186:189], v[218:221], v[84:87]
	v_mfma_f32_16x16x32_bf16 v[80:83], v[194:197], v[218:221], v[80:83]
	v_mfma_f32_16x16x32_bf16 v[68:71], v[186:189], v[226:229], v[68:71]
	v_mfma_f32_16x16x32_bf16 v[64:67], v[194:197], v[226:229], v[64:67]
	s_barrier
	s_add_i32 s36, s40, s61
	v_lshl_add_u64 v[158:159], v[158:159], 0, s[14:15]
	s_mov_b32 m0, s36
	ds_read_b128 v[198:201], v179 offset:49152
	ds_read_b128 v[202:205], v179 offset:50176
	ds_read_b128 v[206:209], v179 offset:51200
	ds_read_b128 v[210:213], v179 offset:52224
	ds_read_b128 v[214:217], v179 offset:53248
	ds_read_b128 v[218:221], v179 offset:54272
	ds_read_b128 v[222:225], v179 offset:55296
	ds_read_b128 v[226:229], v179 offset:56320
	global_load_lds_dwordx4 v[158:159], off
	s_add_i32 m0, s36, 0x2000
	s_add_u32 s8, s8, 0x40080
	v_lshl_add_u64 v[158:159], v[230:231], 0, s[14:15]
	s_addc_u32 s9, s9, 0
	s_add_i32 s36, s41, s61
	global_load_lds_dwordx4 v[158:159], off
	s_mov_b32 m0, s36
	v_lshl_add_u64 v[158:159], s[8:9], 0, v[134:135]
	global_load_lds_dwordx4 v[158:159], off
	s_add_i32 m0, s36, 0x2000
	v_lshl_add_u64 v[158:159], s[8:9], 0, v[138:139]
	global_load_lds_dwordx4 v[158:159], off
	s_mov_b32 m0, s76
	v_lshl_add_u64 v[158:159], v[232:233], 0, s[14:15]
	global_load_lds_dwordx4 v[158:159], off
	s_mov_b32 m0, s77
	v_lshl_add_u64 v[158:159], v[234:235], 0, s[14:15]
	global_load_lds_dwordx4 v[158:159], off
	s_waitcnt vmcnt(8) lgkmcnt(0)
	s_barrier
	v_mfma_f32_16x16x32_bf16 v[60:63], v[128:131], v[198:201], v[60:63]
	v_mfma_f32_16x16x32_bf16 v[56:59], v[162:165], v[198:201], v[56:59]
	v_mfma_f32_16x16x32_bf16 v[44:47], v[128:131], v[206:209], v[44:47]
	v_mfma_f32_16x16x32_bf16 v[40:43], v[162:165], v[206:209], v[40:43]
	v_mfma_f32_16x16x32_bf16 v[28:31], v[128:131], v[214:217], v[28:31]
	v_mfma_f32_16x16x32_bf16 v[24:27], v[162:165], v[214:217], v[24:27]
	v_mfma_f32_16x16x32_bf16 v[12:15], v[128:131], v[222:225], v[12:15]
	v_mfma_f32_16x16x32_bf16 v[8:11], v[162:165], v[222:225], v[8:11]
	v_mfma_f32_16x16x32_bf16 v[60:63], v[154:157], v[202:205], v[60:63]
	v_mfma_f32_16x16x32_bf16 v[56:59], v[166:169], v[202:205], v[56:59]
	v_mfma_f32_16x16x32_bf16 v[44:47], v[154:157], v[210:213], v[44:47]
	v_mfma_f32_16x16x32_bf16 v[40:43], v[166:169], v[210:213], v[40:43]
	v_mfma_f32_16x16x32_bf16 v[28:31], v[154:157], v[218:221], v[28:31]
	v_mfma_f32_16x16x32_bf16 v[24:27], v[166:169], v[218:221], v[24:27]
	v_mfma_f32_16x16x32_bf16 v[12:15], v[154:157], v[226:229], v[12:15]
	v_mfma_f32_16x16x32_bf16 v[8:11], v[166:169], v[226:229], v[8:11]
	v_mfma_f32_16x16x32_bf16 v[52:55], v[182:185], v[198:201], v[52:55]
	v_mfma_f32_16x16x32_bf16 v[48:51], v[190:193], v[198:201], v[48:51]
	v_mfma_f32_16x16x32_bf16 v[36:39], v[182:185], v[206:209], v[36:39]
	v_mfma_f32_16x16x32_bf16 v[32:35], v[190:193], v[206:209], v[32:35]
	v_mfma_f32_16x16x32_bf16 v[20:23], v[182:185], v[214:217], v[20:23]
	v_mfma_f32_16x16x32_bf16 v[16:19], v[190:193], v[214:217], v[16:19]
	v_mfma_f32_16x16x32_bf16 v[4:7], v[182:185], v[222:225], v[4:7]
	v_mfma_f32_16x16x32_bf16 v[0:3], v[190:193], v[222:225], v[0:3]
	v_mfma_f32_16x16x32_bf16 v[52:55], v[186:189], v[202:205], v[52:55]
	v_mfma_f32_16x16x32_bf16 v[48:51], v[194:197], v[202:205], v[48:51]
	v_mfma_f32_16x16x32_bf16 v[36:39], v[186:189], v[210:213], v[36:39]
	v_mfma_f32_16x16x32_bf16 v[32:35], v[194:197], v[210:213], v[32:35]
	v_mfma_f32_16x16x32_bf16 v[20:23], v[186:189], v[218:221], v[20:23]
	v_mfma_f32_16x16x32_bf16 v[16:19], v[194:197], v[218:221], v[16:19]
	v_mfma_f32_16x16x32_bf16 v[4:7], v[186:189], v[226:229], v[4:7]
	v_mfma_f32_16x16x32_bf16 v[0:3], v[194:197], v[226:229], v[0:3]
	s_barrier
	s_add_i32 s39, s39, 2
	s_add_u32 s0, s0, 0x100
	s_addc_u32 s1, s1, 0
	s_add_u32 s33, s33, 0x100
	s_addc_u32 s38, s38, 0
	s_cmp_gt_u32 s39, 13
	s_cbranch_scc0 .LBB0_799
	s_branch .Lpeel_exit_5
.LBB0_799:
	ds_read_b128 v[128:131], v177
	ds_read_b128 v[154:157], v177 offset:1024
	ds_read_b128 v[162:165], v177 offset:2048
	ds_read_b128 v[166:169], v177 offset:3072
	ds_read_b128 v[182:185], v178
	ds_read_b128 v[186:189], v178 offset:1024
	ds_read_b128 v[190:193], v178 offset:2048
	ds_read_b128 v[194:197], v178 offset:3072
	s_add_u32 s8, s0, 0xfffc0080
	s_addc_u32 s9, s1, -1
	s_cmp_eq_u32 s39, 12
	s_cselect_b32 s37, s3, s9
	s_cselect_b32 s36, s7, s8
	s_cselect_b32 s9, s27, s38
	s_cselect_b32 s8, s29, s33
	v_lshl_add_u64 v[158:159], s[0:1], 0, v[146:147]
	s_add_i32 m0, s62, 0xc000
	ds_read_b128 v[198:201], v179
	ds_read_b128 v[202:205], v179 offset:1024
	ds_read_b128 v[206:209], v179 offset:2048
	ds_read_b128 v[210:213], v179 offset:3072
	ds_read_b128 v[214:217], v179 offset:4096
	ds_read_b128 v[218:221], v179 offset:5120
	ds_read_b128 v[222:225], v179 offset:6144
	ds_read_b128 v[226:229], v179 offset:7168
	global_load_lds_dwordx4 v[158:159], off
	s_add_i32 m0, s62, 0xe000
	v_lshl_add_u64 v[158:159], s[0:1], 0, v[148:149]
	global_load_lds_dwordx4 v[158:159], off
	s_waitcnt vmcnt(8) lgkmcnt(0)
	s_barrier
	v_mfma_f32_16x16x32_bf16 v[124:127], v[128:131], v[198:201], v[124:127]
	v_mfma_f32_16x16x32_bf16 v[120:123], v[162:165], v[198:201], v[120:123]
	v_mfma_f32_16x16x32_bf16 v[108:111], v[128:131], v[206:209], v[108:111]
	v_mfma_f32_16x16x32_bf16 v[104:107], v[162:165], v[206:209], v[104:107]
	v_mfma_f32_16x16x32_bf16 v[92:95], v[128:131], v[214:217], v[92:95]
	v_mfma_f32_16x16x32_bf16 v[88:91], v[162:165], v[214:217], v[88:91]
	v_mfma_f32_16x16x32_bf16 v[76:79], v[128:131], v[222:225], v[76:79]
	v_mfma_f32_16x16x32_bf16 v[72:75], v[162:165], v[222:225], v[72:75]
	v_mfma_f32_16x16x32_bf16 v[124:127], v[154:157], v[202:205], v[124:127]
	v_mfma_f32_16x16x32_bf16 v[120:123], v[166:169], v[202:205], v[120:123]
	v_mfma_f32_16x16x32_bf16 v[108:111], v[154:157], v[210:213], v[108:111]
	v_mfma_f32_16x16x32_bf16 v[104:107], v[166:169], v[210:213], v[104:107]
	v_mfma_f32_16x16x32_bf16 v[92:95], v[154:157], v[218:221], v[92:95]
	v_mfma_f32_16x16x32_bf16 v[88:91], v[166:169], v[218:221], v[88:91]
	v_mfma_f32_16x16x32_bf16 v[76:79], v[154:157], v[226:229], v[76:79]
	v_mfma_f32_16x16x32_bf16 v[72:75], v[166:169], v[226:229], v[72:75]
	v_mfma_f32_16x16x32_bf16 v[116:119], v[182:185], v[198:201], v[116:119]
	v_mfma_f32_16x16x32_bf16 v[112:115], v[190:193], v[198:201], v[112:115]
	v_mfma_f32_16x16x32_bf16 v[100:103], v[182:185], v[206:209], v[100:103]
	v_mfma_f32_16x16x32_bf16 v[96:99], v[190:193], v[206:209], v[96:99]
	v_mfma_f32_16x16x32_bf16 v[84:87], v[182:185], v[214:217], v[84:87]
	v_mfma_f32_16x16x32_bf16 v[80:83], v[190:193], v[214:217], v[80:83]
	v_mfma_f32_16x16x32_bf16 v[68:71], v[182:185], v[222:225], v[68:71]
	v_mfma_f32_16x16x32_bf16 v[64:67], v[190:193], v[222:225], v[64:67]
	v_mfma_f32_16x16x32_bf16 v[116:119], v[186:189], v[202:205], v[116:119]
	v_mfma_f32_16x16x32_bf16 v[112:115], v[194:197], v[202:205], v[112:115]
	v_mfma_f32_16x16x32_bf16 v[100:103], v[186:189], v[210:213], v[100:103]
	v_mfma_f32_16x16x32_bf16 v[96:99], v[194:197], v[210:213], v[96:99]
	v_mfma_f32_16x16x32_bf16 v[84:87], v[186:189], v[218:221], v[84:87]
	v_mfma_f32_16x16x32_bf16 v[80:83], v[194:197], v[218:221], v[80:83]
	v_mfma_f32_16x16x32_bf16 v[68:71], v[186:189], v[226:229], v[68:71]
	v_mfma_f32_16x16x32_bf16 v[64:67], v[194:197], v[226:229], v[64:67]
	s_barrier
	s_add_i32 s40, s78, s61
	v_lshl_add_u64 v[158:159], s[8:9], 0, v[134:135]
	s_mov_b32 m0, s40
	ds_read_b128 v[198:201], v179 offset:16384
	ds_read_b128 v[202:205], v179 offset:17408
	ds_read_b128 v[206:209], v179 offset:18432
	ds_read_b128 v[210:213], v179 offset:19456
	ds_read_b128 v[214:217], v179 offset:20480
	ds_read_b128 v[218:221], v179 offset:21504
	ds_read_b128 v[222:225], v179 offset:22528
	ds_read_b128 v[226:229], v179 offset:23552
	global_load_lds_dwordx4 v[158:159], off
	s_add_i32 m0, s40, 0x2000
	s_add_u32 s40, s8, 0x40000
	v_lshl_add_u64 v[230:231], s[8:9], 0, v[138:139]
	s_addc_u32 s41, s9, 0
	s_add_i32 s42, s79, s61
	global_load_lds_dwordx4 v[230:231], off
	v_lshl_add_u64 v[232:233], s[40:41], 0, v[134:135]
	s_mov_b32 m0, s42
	v_lshl_add_u64 v[234:235], s[36:37], 0, v[136:137]
	global_load_lds_dwordx4 v[232:233], off
	s_add_i32 m0, s42, 0x2000
	v_lshl_add_u64 v[232:233], s[40:41], 0, v[138:139]
	global_load_lds_dwordx4 v[232:233], off
	s_mov_b32 m0, s62
	v_lshl_add_u64 v[232:233], s[36:37], 0, v[132:133]
	global_load_lds_dwordx4 v[232:233], off
	s_mov_b32 m0, s63
	s_nop 0
	global_load_lds_dwordx4 v[234:235], off
	s_waitcnt vmcnt(8) lgkmcnt(0)
	s_barrier
	v_mfma_f32_16x16x32_bf16 v[60:63], v[128:131], v[198:201], v[60:63]
	v_mfma_f32_16x16x32_bf16 v[56:59], v[162:165], v[198:201], v[56:59]
	v_mfma_f32_16x16x32_bf16 v[44:47], v[128:131], v[206:209], v[44:47]
	v_mfma_f32_16x16x32_bf16 v[40:43], v[162:165], v[206:209], v[40:43]
	v_mfma_f32_16x16x32_bf16 v[28:31], v[128:131], v[214:217], v[28:31]
	v_mfma_f32_16x16x32_bf16 v[24:27], v[162:165], v[214:217], v[24:27]
	v_mfma_f32_16x16x32_bf16 v[12:15], v[128:131], v[222:225], v[12:15]
	v_mfma_f32_16x16x32_bf16 v[8:11], v[162:165], v[222:225], v[8:11]
	v_mfma_f32_16x16x32_bf16 v[60:63], v[154:157], v[202:205], v[60:63]
	v_mfma_f32_16x16x32_bf16 v[56:59], v[166:169], v[202:205], v[56:59]
	v_mfma_f32_16x16x32_bf16 v[44:47], v[154:157], v[210:213], v[44:47]
	v_mfma_f32_16x16x32_bf16 v[40:43], v[166:169], v[210:213], v[40:43]
	v_mfma_f32_16x16x32_bf16 v[28:31], v[154:157], v[218:221], v[28:31]
	v_mfma_f32_16x16x32_bf16 v[24:27], v[166:169], v[218:221], v[24:27]
	v_mfma_f32_16x16x32_bf16 v[12:15], v[154:157], v[226:229], v[12:15]
	v_mfma_f32_16x16x32_bf16 v[8:11], v[166:169], v[226:229], v[8:11]
	v_mfma_f32_16x16x32_bf16 v[52:55], v[182:185], v[198:201], v[52:55]
	v_mfma_f32_16x16x32_bf16 v[48:51], v[190:193], v[198:201], v[48:51]
	v_mfma_f32_16x16x32_bf16 v[36:39], v[182:185], v[206:209], v[36:39]
	v_mfma_f32_16x16x32_bf16 v[32:35], v[190:193], v[206:209], v[32:35]
	v_mfma_f32_16x16x32_bf16 v[20:23], v[182:185], v[214:217], v[20:23]
	v_mfma_f32_16x16x32_bf16 v[16:19], v[190:193], v[214:217], v[16:19]
	v_mfma_f32_16x16x32_bf16 v[4:7], v[182:185], v[222:225], v[4:7]
	v_mfma_f32_16x16x32_bf16 v[0:3], v[190:193], v[222:225], v[0:3]
	v_mfma_f32_16x16x32_bf16 v[52:55], v[186:189], v[202:205], v[52:55]
	v_mfma_f32_16x16x32_bf16 v[48:51], v[194:197], v[202:205], v[48:51]
	v_mfma_f32_16x16x32_bf16 v[36:39], v[186:189], v[210:213], v[36:39]
	v_mfma_f32_16x16x32_bf16 v[32:35], v[194:197], v[210:213], v[32:35]
	v_mfma_f32_16x16x32_bf16 v[20:23], v[186:189], v[218:221], v[20:23]
	v_mfma_f32_16x16x32_bf16 v[16:19], v[194:197], v[218:221], v[16:19]
	v_mfma_f32_16x16x32_bf16 v[4:7], v[186:189], v[226:229], v[4:7]
	v_mfma_f32_16x16x32_bf16 v[0:3], v[194:197], v[226:229], v[0:3]
	s_barrier
	s_add_i32 s40, 0, 0x18000
	v_add_u32_e32 v140, s40, v171
	s_add_i32 s41, 0, 0x1c000
	ds_read_b128 v[128:131], v140
	ds_read_b128 v[154:157], v140 offset:1024
	ds_read_b128 v[162:165], v140 offset:2048
	ds_read_b128 v[166:169], v140 offset:3072
	v_add_u32_e32 v140, s41, v171
	ds_read_b128 v[182:185], v140
	ds_read_b128 v[186:189], v140 offset:1024
	ds_read_b128 v[190:193], v140 offset:2048
	ds_read_b128 v[194:197], v140 offset:3072
	s_add_u32 s36, s36, 0x40000
	s_addc_u32 s37, s37, 0
	s_mov_b32 m0, s64
	v_lshl_add_u64 v[236:237], s[36:37], 0, v[132:133]
	ds_read_b128 v[198:201], v179 offset:32768
	ds_read_b128 v[202:205], v179 offset:33792
	ds_read_b128 v[206:209], v179 offset:34816
	ds_read_b128 v[210:213], v179 offset:35840
	ds_read_b128 v[214:217], v179 offset:36864
	ds_read_b128 v[218:221], v179 offset:37888
	ds_read_b128 v[222:225], v179 offset:38912
	ds_read_b128 v[226:229], v179 offset:39936
	global_load_lds_dwordx4 v[236:237], off
	s_mov_b32 m0, s65
	v_lshl_add_u64 v[236:237], s[36:37], 0, v[136:137]
	global_load_lds_dwordx4 v[236:237], off
	s_waitcnt vmcnt(8) lgkmcnt(0)
	s_barrier
	v_mfma_f32_16x16x32_bf16 v[124:127], v[128:131], v[198:201], v[124:127]
	v_mfma_f32_16x16x32_bf16 v[120:123], v[162:165], v[198:201], v[120:123]
	v_mfma_f32_16x16x32_bf16 v[108:111], v[128:131], v[206:209], v[108:111]
	v_mfma_f32_16x16x32_bf16 v[104:107], v[162:165], v[206:209], v[104:107]
	v_mfma_f32_16x16x32_bf16 v[92:95], v[128:131], v[214:217], v[92:95]
	v_mfma_f32_16x16x32_bf16 v[88:91], v[162:165], v[214:217], v[88:91]
	v_mfma_f32_16x16x32_bf16 v[76:79], v[128:131], v[222:225], v[76:79]
	v_mfma_f32_16x16x32_bf16 v[72:75], v[162:165], v[222:225], v[72:75]
	v_mfma_f32_16x16x32_bf16 v[124:127], v[154:157], v[202:205], v[124:127]
	v_mfma_f32_16x16x32_bf16 v[120:123], v[166:169], v[202:205], v[120:123]
	v_mfma_f32_16x16x32_bf16 v[108:111], v[154:157], v[210:213], v[108:111]
	v_mfma_f32_16x16x32_bf16 v[104:107], v[166:169], v[210:213], v[104:107]
	v_mfma_f32_16x16x32_bf16 v[92:95], v[154:157], v[218:221], v[92:95]
	v_mfma_f32_16x16x32_bf16 v[88:91], v[166:169], v[218:221], v[88:91]
	v_mfma_f32_16x16x32_bf16 v[76:79], v[154:157], v[226:229], v[76:79]
	v_mfma_f32_16x16x32_bf16 v[72:75], v[166:169], v[226:229], v[72:75]
	v_mfma_f32_16x16x32_bf16 v[116:119], v[182:185], v[198:201], v[116:119]
	v_mfma_f32_16x16x32_bf16 v[112:115], v[190:193], v[198:201], v[112:115]
	v_mfma_f32_16x16x32_bf16 v[100:103], v[182:185], v[206:209], v[100:103]
	v_mfma_f32_16x16x32_bf16 v[96:99], v[190:193], v[206:209], v[96:99]
	v_mfma_f32_16x16x32_bf16 v[84:87], v[182:185], v[214:217], v[84:87]
	v_mfma_f32_16x16x32_bf16 v[80:83], v[190:193], v[214:217], v[80:83]
	v_mfma_f32_16x16x32_bf16 v[68:71], v[182:185], v[222:225], v[68:71]
	v_mfma_f32_16x16x32_bf16 v[64:67], v[190:193], v[222:225], v[64:67]
	v_mfma_f32_16x16x32_bf16 v[116:119], v[186:189], v[202:205], v[116:119]
	v_mfma_f32_16x16x32_bf16 v[112:115], v[194:197], v[202:205], v[112:115]
	v_mfma_f32_16x16x32_bf16 v[100:103], v[186:189], v[210:213], v[100:103]
	v_mfma_f32_16x16x32_bf16 v[96:99], v[194:197], v[210:213], v[96:99]
	v_mfma_f32_16x16x32_bf16 v[84:87], v[186:189], v[218:221], v[84:87]
	v_mfma_f32_16x16x32_bf16 v[80:83], v[194:197], v[218:221], v[80:83]
	v_mfma_f32_16x16x32_bf16 v[68:71], v[186:189], v[226:229], v[68:71]
	v_mfma_f32_16x16x32_bf16 v[64:67], v[194:197], v[226:229], v[64:67]
	s_barrier
	s_add_i32 s36, s40, s61
	v_lshl_add_u64 v[158:159], v[158:159], 0, s[14:15]
	s_mov_b32 m0, s36
	ds_read_b128 v[198:201], v179 offset:49152
	ds_read_b128 v[202:205], v179 offset:50176
	ds_read_b128 v[206:209], v179 offset:51200
	ds_read_b128 v[210:213], v179 offset:52224
	ds_read_b128 v[214:217], v179 offset:53248
	ds_read_b128 v[218:221], v179 offset:54272
	ds_read_b128 v[222:225], v179 offset:55296
	ds_read_b128 v[226:229], v179 offset:56320
	global_load_lds_dwordx4 v[158:159], off
	s_add_i32 m0, s36, 0x2000
	s_add_u32 s8, s8, 0x40080
	v_lshl_add_u64 v[158:159], v[230:231], 0, s[14:15]
	s_addc_u32 s9, s9, 0
	s_add_i32 s36, s41, s61
	global_load_lds_dwordx4 v[158:159], off
	s_mov_b32 m0, s36
	v_lshl_add_u64 v[158:159], s[8:9], 0, v[134:135]
	global_load_lds_dwordx4 v[158:159], off
	s_add_i32 m0, s36, 0x2000
	v_lshl_add_u64 v[158:159], s[8:9], 0, v[138:139]
	global_load_lds_dwordx4 v[158:159], off
	s_mov_b32 m0, s76
	v_lshl_add_u64 v[158:159], v[232:233], 0, s[14:15]
	global_load_lds_dwordx4 v[158:159], off
	s_mov_b32 m0, s77
	v_lshl_add_u64 v[158:159], v[234:235], 0, s[14:15]
	global_load_lds_dwordx4 v[158:159], off
	s_waitcnt vmcnt(8) lgkmcnt(0)
	s_barrier
	v_mfma_f32_16x16x32_bf16 v[60:63], v[128:131], v[198:201], v[60:63]
	v_mfma_f32_16x16x32_bf16 v[56:59], v[162:165], v[198:201], v[56:59]
	v_mfma_f32_16x16x32_bf16 v[44:47], v[128:131], v[206:209], v[44:47]
	v_mfma_f32_16x16x32_bf16 v[40:43], v[162:165], v[206:209], v[40:43]
	v_mfma_f32_16x16x32_bf16 v[28:31], v[128:131], v[214:217], v[28:31]
	v_mfma_f32_16x16x32_bf16 v[24:27], v[162:165], v[214:217], v[24:27]
	v_mfma_f32_16x16x32_bf16 v[12:15], v[128:131], v[222:225], v[12:15]
	v_mfma_f32_16x16x32_bf16 v[8:11], v[162:165], v[222:225], v[8:11]
	v_mfma_f32_16x16x32_bf16 v[60:63], v[154:157], v[202:205], v[60:63]
	v_mfma_f32_16x16x32_bf16 v[56:59], v[166:169], v[202:205], v[56:59]
	v_mfma_f32_16x16x32_bf16 v[44:47], v[154:157], v[210:213], v[44:47]
	v_mfma_f32_16x16x32_bf16 v[40:43], v[166:169], v[210:213], v[40:43]
	v_mfma_f32_16x16x32_bf16 v[28:31], v[154:157], v[218:221], v[28:31]
	v_mfma_f32_16x16x32_bf16 v[24:27], v[166:169], v[218:221], v[24:27]
	v_mfma_f32_16x16x32_bf16 v[12:15], v[154:157], v[226:229], v[12:15]
	v_mfma_f32_16x16x32_bf16 v[8:11], v[166:169], v[226:229], v[8:11]
	v_mfma_f32_16x16x32_bf16 v[52:55], v[182:185], v[198:201], v[52:55]
	v_mfma_f32_16x16x32_bf16 v[48:51], v[190:193], v[198:201], v[48:51]
	v_mfma_f32_16x16x32_bf16 v[36:39], v[182:185], v[206:209], v[36:39]
	v_mfma_f32_16x16x32_bf16 v[32:35], v[190:193], v[206:209], v[32:35]
	v_mfma_f32_16x16x32_bf16 v[20:23], v[182:185], v[214:217], v[20:23]
	v_mfma_f32_16x16x32_bf16 v[16:19], v[190:193], v[214:217], v[16:19]
	v_mfma_f32_16x16x32_bf16 v[4:7], v[182:185], v[222:225], v[4:7]
	v_mfma_f32_16x16x32_bf16 v[0:3], v[190:193], v[222:225], v[0:3]
	v_mfma_f32_16x16x32_bf16 v[52:55], v[186:189], v[202:205], v[52:55]
	v_mfma_f32_16x16x32_bf16 v[48:51], v[194:197], v[202:205], v[48:51]
	v_mfma_f32_16x16x32_bf16 v[36:39], v[186:189], v[210:213], v[36:39]
	v_mfma_f32_16x16x32_bf16 v[32:35], v[194:197], v[210:213], v[32:35]
	v_mfma_f32_16x16x32_bf16 v[20:23], v[186:189], v[218:221], v[20:23]
	v_mfma_f32_16x16x32_bf16 v[16:19], v[194:197], v[218:221], v[16:19]
	v_mfma_f32_16x16x32_bf16 v[4:7], v[186:189], v[226:229], v[4:7]
	v_mfma_f32_16x16x32_bf16 v[0:3], v[194:197], v[226:229], v[0:3]
	s_barrier
	s_add_i32 s39, s39, 2
	s_add_u32 s0, s0, 0x100
	s_addc_u32 s1, s1, 0
	s_add_u32 s33, s33, 0x100
	s_addc_u32 s38, s38, 0
	s_cmp_gt_u32 s39, 13
	s_cbranch_scc0 .LBB0_799

.LBB0_1402:
	s_ashr_i32 s17, s16, 31
	s_lshl_b64 s[18:19], s[16:17], 19
	s_add_u32 s18, s76, s18
	s_addc_u32 s19, s78, s19
	s_and_b64 s[20:21], s[6:7], exec
	s_cselect_b32 s17, s19, s1
	s_cselect_b32 s33, s18, s0
	s_ashr_i32 s15, s14, 31
	s_lshl_b64 s[20:21], s[14:15], 19
	s_add_u32 s20, s31, s20
	s_addc_u32 s21, s34, s21
	s_and_b64 s[28:29], s[6:7], exec
	s_cselect_b32 s15, s21, s27
	s_cselect_b32 s50, s20, s26
	s_add_u32 s0, s0, 0x40080
	s_addc_u32 s1, s1, 0
	s_add_u32 s51, s26, 0x100
	s_addc_u32 s52, s27, 0
	s_mov_b32 s53, -2
	s_waitcnt lgkmcnt(0)
	ds_read_b128 v[128:131], v193
	ds_read_b128 v[132:135], v193 offset:1024
	ds_read_b128 v[136:139], v193 offset:2048
	ds_read_b128 v[140:143], v193 offset:3072
	ds_read_b128 v[144:147], v194
	ds_read_b128 v[148:151], v194 offset:1024
	ds_read_b128 v[152:155], v194 offset:2048
	ds_read_b128 v[156:159], v194 offset:3072
	s_add_u32 s26, s0, 0xfffc0080
	s_addc_u32 s27, s1, -1
	s_cmp_eq_u32 s53, 12
	s_cselect_b32 s29, s17, s27
	s_cselect_b32 s28, s33, s26
	s_cselect_b32 s27, s15, s52
	s_cselect_b32 s26, s50, s51
	v_lshl_add_u64 v[224:225], s[0:1], 0, v[170:171]
	s_add_i32 m0, s23, 0xc000
	ds_read_b128 v[178:181], v195
	ds_read_b128 v[196:199], v195 offset:1024
	ds_read_b128 v[200:203], v195 offset:2048
	ds_read_b128 v[204:207], v195 offset:3072
	ds_read_b128 v[208:211], v195 offset:4096
	ds_read_b128 v[212:215], v195 offset:5120
	ds_read_b128 v[216:219], v195 offset:6144
	ds_read_b128 v[220:223], v195 offset:7168
	global_load_lds_dwordx4 v[224:225], off
	s_add_i32 m0, s23, 0xe000
	v_lshl_add_u64 v[224:225], s[0:1], 0, v[172:173]
	global_load_lds_dwordx4 v[224:225], off
	s_waitcnt vmcnt(8) lgkmcnt(0)
	s_barrier
	v_mfma_f32_16x16x32_bf16 v[124:127], v[128:131], v[178:181], 0
	v_mfma_f32_16x16x32_bf16 v[120:123], v[136:139], v[178:181], 0
	v_mfma_f32_16x16x32_bf16 v[108:111], v[128:131], v[200:203], 0
	v_mfma_f32_16x16x32_bf16 v[104:107], v[136:139], v[200:203], 0
	v_mfma_f32_16x16x32_bf16 v[92:95], v[128:131], v[208:211], 0
	v_mfma_f32_16x16x32_bf16 v[88:91], v[136:139], v[208:211], 0
	v_mfma_f32_16x16x32_bf16 v[76:79], v[128:131], v[216:219], 0
	v_mfma_f32_16x16x32_bf16 v[72:75], v[136:139], v[216:219], 0
	v_mfma_f32_16x16x32_bf16 v[124:127], v[132:135], v[196:199], v[124:127]
	v_mfma_f32_16x16x32_bf16 v[120:123], v[140:143], v[196:199], v[120:123]
	v_mfma_f32_16x16x32_bf16 v[108:111], v[132:135], v[204:207], v[108:111]
	v_mfma_f32_16x16x32_bf16 v[104:107], v[140:143], v[204:207], v[104:107]
	v_mfma_f32_16x16x32_bf16 v[92:95], v[132:135], v[212:215], v[92:95]
	v_mfma_f32_16x16x32_bf16 v[88:91], v[140:143], v[212:215], v[88:91]
	v_mfma_f32_16x16x32_bf16 v[76:79], v[132:135], v[220:223], v[76:79]
	v_mfma_f32_16x16x32_bf16 v[72:75], v[140:143], v[220:223], v[72:75]
	v_mfma_f32_16x16x32_bf16 v[116:119], v[144:147], v[178:181], 0
	v_mfma_f32_16x16x32_bf16 v[112:115], v[152:155], v[178:181], 0
	v_mfma_f32_16x16x32_bf16 v[100:103], v[144:147], v[200:203], 0
	v_mfma_f32_16x16x32_bf16 v[96:99], v[152:155], v[200:203], 0
	v_mfma_f32_16x16x32_bf16 v[84:87], v[144:147], v[208:211], 0
	v_mfma_f32_16x16x32_bf16 v[80:83], v[152:155], v[208:211], 0
	v_mfma_f32_16x16x32_bf16 v[68:71], v[144:147], v[216:219], 0
	v_mfma_f32_16x16x32_bf16 v[64:67], v[152:155], v[216:219], 0
	v_mfma_f32_16x16x32_bf16 v[116:119], v[148:151], v[196:199], v[116:119]
	v_mfma_f32_16x16x32_bf16 v[112:115], v[156:159], v[196:199], v[112:115]
	v_mfma_f32_16x16x32_bf16 v[100:103], v[148:151], v[204:207], v[100:103]
	v_mfma_f32_16x16x32_bf16 v[96:99], v[156:159], v[204:207], v[96:99]
	v_mfma_f32_16x16x32_bf16 v[84:87], v[148:151], v[212:215], v[84:87]
	v_mfma_f32_16x16x32_bf16 v[80:83], v[156:159], v[212:215], v[80:83]
	v_mfma_f32_16x16x32_bf16 v[68:71], v[148:151], v[220:223], v[68:71]
	v_mfma_f32_16x16x32_bf16 v[64:67], v[156:159], v[220:223], v[64:67]
	s_barrier
	s_add_i32 s54, s44, s35
	v_lshl_add_u64 v[224:225], s[26:27], 0, v[164:165]
	s_mov_b32 m0, s54
	ds_read_b128 v[178:181], v195 offset:16384
	ds_read_b128 v[196:199], v195 offset:17408
	ds_read_b128 v[200:203], v195 offset:18432
	ds_read_b128 v[204:207], v195 offset:19456
	ds_read_b128 v[208:211], v195 offset:20480
	ds_read_b128 v[212:215], v195 offset:21504
	ds_read_b128 v[216:219], v195 offset:22528
	ds_read_b128 v[220:223], v195 offset:23552
	global_load_lds_dwordx4 v[224:225], off
	s_add_i32 m0, s54, 0x2000
	s_add_u32 s54, s26, 0x40000
	v_lshl_add_u64 v[226:227], s[26:27], 0, v[168:169]
	s_addc_u32 s55, s27, 0
	s_add_i32 s56, s45, s35
	global_load_lds_dwordx4 v[226:227], off
	v_lshl_add_u64 v[228:229], s[54:55], 0, v[164:165]
	s_mov_b32 m0, s56
	v_lshl_add_u64 v[230:231], s[28:29], 0, v[166:167]
	global_load_lds_dwordx4 v[228:229], off
	s_add_i32 m0, s56, 0x2000
	v_lshl_add_u64 v[228:229], s[54:55], 0, v[168:169]
	global_load_lds_dwordx4 v[228:229], off
	s_mov_b32 m0, s23
	v_lshl_add_u64 v[228:229], s[28:29], 0, v[162:163]
	global_load_lds_dwordx4 v[228:229], off
	s_mov_b32 m0, s25
	s_nop 0
	global_load_lds_dwordx4 v[230:231], off
	s_waitcnt vmcnt(8) lgkmcnt(0)
	s_barrier
	v_mfma_f32_16x16x32_bf16 v[60:63], v[128:131], v[178:181], 0
	v_mfma_f32_16x16x32_bf16 v[56:59], v[136:139], v[178:181], 0
	v_mfma_f32_16x16x32_bf16 v[44:47], v[128:131], v[200:203], 0
	v_mfma_f32_16x16x32_bf16 v[40:43], v[136:139], v[200:203], 0
	v_mfma_f32_16x16x32_bf16 v[28:31], v[128:131], v[208:211], 0
	v_mfma_f32_16x16x32_bf16 v[24:27], v[136:139], v[208:211], 0
	v_mfma_f32_16x16x32_bf16 v[12:15], v[128:131], v[216:219], 0
	v_mfma_f32_16x16x32_bf16 v[8:11], v[136:139], v[216:219], 0
	v_mfma_f32_16x16x32_bf16 v[60:63], v[132:135], v[196:199], v[60:63]
	v_mfma_f32_16x16x32_bf16 v[56:59], v[140:143], v[196:199], v[56:59]
	v_mfma_f32_16x16x32_bf16 v[44:47], v[132:135], v[204:207], v[44:47]
	v_mfma_f32_16x16x32_bf16 v[40:43], v[140:143], v[204:207], v[40:43]
	v_mfma_f32_16x16x32_bf16 v[28:31], v[132:135], v[212:215], v[28:31]
	v_mfma_f32_16x16x32_bf16 v[24:27], v[140:143], v[212:215], v[24:27]
	v_mfma_f32_16x16x32_bf16 v[12:15], v[132:135], v[220:223], v[12:15]
	v_mfma_f32_16x16x32_bf16 v[8:11], v[140:143], v[220:223], v[8:11]
	v_mfma_f32_16x16x32_bf16 v[52:55], v[144:147], v[178:181], 0
	v_mfma_f32_16x16x32_bf16 v[48:51], v[152:155], v[178:181], 0
	v_mfma_f32_16x16x32_bf16 v[36:39], v[144:147], v[200:203], 0
	v_mfma_f32_16x16x32_bf16 v[32:35], v[152:155], v[200:203], 0
	v_mfma_f32_16x16x32_bf16 v[20:23], v[144:147], v[208:211], 0
	v_mfma_f32_16x16x32_bf16 v[16:19], v[152:155], v[208:211], 0
	v_mfma_f32_16x16x32_bf16 v[4:7], v[144:147], v[216:219], 0
	v_mfma_f32_16x16x32_bf16 v[0:3], v[152:155], v[216:219], 0
	v_mfma_f32_16x16x32_bf16 v[52:55], v[148:151], v[196:199], v[52:55]
	v_mfma_f32_16x16x32_bf16 v[48:51], v[156:159], v[196:199], v[48:51]
	v_mfma_f32_16x16x32_bf16 v[36:39], v[148:151], v[204:207], v[36:39]
	v_mfma_f32_16x16x32_bf16 v[32:35], v[156:159], v[204:207], v[32:35]
	v_mfma_f32_16x16x32_bf16 v[20:23], v[148:151], v[212:215], v[20:23]
	v_mfma_f32_16x16x32_bf16 v[16:19], v[156:159], v[212:215], v[16:19]
	v_mfma_f32_16x16x32_bf16 v[4:7], v[148:151], v[220:223], v[4:7]
	v_mfma_f32_16x16x32_bf16 v[0:3], v[156:159], v[220:223], v[0:3]
	s_barrier
	s_add_i32 s54, 0, 0x18000
	s_add_i32 s55, 0, 0x1c000
	v_add_u32_e32 v140, s54, v188
	v_add_u32_e32 v156, s55, v188
	ds_read_b128 v[128:131], v140
	ds_read_b128 v[132:135], v140 offset:1024
	ds_read_b128 v[136:139], v140 offset:2048
	ds_read_b128 v[140:143], v140 offset:3072
	ds_read_b128 v[144:147], v156
	ds_read_b128 v[148:151], v156 offset:1024
	ds_read_b128 v[152:155], v156 offset:2048
	ds_read_b128 v[156:159], v156 offset:3072
	s_add_u32 s28, s28, 0x40000
	s_addc_u32 s29, s29, 0
	s_mov_b32 m0, s36
	v_lshl_add_u64 v[232:233], s[28:29], 0, v[162:163]
	ds_read_b128 v[178:181], v195 offset:32768
	ds_read_b128 v[196:199], v195 offset:33792
	ds_read_b128 v[200:203], v195 offset:34816
	ds_read_b128 v[204:207], v195 offset:35840
	ds_read_b128 v[208:211], v195 offset:36864
	ds_read_b128 v[212:215], v195 offset:37888
	ds_read_b128 v[216:219], v195 offset:38912
	ds_read_b128 v[220:223], v195 offset:39936
	global_load_lds_dwordx4 v[232:233], off
	s_mov_b32 m0, s37
	v_lshl_add_u64 v[232:233], s[28:29], 0, v[166:167]
	global_load_lds_dwordx4 v[232:233], off
	s_waitcnt vmcnt(8) lgkmcnt(0)
	s_barrier
	v_mfma_f32_16x16x32_bf16 v[124:127], v[128:131], v[178:181], v[124:127]
	v_mfma_f32_16x16x32_bf16 v[120:123], v[136:139], v[178:181], v[120:123]
	v_mfma_f32_16x16x32_bf16 v[108:111], v[128:131], v[200:203], v[108:111]
	v_mfma_f32_16x16x32_bf16 v[104:107], v[136:139], v[200:203], v[104:107]
	v_mfma_f32_16x16x32_bf16 v[92:95], v[128:131], v[208:211], v[92:95]
	v_mfma_f32_16x16x32_bf16 v[88:91], v[136:139], v[208:211], v[88:91]
	v_mfma_f32_16x16x32_bf16 v[76:79], v[128:131], v[216:219], v[76:79]
	v_mfma_f32_16x16x32_bf16 v[72:75], v[136:139], v[216:219], v[72:75]
	v_mfma_f32_16x16x32_bf16 v[124:127], v[132:135], v[196:199], v[124:127]
	v_mfma_f32_16x16x32_bf16 v[120:123], v[140:143], v[196:199], v[120:123]
	v_mfma_f32_16x16x32_bf16 v[108:111], v[132:135], v[204:207], v[108:111]
	v_mfma_f32_16x16x32_bf16 v[104:107], v[140:143], v[204:207], v[104:107]
	v_mfma_f32_16x16x32_bf16 v[92:95], v[132:135], v[212:215], v[92:95]
	v_mfma_f32_16x16x32_bf16 v[88:91], v[140:143], v[212:215], v[88:91]
	v_mfma_f32_16x16x32_bf16 v[76:79], v[132:135], v[220:223], v[76:79]
	v_mfma_f32_16x16x32_bf16 v[72:75], v[140:143], v[220:223], v[72:75]
	v_mfma_f32_16x16x32_bf16 v[116:119], v[144:147], v[178:181], v[116:119]
	v_mfma_f32_16x16x32_bf16 v[112:115], v[152:155], v[178:181], v[112:115]
	v_mfma_f32_16x16x32_bf16 v[100:103], v[144:147], v[200:203], v[100:103]
	v_mfma_f32_16x16x32_bf16 v[96:99], v[152:155], v[200:203], v[96:99]
	v_mfma_f32_16x16x32_bf16 v[84:87], v[144:147], v[208:211], v[84:87]
	v_mfma_f32_16x16x32_bf16 v[80:83], v[152:155], v[208:211], v[80:83]
	v_mfma_f32_16x16x32_bf16 v[68:71], v[144:147], v[216:219], v[68:71]
	v_mfma_f32_16x16x32_bf16 v[64:67], v[152:155], v[216:219], v[64:67]
	v_mfma_f32_16x16x32_bf16 v[116:119], v[148:151], v[196:199], v[116:119]
	v_mfma_f32_16x16x32_bf16 v[112:115], v[156:159], v[196:199], v[112:115]
	v_mfma_f32_16x16x32_bf16 v[100:103], v[148:151], v[204:207], v[100:103]
	v_mfma_f32_16x16x32_bf16 v[96:99], v[156:159], v[204:207], v[96:99]
	v_mfma_f32_16x16x32_bf16 v[84:87], v[148:151], v[212:215], v[84:87]
	v_mfma_f32_16x16x32_bf16 v[80:83], v[156:159], v[212:215], v[80:83]
	v_mfma_f32_16x16x32_bf16 v[68:71], v[148:151], v[220:223], v[68:71]
	v_mfma_f32_16x16x32_bf16 v[64:67], v[156:159], v[220:223], v[64:67]
	s_barrier
	s_add_i32 s28, s54, s35
	v_lshl_add_u64 v[224:225], v[224:225], 0, s[10:11]
	s_mov_b32 m0, s28
	ds_read_b128 v[178:181], v195 offset:49152
	ds_read_b128 v[196:199], v195 offset:50176
	ds_read_b128 v[200:203], v195 offset:51200
	ds_read_b128 v[204:207], v195 offset:52224
	ds_read_b128 v[208:211], v195 offset:53248
	ds_read_b128 v[212:215], v195 offset:54272
	ds_read_b128 v[216:219], v195 offset:55296
	ds_read_b128 v[220:223], v195 offset:56320
	global_load_lds_dwordx4 v[224:225], off
	s_add_i32 m0, s28, 0x2000
	s_add_u32 s26, s26, 0x40080
	v_lshl_add_u64 v[224:225], v[226:227], 0, s[10:11]
	s_addc_u32 s27, s27, 0
	s_add_i32 s28, s55, s35
	global_load_lds_dwordx4 v[224:225], off
	s_mov_b32 m0, s28
	v_lshl_add_u64 v[224:225], s[26:27], 0, v[164:165]
	global_load_lds_dwordx4 v[224:225], off
	s_add_i32 m0, s28, 0x2000
	v_lshl_add_u64 v[224:225], s[26:27], 0, v[168:169]
	global_load_lds_dwordx4 v[224:225], off
	s_mov_b32 m0, s40
	v_lshl_add_u64 v[224:225], v[228:229], 0, s[10:11]
	global_load_lds_dwordx4 v[224:225], off
	s_mov_b32 m0, s41
	v_lshl_add_u64 v[224:225], v[230:231], 0, s[10:11]
	global_load_lds_dwordx4 v[224:225], off
	s_waitcnt vmcnt(8) lgkmcnt(0)
	s_barrier
	v_mfma_f32_16x16x32_bf16 v[60:63], v[128:131], v[178:181], v[60:63]
	v_mfma_f32_16x16x32_bf16 v[56:59], v[136:139], v[178:181], v[56:59]
	v_mfma_f32_16x16x32_bf16 v[44:47], v[128:131], v[200:203], v[44:47]
	v_mfma_f32_16x16x32_bf16 v[40:43], v[136:139], v[200:203], v[40:43]
	v_mfma_f32_16x16x32_bf16 v[28:31], v[128:131], v[208:211], v[28:31]
	v_mfma_f32_16x16x32_bf16 v[24:27], v[136:139], v[208:211], v[24:27]
	v_mfma_f32_16x16x32_bf16 v[12:15], v[128:131], v[216:219], v[12:15]
	v_mfma_f32_16x16x32_bf16 v[8:11], v[136:139], v[216:219], v[8:11]
	v_mfma_f32_16x16x32_bf16 v[60:63], v[132:135], v[196:199], v[60:63]
	v_mfma_f32_16x16x32_bf16 v[56:59], v[140:143], v[196:199], v[56:59]
	v_mfma_f32_16x16x32_bf16 v[44:47], v[132:135], v[204:207], v[44:47]
	v_mfma_f32_16x16x32_bf16 v[40:43], v[140:143], v[204:207], v[40:43]
	v_mfma_f32_16x16x32_bf16 v[28:31], v[132:135], v[212:215], v[28:31]
	v_mfma_f32_16x16x32_bf16 v[24:27], v[140:143], v[212:215], v[24:27]
	v_mfma_f32_16x16x32_bf16 v[12:15], v[132:135], v[220:223], v[12:15]
	v_mfma_f32_16x16x32_bf16 v[8:11], v[140:143], v[220:223], v[8:11]
	v_mfma_f32_16x16x32_bf16 v[52:55], v[144:147], v[178:181], v[52:55]
	v_mfma_f32_16x16x32_bf16 v[48:51], v[152:155], v[178:181], v[48:51]
	v_mfma_f32_16x16x32_bf16 v[36:39], v[144:147], v[200:203], v[36:39]
	v_mfma_f32_16x16x32_bf16 v[32:35], v[152:155], v[200:203], v[32:35]
	v_mfma_f32_16x16x32_bf16 v[20:23], v[144:147], v[208:211], v[20:23]
	v_mfma_f32_16x16x32_bf16 v[16:19], v[152:155], v[208:211], v[16:19]
	v_mfma_f32_16x16x32_bf16 v[4:7], v[144:147], v[216:219], v[4:7]
	v_mfma_f32_16x16x32_bf16 v[0:3], v[152:155], v[216:219], v[0:3]
	v_mfma_f32_16x16x32_bf16 v[52:55], v[148:151], v[196:199], v[52:55]
	v_mfma_f32_16x16x32_bf16 v[48:51], v[156:159], v[196:199], v[48:51]
	v_mfma_f32_16x16x32_bf16 v[36:39], v[148:151], v[204:207], v[36:39]
	v_mfma_f32_16x16x32_bf16 v[32:35], v[156:159], v[204:207], v[32:35]
	v_mfma_f32_16x16x32_bf16 v[20:23], v[148:151], v[212:215], v[20:23]
	v_mfma_f32_16x16x32_bf16 v[16:19], v[156:159], v[212:215], v[16:19]
	v_mfma_f32_16x16x32_bf16 v[4:7], v[148:151], v[220:223], v[4:7]
	v_mfma_f32_16x16x32_bf16 v[0:3], v[156:159], v[220:223], v[0:3]
	s_barrier
	s_add_i32 s53, s53, 2
	s_add_u32 s0, s0, 0x100
	s_addc_u32 s1, s1, 0
	s_add_u32 s51, s51, 0x100
	s_addc_u32 s52, s52, 0
	s_cmp_gt_u32 s53, 13
	s_cbranch_scc0 .LBB0_1403
	s_branch .Lpeel_exit_6
.LBB0_1403:
	ds_read_b128 v[128:131], v193
	ds_read_b128 v[132:135], v193 offset:1024
	ds_read_b128 v[136:139], v193 offset:2048
	ds_read_b128 v[140:143], v193 offset:3072
	ds_read_b128 v[144:147], v194
	ds_read_b128 v[148:151], v194 offset:1024
	ds_read_b128 v[152:155], v194 offset:2048
	ds_read_b128 v[156:159], v194 offset:3072
	s_add_u32 s26, s0, 0xfffc0080
	s_addc_u32 s27, s1, -1
	s_cmp_eq_u32 s53, 12
	s_cselect_b32 s29, s17, s27
	s_cselect_b32 s28, s33, s26
	s_cselect_b32 s27, s15, s52
	s_cselect_b32 s26, s50, s51
	v_lshl_add_u64 v[224:225], s[0:1], 0, v[170:171]
	s_add_i32 m0, s23, 0xc000
	ds_read_b128 v[178:181], v195
	ds_read_b128 v[196:199], v195 offset:1024
	ds_read_b128 v[200:203], v195 offset:2048
	ds_read_b128 v[204:207], v195 offset:3072
	ds_read_b128 v[208:211], v195 offset:4096
	ds_read_b128 v[212:215], v195 offset:5120
	ds_read_b128 v[216:219], v195 offset:6144
	ds_read_b128 v[220:223], v195 offset:7168
	global_load_lds_dwordx4 v[224:225], off
	s_add_i32 m0, s23, 0xe000
	v_lshl_add_u64 v[224:225], s[0:1], 0, v[172:173]
	global_load_lds_dwordx4 v[224:225], off
	s_waitcnt vmcnt(8) lgkmcnt(0)
	s_barrier
	v_mfma_f32_16x16x32_bf16 v[124:127], v[128:131], v[178:181], v[124:127]
	v_mfma_f32_16x16x32_bf16 v[120:123], v[136:139], v[178:181], v[120:123]
	v_mfma_f32_16x16x32_bf16 v[108:111], v[128:131], v[200:203], v[108:111]
	v_mfma_f32_16x16x32_bf16 v[104:107], v[136:139], v[200:203], v[104:107]
	v_mfma_f32_16x16x32_bf16 v[92:95], v[128:131], v[208:211], v[92:95]
	v_mfma_f32_16x16x32_bf16 v[88:91], v[136:139], v[208:211], v[88:91]
	v_mfma_f32_16x16x32_bf16 v[76:79], v[128:131], v[216:219], v[76:79]
	v_mfma_f32_16x16x32_bf16 v[72:75], v[136:139], v[216:219], v[72:75]
	v_mfma_f32_16x16x32_bf16 v[124:127], v[132:135], v[196:199], v[124:127]
	v_mfma_f32_16x16x32_bf16 v[120:123], v[140:143], v[196:199], v[120:123]
	v_mfma_f32_16x16x32_bf16 v[108:111], v[132:135], v[204:207], v[108:111]
	v_mfma_f32_16x16x32_bf16 v[104:107], v[140:143], v[204:207], v[104:107]
	v_mfma_f32_16x16x32_bf16 v[92:95], v[132:135], v[212:215], v[92:95]
	v_mfma_f32_16x16x32_bf16 v[88:91], v[140:143], v[212:215], v[88:91]
	v_mfma_f32_16x16x32_bf16 v[76:79], v[132:135], v[220:223], v[76:79]
	v_mfma_f32_16x16x32_bf16 v[72:75], v[140:143], v[220:223], v[72:75]
	v_mfma_f32_16x16x32_bf16 v[116:119], v[144:147], v[178:181], v[116:119]
	v_mfma_f32_16x16x32_bf16 v[112:115], v[152:155], v[178:181], v[112:115]
	v_mfma_f32_16x16x32_bf16 v[100:103], v[144:147], v[200:203], v[100:103]
	v_mfma_f32_16x16x32_bf16 v[96:99], v[152:155], v[200:203], v[96:99]
	v_mfma_f32_16x16x32_bf16 v[84:87], v[144:147], v[208:211], v[84:87]
	v_mfma_f32_16x16x32_bf16 v[80:83], v[152:155], v[208:211], v[80:83]
	v_mfma_f32_16x16x32_bf16 v[68:71], v[144:147], v[216:219], v[68:71]
	v_mfma_f32_16x16x32_bf16 v[64:67], v[152:155], v[216:219], v[64:67]
	v_mfma_f32_16x16x32_bf16 v[116:119], v[148:151], v[196:199], v[116:119]
	v_mfma_f32_16x16x32_bf16 v[112:115], v[156:159], v[196:199], v[112:115]
	v_mfma_f32_16x16x32_bf16 v[100:103], v[148:151], v[204:207], v[100:103]
	v_mfma_f32_16x16x32_bf16 v[96:99], v[156:159], v[204:207], v[96:99]
	v_mfma_f32_16x16x32_bf16 v[84:87], v[148:151], v[212:215], v[84:87]
	v_mfma_f32_16x16x32_bf16 v[80:83], v[156:159], v[212:215], v[80:83]
	v_mfma_f32_16x16x32_bf16 v[68:71], v[148:151], v[220:223], v[68:71]
	v_mfma_f32_16x16x32_bf16 v[64:67], v[156:159], v[220:223], v[64:67]
	s_barrier
	s_add_i32 s54, s44, s35
	v_lshl_add_u64 v[224:225], s[26:27], 0, v[164:165]
	s_mov_b32 m0, s54
	ds_read_b128 v[178:181], v195 offset:16384
	ds_read_b128 v[196:199], v195 offset:17408
	ds_read_b128 v[200:203], v195 offset:18432
	ds_read_b128 v[204:207], v195 offset:19456
	ds_read_b128 v[208:211], v195 offset:20480
	ds_read_b128 v[212:215], v195 offset:21504
	ds_read_b128 v[216:219], v195 offset:22528
	ds_read_b128 v[220:223], v195 offset:23552
	global_load_lds_dwordx4 v[224:225], off
	s_add_i32 m0, s54, 0x2000
	s_add_u32 s54, s26, 0x40000
	v_lshl_add_u64 v[226:227], s[26:27], 0, v[168:169]
	s_addc_u32 s55, s27, 0
	s_add_i32 s56, s45, s35
	global_load_lds_dwordx4 v[226:227], off
	v_lshl_add_u64 v[228:229], s[54:55], 0, v[164:165]
	s_mov_b32 m0, s56
	v_lshl_add_u64 v[230:231], s[28:29], 0, v[166:167]
	global_load_lds_dwordx4 v[228:229], off
	s_add_i32 m0, s56, 0x2000
	v_lshl_add_u64 v[228:229], s[54:55], 0, v[168:169]
	global_load_lds_dwordx4 v[228:229], off
	s_mov_b32 m0, s23
	v_lshl_add_u64 v[228:229], s[28:29], 0, v[162:163]
	global_load_lds_dwordx4 v[228:229], off
	s_mov_b32 m0, s25
	s_nop 0
	global_load_lds_dwordx4 v[230:231], off
	s_waitcnt vmcnt(8) lgkmcnt(0)
	s_barrier
	v_mfma_f32_16x16x32_bf16 v[60:63], v[128:131], v[178:181], v[60:63]
	v_mfma_f32_16x16x32_bf16 v[56:59], v[136:139], v[178:181], v[56:59]
	v_mfma_f32_16x16x32_bf16 v[44:47], v[128:131], v[200:203], v[44:47]
	v_mfma_f32_16x16x32_bf16 v[40:43], v[136:139], v[200:203], v[40:43]
	v_mfma_f32_16x16x32_bf16 v[28:31], v[128:131], v[208:211], v[28:31]
	v_mfma_f32_16x16x32_bf16 v[24:27], v[136:139], v[208:211], v[24:27]
	v_mfma_f32_16x16x32_bf16 v[12:15], v[128:131], v[216:219], v[12:15]
	v_mfma_f32_16x16x32_bf16 v[8:11], v[136:139], v[216:219], v[8:11]
	v_mfma_f32_16x16x32_bf16 v[60:63], v[132:135], v[196:199], v[60:63]
	v_mfma_f32_16x16x32_bf16 v[56:59], v[140:143], v[196:199], v[56:59]
	v_mfma_f32_16x16x32_bf16 v[44:47], v[132:135], v[204:207], v[44:47]
	v_mfma_f32_16x16x32_bf16 v[40:43], v[140:143], v[204:207], v[40:43]
	v_mfma_f32_16x16x32_bf16 v[28:31], v[132:135], v[212:215], v[28:31]
	v_mfma_f32_16x16x32_bf16 v[24:27], v[140:143], v[212:215], v[24:27]
	v_mfma_f32_16x16x32_bf16 v[12:15], v[132:135], v[220:223], v[12:15]
	v_mfma_f32_16x16x32_bf16 v[8:11], v[140:143], v[220:223], v[8:11]
	v_mfma_f32_16x16x32_bf16 v[52:55], v[144:147], v[178:181], v[52:55]
	v_mfma_f32_16x16x32_bf16 v[48:51], v[152:155], v[178:181], v[48:51]
	v_mfma_f32_16x16x32_bf16 v[36:39], v[144:147], v[200:203], v[36:39]
	v_mfma_f32_16x16x32_bf16 v[32:35], v[152:155], v[200:203], v[32:35]
	v_mfma_f32_16x16x32_bf16 v[20:23], v[144:147], v[208:211], v[20:23]
	v_mfma_f32_16x16x32_bf16 v[16:19], v[152:155], v[208:211], v[16:19]
	v_mfma_f32_16x16x32_bf16 v[4:7], v[144:147], v[216:219], v[4:7]
	v_mfma_f32_16x16x32_bf16 v[0:3], v[152:155], v[216:219], v[0:3]
	v_mfma_f32_16x16x32_bf16 v[52:55], v[148:151], v[196:199], v[52:55]
	v_mfma_f32_16x16x32_bf16 v[48:51], v[156:159], v[196:199], v[48:51]
	v_mfma_f32_16x16x32_bf16 v[36:39], v[148:151], v[204:207], v[36:39]
	v_mfma_f32_16x16x32_bf16 v[32:35], v[156:159], v[204:207], v[32:35]
	v_mfma_f32_16x16x32_bf16 v[20:23], v[148:151], v[212:215], v[20:23]
	v_mfma_f32_16x16x32_bf16 v[16:19], v[156:159], v[212:215], v[16:19]
	v_mfma_f32_16x16x32_bf16 v[4:7], v[148:151], v[220:223], v[4:7]
	v_mfma_f32_16x16x32_bf16 v[0:3], v[156:159], v[220:223], v[0:3]
	s_barrier
	s_add_i32 s54, 0, 0x18000
	s_add_i32 s55, 0, 0x1c000
	v_add_u32_e32 v140, s54, v188
	v_add_u32_e32 v156, s55, v188
	ds_read_b128 v[128:131], v140
	ds_read_b128 v[132:135], v140 offset:1024
	ds_read_b128 v[136:139], v140 offset:2048
	ds_read_b128 v[140:143], v140 offset:3072
	ds_read_b128 v[144:147], v156
	ds_read_b128 v[148:151], v156 offset:1024
	ds_read_b128 v[152:155], v156 offset:2048
	ds_read_b128 v[156:159], v156 offset:3072
	s_add_u32 s28, s28, 0x40000
	s_addc_u32 s29, s29, 0
	s_mov_b32 m0, s36
	v_lshl_add_u64 v[232:233], s[28:29], 0, v[162:163]
	ds_read_b128 v[178:181], v195 offset:32768
	ds_read_b128 v[196:199], v195 offset:33792
	ds_read_b128 v[200:203], v195 offset:34816
	ds_read_b128 v[204:207], v195 offset:35840
	ds_read_b128 v[208:211], v195 offset:36864
	ds_read_b128 v[212:215], v195 offset:37888
	ds_read_b128 v[216:219], v195 offset:38912
	ds_read_b128 v[220:223], v195 offset:39936
	global_load_lds_dwordx4 v[232:233], off
	s_mov_b32 m0, s37
	v_lshl_add_u64 v[232:233], s[28:29], 0, v[166:167]
	global_load_lds_dwordx4 v[232:233], off
	s_waitcnt vmcnt(8) lgkmcnt(0)
	s_barrier
	v_mfma_f32_16x16x32_bf16 v[124:127], v[128:131], v[178:181], v[124:127]
	v_mfma_f32_16x16x32_bf16 v[120:123], v[136:139], v[178:181], v[120:123]
	v_mfma_f32_16x16x32_bf16 v[108:111], v[128:131], v[200:203], v[108:111]
	v_mfma_f32_16x16x32_bf16 v[104:107], v[136:139], v[200:203], v[104:107]
	v_mfma_f32_16x16x32_bf16 v[92:95], v[128:131], v[208:211], v[92:95]
	v_mfma_f32_16x16x32_bf16 v[88:91], v[136:139], v[208:211], v[88:91]
	v_mfma_f32_16x16x32_bf16 v[76:79], v[128:131], v[216:219], v[76:79]
	v_mfma_f32_16x16x32_bf16 v[72:75], v[136:139], v[216:219], v[72:75]
	v_mfma_f32_16x16x32_bf16 v[124:127], v[132:135], v[196:199], v[124:127]
	v_mfma_f32_16x16x32_bf16 v[120:123], v[140:143], v[196:199], v[120:123]
	v_mfma_f32_16x16x32_bf16 v[108:111], v[132:135], v[204:207], v[108:111]
	v_mfma_f32_16x16x32_bf16 v[104:107], v[140:143], v[204:207], v[104:107]
	v_mfma_f32_16x16x32_bf16 v[92:95], v[132:135], v[212:215], v[92:95]
	v_mfma_f32_16x16x32_bf16 v[88:91], v[140:143], v[212:215], v[88:91]
	v_mfma_f32_16x16x32_bf16 v[76:79], v[132:135], v[220:223], v[76:79]
	v_mfma_f32_16x16x32_bf16 v[72:75], v[140:143], v[220:223], v[72:75]
	v_mfma_f32_16x16x32_bf16 v[116:119], v[144:147], v[178:181], v[116:119]
	v_mfma_f32_16x16x32_bf16 v[112:115], v[152:155], v[178:181], v[112:115]
	v_mfma_f32_16x16x32_bf16 v[100:103], v[144:147], v[200:203], v[100:103]
	v_mfma_f32_16x16x32_bf16 v[96:99], v[152:155], v[200:203], v[96:99]
	v_mfma_f32_16x16x32_bf16 v[84:87], v[144:147], v[208:211], v[84:87]
	v_mfma_f32_16x16x32_bf16 v[80:83], v[152:155], v[208:211], v[80:83]
	v_mfma_f32_16x16x32_bf16 v[68:71], v[144:147], v[216:219], v[68:71]
	v_mfma_f32_16x16x32_bf16 v[64:67], v[152:155], v[216:219], v[64:67]
	v_mfma_f32_16x16x32_bf16 v[116:119], v[148:151], v[196:199], v[116:119]
	v_mfma_f32_16x16x32_bf16 v[112:115], v[156:159], v[196:199], v[112:115]
	v_mfma_f32_16x16x32_bf16 v[100:103], v[148:151], v[204:207], v[100:103]
	v_mfma_f32_16x16x32_bf16 v[96:99], v[156:159], v[204:207], v[96:99]
	v_mfma_f32_16x16x32_bf16 v[84:87], v[148:151], v[212:215], v[84:87]
	v_mfma_f32_16x16x32_bf16 v[80:83], v[156:159], v[212:215], v[80:83]
	v_mfma_f32_16x16x32_bf16 v[68:71], v[148:151], v[220:223], v[68:71]
	v_mfma_f32_16x16x32_bf16 v[64:67], v[156:159], v[220:223], v[64:67]
	s_barrier
	s_add_i32 s28, s54, s35
	v_lshl_add_u64 v[224:225], v[224:225], 0, s[10:11]
	s_mov_b32 m0, s28
	ds_read_b128 v[178:181], v195 offset:49152
	ds_read_b128 v[196:199], v195 offset:50176
	ds_read_b128 v[200:203], v195 offset:51200
	ds_read_b128 v[204:207], v195 offset:52224
	ds_read_b128 v[208:211], v195 offset:53248
	ds_read_b128 v[212:215], v195 offset:54272
	ds_read_b128 v[216:219], v195 offset:55296
	ds_read_b128 v[220:223], v195 offset:56320
	global_load_lds_dwordx4 v[224:225], off
	s_add_i32 m0, s28, 0x2000
	s_add_u32 s26, s26, 0x40080
	v_lshl_add_u64 v[224:225], v[226:227], 0, s[10:11]
	s_addc_u32 s27, s27, 0
	s_add_i32 s28, s55, s35
	global_load_lds_dwordx4 v[224:225], off
	s_mov_b32 m0, s28
	v_lshl_add_u64 v[224:225], s[26:27], 0, v[164:165]
	global_load_lds_dwordx4 v[224:225], off
	s_add_i32 m0, s28, 0x2000
	v_lshl_add_u64 v[224:225], s[26:27], 0, v[168:169]
	global_load_lds_dwordx4 v[224:225], off
	s_mov_b32 m0, s40
	v_lshl_add_u64 v[224:225], v[228:229], 0, s[10:11]
	global_load_lds_dwordx4 v[224:225], off
	s_mov_b32 m0, s41
	v_lshl_add_u64 v[224:225], v[230:231], 0, s[10:11]
	global_load_lds_dwordx4 v[224:225], off
	s_waitcnt vmcnt(8) lgkmcnt(0)
	s_barrier
	v_mfma_f32_16x16x32_bf16 v[60:63], v[128:131], v[178:181], v[60:63]
	v_mfma_f32_16x16x32_bf16 v[56:59], v[136:139], v[178:181], v[56:59]
	v_mfma_f32_16x16x32_bf16 v[44:47], v[128:131], v[200:203], v[44:47]
	v_mfma_f32_16x16x32_bf16 v[40:43], v[136:139], v[200:203], v[40:43]
	v_mfma_f32_16x16x32_bf16 v[28:31], v[128:131], v[208:211], v[28:31]
	v_mfma_f32_16x16x32_bf16 v[24:27], v[136:139], v[208:211], v[24:27]
	v_mfma_f32_16x16x32_bf16 v[12:15], v[128:131], v[216:219], v[12:15]
	v_mfma_f32_16x16x32_bf16 v[8:11], v[136:139], v[216:219], v[8:11]
	v_mfma_f32_16x16x32_bf16 v[60:63], v[132:135], v[196:199], v[60:63]
	v_mfma_f32_16x16x32_bf16 v[56:59], v[140:143], v[196:199], v[56:59]
	v_mfma_f32_16x16x32_bf16 v[44:47], v[132:135], v[204:207], v[44:47]
	v_mfma_f32_16x16x32_bf16 v[40:43], v[140:143], v[204:207], v[40:43]
	v_mfma_f32_16x16x32_bf16 v[28:31], v[132:135], v[212:215], v[28:31]
	v_mfma_f32_16x16x32_bf16 v[24:27], v[140:143], v[212:215], v[24:27]
	v_mfma_f32_16x16x32_bf16 v[12:15], v[132:135], v[220:223], v[12:15]
	v_mfma_f32_16x16x32_bf16 v[8:11], v[140:143], v[220:223], v[8:11]
	v_mfma_f32_16x16x32_bf16 v[52:55], v[144:147], v[178:181], v[52:55]
	v_mfma_f32_16x16x32_bf16 v[48:51], v[152:155], v[178:181], v[48:51]
	v_mfma_f32_16x16x32_bf16 v[36:39], v[144:147], v[200:203], v[36:39]
	v_mfma_f32_16x16x32_bf16 v[32:35], v[152:155], v[200:203], v[32:35]
	v_mfma_f32_16x16x32_bf16 v[20:23], v[144:147], v[208:211], v[20:23]
	v_mfma_f32_16x16x32_bf16 v[16:19], v[152:155], v[208:211], v[16:19]
	v_mfma_f32_16x16x32_bf16 v[4:7], v[144:147], v[216:219], v[4:7]
	v_mfma_f32_16x16x32_bf16 v[0:3], v[152:155], v[216:219], v[0:3]
	v_mfma_f32_16x16x32_bf16 v[52:55], v[148:151], v[196:199], v[52:55]
	v_mfma_f32_16x16x32_bf16 v[48:51], v[156:159], v[196:199], v[48:51]
	v_mfma_f32_16x16x32_bf16 v[36:39], v[148:151], v[204:207], v[36:39]
	v_mfma_f32_16x16x32_bf16 v[32:35], v[156:159], v[204:207], v[32:35]
	v_mfma_f32_16x16x32_bf16 v[20:23], v[148:151], v[212:215], v[20:23]
	v_mfma_f32_16x16x32_bf16 v[16:19], v[156:159], v[212:215], v[16:19]
	v_mfma_f32_16x16x32_bf16 v[4:7], v[148:151], v[220:223], v[4:7]
	v_mfma_f32_16x16x32_bf16 v[0:3], v[156:159], v[220:223], v[0:3]
	s_barrier
	s_add_i32 s53, s53, 2
	s_add_u32 s0, s0, 0x100
	s_addc_u32 s1, s1, 0
	s_add_u32 s51, s51, 0x100
	s_addc_u32 s52, s52, 0
	s_cmp_gt_u32 s53, 13
	s_cbranch_scc0 .LBB0_1403

.LBB0_1487:
	s_ashr_i32 s15, s14, 31
	s_lshl_b64 s[16:17], s[14:15], 19
	s_add_u32 s16, s66, s16
	s_addc_u32 s17, s67, s17
	s_and_b64 s[18:19], s[4:5], exec
	s_cselect_b32 s15, s17, s1
	s_cselect_b32 s41, s16, s0
	s_ashr_i32 s13, s12, 31
	s_lshl_b64 s[18:19], s[12:13], 19
	s_add_u32 s18, s26, s18
	s_addc_u32 s19, s27, s19
	s_and_b64 s[24:25], s[4:5], exec
	s_cselect_b32 s13, s19, s23
	s_cselect_b32 s42, s18, s22
	s_add_u32 s0, s0, 0x40080
	s_addc_u32 s1, s1, 0
	s_add_u32 s43, s22, 0x100
	s_addc_u32 s44, s23, 0
	s_mov_b32 s45, -2
	v_lshl_add_u32 v248, s20, 8, v156
	v_ashrrev_i32_e32 v249, 31, v248
	v_lshl_add_u64 v[248:249], v[248:249], 2, s[8:9]
	global_load_dword v240, v[248:249], off
	global_load_dword v241, v[248:249], off offset:64
	global_load_dword v242, v[248:249], off offset:128
	global_load_dword v243, v[248:249], off offset:192
	global_load_dword v244, v[248:249], off offset:512
	global_load_dword v245, v[248:249], off offset:576
	global_load_dword v246, v[248:249], off offset:640
	global_load_dword v247, v[248:249], off offset:704
	ds_read_b128 v[144:147], v159
	ds_read_b128 v[148:151], v159 offset:1024
	ds_read_b128 v[152:155], v159 offset:2048
	ds_read_b128 v[166:169], v159 offset:3072
	ds_read_b128 v[170:173], v162
	ds_read_b128 v[174:177], v162 offset:1024
	ds_read_b128 v[178:181], v162 offset:2048
	ds_read_b128 v[188:191], v162 offset:3072
	s_add_u32 s22, s0, 0xfffc0080
	s_addc_u32 s23, s1, -1
	s_cmp_eq_u32 s45, 12
	s_cselect_b32 s25, s15, s23
	s_cselect_b32 s24, s41, s22
	s_cselect_b32 s23, s13, s44
	s_cselect_b32 s22, s42, s43
	v_lshl_add_u64 v[224:225], s[0:1], 0, v[136:137]
	s_add_i32 m0, s21, 0xc000
	ds_read_b128 v[192:195], v163
	ds_read_b128 v[196:199], v163 offset:1024
	ds_read_b128 v[200:203], v163 offset:2048
	ds_read_b128 v[204:207], v163 offset:3072
	ds_read_b128 v[208:211], v163 offset:4096
	ds_read_b128 v[212:215], v163 offset:5120
	ds_read_b128 v[216:219], v163 offset:6144
	ds_read_b128 v[220:223], v163 offset:7168
	global_load_lds_dwordx4 v[224:225], off
	s_add_i32 m0, s21, 0xe000
	v_lshl_add_u64 v[224:225], s[0:1], 0, v[138:139]
	global_load_lds_dwordx4 v[224:225], off
	s_waitcnt vmcnt(8) lgkmcnt(0)
	s_barrier
	v_mfma_f32_16x16x32_bf16 v[124:127], v[144:147], v[192:195], 0
	v_mfma_f32_16x16x32_bf16 v[120:123], v[152:155], v[192:195], 0
	v_mfma_f32_16x16x32_bf16 v[116:119], v[144:147], v[200:203], 0
	v_mfma_f32_16x16x32_bf16 v[104:107], v[152:155], v[200:203], 0
	v_mfma_f32_16x16x32_bf16 v[92:95], v[144:147], v[208:211], 0
	v_mfma_f32_16x16x32_bf16 v[88:91], v[152:155], v[208:211], 0
	v_mfma_f32_16x16x32_bf16 v[76:79], v[144:147], v[216:219], 0
	v_mfma_f32_16x16x32_bf16 v[72:75], v[152:155], v[216:219], 0
	v_mfma_f32_16x16x32_bf16 v[124:127], v[148:151], v[196:199], v[124:127]
	v_mfma_f32_16x16x32_bf16 v[120:123], v[166:169], v[196:199], v[120:123]
	v_mfma_f32_16x16x32_bf16 v[116:119], v[148:151], v[204:207], v[116:119]
	v_mfma_f32_16x16x32_bf16 v[104:107], v[166:169], v[204:207], v[104:107]
	v_mfma_f32_16x16x32_bf16 v[92:95], v[148:151], v[212:215], v[92:95]
	v_mfma_f32_16x16x32_bf16 v[88:91], v[166:169], v[212:215], v[88:91]
	v_mfma_f32_16x16x32_bf16 v[76:79], v[148:151], v[220:223], v[76:79]
	v_mfma_f32_16x16x32_bf16 v[72:75], v[166:169], v[220:223], v[72:75]
	v_mfma_f32_16x16x32_bf16 v[112:115], v[170:173], v[192:195], 0
	v_mfma_f32_16x16x32_bf16 v[108:111], v[178:181], v[192:195], 0
	v_mfma_f32_16x16x32_bf16 v[100:103], v[170:173], v[200:203], 0
	v_mfma_f32_16x16x32_bf16 v[96:99], v[178:181], v[200:203], 0
	v_mfma_f32_16x16x32_bf16 v[84:87], v[170:173], v[208:211], 0
	v_mfma_f32_16x16x32_bf16 v[80:83], v[178:181], v[208:211], 0
	v_mfma_f32_16x16x32_bf16 v[68:71], v[170:173], v[216:219], 0
	v_mfma_f32_16x16x32_bf16 v[64:67], v[178:181], v[216:219], 0
	v_mfma_f32_16x16x32_bf16 v[112:115], v[174:177], v[196:199], v[112:115]
	v_mfma_f32_16x16x32_bf16 v[108:111], v[188:191], v[196:199], v[108:111]
	v_mfma_f32_16x16x32_bf16 v[100:103], v[174:177], v[204:207], v[100:103]
	v_mfma_f32_16x16x32_bf16 v[96:99], v[188:191], v[204:207], v[96:99]
	v_mfma_f32_16x16x32_bf16 v[84:87], v[174:177], v[212:215], v[84:87]
	v_mfma_f32_16x16x32_bf16 v[80:83], v[188:191], v[212:215], v[80:83]
	v_mfma_f32_16x16x32_bf16 v[68:71], v[174:177], v[220:223], v[68:71]
	v_mfma_f32_16x16x32_bf16 v[64:67], v[188:191], v[220:223], v[64:67]
	s_barrier
	s_add_i32 s46, s39, s28
	v_lshl_add_u64 v[224:225], s[22:23], 0, v[132:133]
	s_mov_b32 m0, s46
	ds_read_b128 v[192:195], v163 offset:16384
	ds_read_b128 v[196:199], v163 offset:17408
	ds_read_b128 v[200:203], v163 offset:18432
	ds_read_b128 v[204:207], v163 offset:19456
	ds_read_b128 v[208:211], v163 offset:20480
	ds_read_b128 v[212:215], v163 offset:21504
	ds_read_b128 v[216:219], v163 offset:22528
	ds_read_b128 v[220:223], v163 offset:23552
	global_load_lds_dwordx4 v[224:225], off
	s_add_i32 m0, s46, 0x2000
	s_add_u32 s46, s22, 0x40000
	v_lshl_add_u64 v[226:227], s[22:23], 0, v[128:129]
	s_addc_u32 s47, s23, 0
	s_add_i32 s48, s40, s28
	global_load_lds_dwordx4 v[226:227], off
	v_lshl_add_u64 v[228:229], s[46:47], 0, v[132:133]
	s_mov_b32 m0, s48
	v_lshl_add_u64 v[230:231], s[24:25], 0, v[130:131]
	global_load_lds_dwordx4 v[228:229], off
	s_add_i32 m0, s48, 0x2000
	v_lshl_add_u64 v[228:229], s[46:47], 0, v[128:129]
	global_load_lds_dwordx4 v[228:229], off
	s_mov_b32 m0, s21
	v_lshl_add_u64 v[228:229], s[24:25], 0, v[134:135]
	global_load_lds_dwordx4 v[228:229], off
	s_mov_b32 m0, s31
	s_nop 0
	global_load_lds_dwordx4 v[230:231], off
	s_waitcnt vmcnt(8) lgkmcnt(0)
	s_barrier
	v_mfma_f32_16x16x32_bf16 v[60:63], v[144:147], v[192:195], 0
	v_mfma_f32_16x16x32_bf16 v[56:59], v[152:155], v[192:195], 0
	v_mfma_f32_16x16x32_bf16 v[44:47], v[144:147], v[200:203], 0
	v_mfma_f32_16x16x32_bf16 v[40:43], v[152:155], v[200:203], 0
	v_mfma_f32_16x16x32_bf16 v[28:31], v[144:147], v[208:211], 0
	v_mfma_f32_16x16x32_bf16 v[24:27], v[152:155], v[208:211], 0
	v_mfma_f32_16x16x32_bf16 v[12:15], v[144:147], v[216:219], 0
	v_mfma_f32_16x16x32_bf16 v[8:11], v[152:155], v[216:219], 0
	v_mfma_f32_16x16x32_bf16 v[60:63], v[148:151], v[196:199], v[60:63]
	v_mfma_f32_16x16x32_bf16 v[56:59], v[166:169], v[196:199], v[56:59]
	v_mfma_f32_16x16x32_bf16 v[44:47], v[148:151], v[204:207], v[44:47]
	v_mfma_f32_16x16x32_bf16 v[40:43], v[166:169], v[204:207], v[40:43]
	v_mfma_f32_16x16x32_bf16 v[28:31], v[148:151], v[212:215], v[28:31]
	v_mfma_f32_16x16x32_bf16 v[24:27], v[166:169], v[212:215], v[24:27]
	v_mfma_f32_16x16x32_bf16 v[12:15], v[148:151], v[220:223], v[12:15]
	v_mfma_f32_16x16x32_bf16 v[8:11], v[166:169], v[220:223], v[8:11]
	v_mfma_f32_16x16x32_bf16 v[52:55], v[170:173], v[192:195], 0
	v_mfma_f32_16x16x32_bf16 v[48:51], v[178:181], v[192:195], 0
	v_mfma_f32_16x16x32_bf16 v[36:39], v[170:173], v[200:203], 0
	v_mfma_f32_16x16x32_bf16 v[32:35], v[178:181], v[200:203], 0
	v_mfma_f32_16x16x32_bf16 v[20:23], v[170:173], v[208:211], 0
	v_mfma_f32_16x16x32_bf16 v[16:19], v[178:181], v[208:211], 0
	v_mfma_f32_16x16x32_bf16 v[4:7], v[170:173], v[216:219], 0
	v_mfma_f32_16x16x32_bf16 v[0:3], v[178:181], v[216:219], 0
	v_mfma_f32_16x16x32_bf16 v[52:55], v[174:177], v[196:199], v[52:55]
	v_mfma_f32_16x16x32_bf16 v[48:51], v[188:191], v[196:199], v[48:51]
	v_mfma_f32_16x16x32_bf16 v[36:39], v[174:177], v[204:207], v[36:39]
	v_mfma_f32_16x16x32_bf16 v[32:35], v[188:191], v[204:207], v[32:35]
	v_mfma_f32_16x16x32_bf16 v[20:23], v[174:177], v[212:215], v[20:23]
	v_mfma_f32_16x16x32_bf16 v[16:19], v[188:191], v[212:215], v[16:19]
	v_mfma_f32_16x16x32_bf16 v[4:7], v[174:177], v[220:223], v[4:7]
	v_mfma_f32_16x16x32_bf16 v[0:3], v[188:191], v[220:223], v[0:3]
	s_barrier
	s_add_i32 s46, 0, 0x18000
	v_add_u32_e32 v165, s46, v157
	s_add_i32 s47, 0, 0x1c000
	ds_read_b128 v[144:147], v165
	ds_read_b128 v[148:151], v165 offset:1024
	ds_read_b128 v[152:155], v165 offset:2048
	ds_read_b128 v[166:169], v165 offset:3072
	v_add_u32_e32 v165, s47, v157
	ds_read_b128 v[170:173], v165
	ds_read_b128 v[174:177], v165 offset:1024
	ds_read_b128 v[178:181], v165 offset:2048
	ds_read_b128 v[188:191], v165 offset:3072
	s_add_u32 s24, s24, 0x40000
	s_addc_u32 s25, s25, 0
	s_mov_b32 m0, s34
	v_lshl_add_u64 v[232:233], s[24:25], 0, v[134:135]
	ds_read_b128 v[192:195], v163 offset:32768
	ds_read_b128 v[196:199], v163 offset:33792
	ds_read_b128 v[200:203], v163 offset:34816
	ds_read_b128 v[204:207], v163 offset:35840
	ds_read_b128 v[208:211], v163 offset:36864
	ds_read_b128 v[212:215], v163 offset:37888
	ds_read_b128 v[216:219], v163 offset:38912
	ds_read_b128 v[220:223], v163 offset:39936
	global_load_lds_dwordx4 v[232:233], off
	s_mov_b32 m0, s35
	v_lshl_add_u64 v[232:233], s[24:25], 0, v[130:131]
	global_load_lds_dwordx4 v[232:233], off
	s_waitcnt vmcnt(8) lgkmcnt(0)
	s_barrier
	v_mfma_f32_16x16x32_bf16 v[124:127], v[144:147], v[192:195], v[124:127]
	v_mfma_f32_16x16x32_bf16 v[120:123], v[152:155], v[192:195], v[120:123]
	v_mfma_f32_16x16x32_bf16 v[116:119], v[144:147], v[200:203], v[116:119]
	v_mfma_f32_16x16x32_bf16 v[104:107], v[152:155], v[200:203], v[104:107]
	v_mfma_f32_16x16x32_bf16 v[92:95], v[144:147], v[208:211], v[92:95]
	v_mfma_f32_16x16x32_bf16 v[88:91], v[152:155], v[208:211], v[88:91]
	v_mfma_f32_16x16x32_bf16 v[76:79], v[144:147], v[216:219], v[76:79]
	v_mfma_f32_16x16x32_bf16 v[72:75], v[152:155], v[216:219], v[72:75]
	v_mfma_f32_16x16x32_bf16 v[124:127], v[148:151], v[196:199], v[124:127]
	v_mfma_f32_16x16x32_bf16 v[120:123], v[166:169], v[196:199], v[120:123]
	v_mfma_f32_16x16x32_bf16 v[116:119], v[148:151], v[204:207], v[116:119]
	v_mfma_f32_16x16x32_bf16 v[104:107], v[166:169], v[204:207], v[104:107]
	v_mfma_f32_16x16x32_bf16 v[92:95], v[148:151], v[212:215], v[92:95]
	v_mfma_f32_16x16x32_bf16 v[88:91], v[166:169], v[212:215], v[88:91]
	v_mfma_f32_16x16x32_bf16 v[76:79], v[148:151], v[220:223], v[76:79]
	v_mfma_f32_16x16x32_bf16 v[72:75], v[166:169], v[220:223], v[72:75]
	v_mfma_f32_16x16x32_bf16 v[112:115], v[170:173], v[192:195], v[112:115]
	v_mfma_f32_16x16x32_bf16 v[108:111], v[178:181], v[192:195], v[108:111]
	v_mfma_f32_16x16x32_bf16 v[100:103], v[170:173], v[200:203], v[100:103]
	v_mfma_f32_16x16x32_bf16 v[96:99], v[178:181], v[200:203], v[96:99]
	v_mfma_f32_16x16x32_bf16 v[84:87], v[170:173], v[208:211], v[84:87]
	v_mfma_f32_16x16x32_bf16 v[80:83], v[178:181], v[208:211], v[80:83]
	v_mfma_f32_16x16x32_bf16 v[68:71], v[170:173], v[216:219], v[68:71]
	v_mfma_f32_16x16x32_bf16 v[64:67], v[178:181], v[216:219], v[64:67]
	v_mfma_f32_16x16x32_bf16 v[112:115], v[174:177], v[196:199], v[112:115]
	v_mfma_f32_16x16x32_bf16 v[108:111], v[188:191], v[196:199], v[108:111]
	v_mfma_f32_16x16x32_bf16 v[100:103], v[174:177], v[204:207], v[100:103]
	v_mfma_f32_16x16x32_bf16 v[96:99], v[188:191], v[204:207], v[96:99]
	v_mfma_f32_16x16x32_bf16 v[84:87], v[174:177], v[212:215], v[84:87]
	v_mfma_f32_16x16x32_bf16 v[80:83], v[188:191], v[212:215], v[80:83]
	v_mfma_f32_16x16x32_bf16 v[68:71], v[174:177], v[220:223], v[68:71]
	v_mfma_f32_16x16x32_bf16 v[64:67], v[188:191], v[220:223], v[64:67]
	s_barrier
	s_add_i32 s24, s46, s28
	v_lshl_add_u64 v[224:225], v[224:225], 0, s[6:7]
	s_mov_b32 m0, s24
	ds_read_b128 v[192:195], v163 offset:49152
	ds_read_b128 v[196:199], v163 offset:50176
	ds_read_b128 v[200:203], v163 offset:51200
	ds_read_b128 v[204:207], v163 offset:52224
	ds_read_b128 v[208:211], v163 offset:53248
	ds_read_b128 v[212:215], v163 offset:54272
	ds_read_b128 v[216:219], v163 offset:55296
	ds_read_b128 v[220:223], v163 offset:56320
	global_load_lds_dwordx4 v[224:225], off
	s_add_i32 m0, s24, 0x2000
	s_add_u32 s22, s22, 0x40080
	v_lshl_add_u64 v[224:225], v[226:227], 0, s[6:7]
	s_addc_u32 s23, s23, 0
	s_add_i32 s24, s47, s28
	global_load_lds_dwordx4 v[224:225], off
	s_mov_b32 m0, s24
	v_lshl_add_u64 v[224:225], s[22:23], 0, v[132:133]
	global_load_lds_dwordx4 v[224:225], off
	s_add_i32 m0, s24, 0x2000
	v_lshl_add_u64 v[224:225], s[22:23], 0, v[128:129]
	global_load_lds_dwordx4 v[224:225], off
	s_mov_b32 m0, s37
	v_lshl_add_u64 v[224:225], v[228:229], 0, s[6:7]
	global_load_lds_dwordx4 v[224:225], off
	s_mov_b32 m0, s38
	v_lshl_add_u64 v[224:225], v[230:231], 0, s[6:7]
	global_load_lds_dwordx4 v[224:225], off
	s_waitcnt vmcnt(8) lgkmcnt(0)
	s_barrier
	v_mfma_f32_16x16x32_bf16 v[60:63], v[144:147], v[192:195], v[60:63]
	v_mfma_f32_16x16x32_bf16 v[56:59], v[152:155], v[192:195], v[56:59]
	v_mfma_f32_16x16x32_bf16 v[44:47], v[144:147], v[200:203], v[44:47]
	v_mfma_f32_16x16x32_bf16 v[40:43], v[152:155], v[200:203], v[40:43]
	v_mfma_f32_16x16x32_bf16 v[28:31], v[144:147], v[208:211], v[28:31]
	v_mfma_f32_16x16x32_bf16 v[24:27], v[152:155], v[208:211], v[24:27]
	v_mfma_f32_16x16x32_bf16 v[12:15], v[144:147], v[216:219], v[12:15]
	v_mfma_f32_16x16x32_bf16 v[8:11], v[152:155], v[216:219], v[8:11]
	v_mfma_f32_16x16x32_bf16 v[60:63], v[148:151], v[196:199], v[60:63]
	v_mfma_f32_16x16x32_bf16 v[56:59], v[166:169], v[196:199], v[56:59]
	v_mfma_f32_16x16x32_bf16 v[44:47], v[148:151], v[204:207], v[44:47]
	v_mfma_f32_16x16x32_bf16 v[40:43], v[166:169], v[204:207], v[40:43]
	v_mfma_f32_16x16x32_bf16 v[28:31], v[148:151], v[212:215], v[28:31]
	v_mfma_f32_16x16x32_bf16 v[24:27], v[166:169], v[212:215], v[24:27]
	v_mfma_f32_16x16x32_bf16 v[12:15], v[148:151], v[220:223], v[12:15]
	v_mfma_f32_16x16x32_bf16 v[8:11], v[166:169], v[220:223], v[8:11]
	v_mfma_f32_16x16x32_bf16 v[52:55], v[170:173], v[192:195], v[52:55]
	v_mfma_f32_16x16x32_bf16 v[48:51], v[178:181], v[192:195], v[48:51]
	v_mfma_f32_16x16x32_bf16 v[36:39], v[170:173], v[200:203], v[36:39]
	v_mfma_f32_16x16x32_bf16 v[32:35], v[178:181], v[200:203], v[32:35]
	v_mfma_f32_16x16x32_bf16 v[20:23], v[170:173], v[208:211], v[20:23]
	v_mfma_f32_16x16x32_bf16 v[16:19], v[178:181], v[208:211], v[16:19]
	v_mfma_f32_16x16x32_bf16 v[4:7], v[170:173], v[216:219], v[4:7]
	v_mfma_f32_16x16x32_bf16 v[0:3], v[178:181], v[216:219], v[0:3]
	v_mfma_f32_16x16x32_bf16 v[52:55], v[174:177], v[196:199], v[52:55]
	v_mfma_f32_16x16x32_bf16 v[48:51], v[188:191], v[196:199], v[48:51]
	v_mfma_f32_16x16x32_bf16 v[36:39], v[174:177], v[204:207], v[36:39]
	v_mfma_f32_16x16x32_bf16 v[32:35], v[188:191], v[204:207], v[32:35]
	v_mfma_f32_16x16x32_bf16 v[20:23], v[174:177], v[212:215], v[20:23]
	v_mfma_f32_16x16x32_bf16 v[16:19], v[188:191], v[212:215], v[16:19]
	v_mfma_f32_16x16x32_bf16 v[4:7], v[174:177], v[220:223], v[4:7]
	v_mfma_f32_16x16x32_bf16 v[0:3], v[188:191], v[220:223], v[0:3]
	s_barrier
	s_add_i32 s45, s45, 2
	s_add_u32 s0, s0, 0x100
	s_addc_u32 s1, s1, 0
	s_add_u32 s43, s43, 0x100
	s_addc_u32 s44, s44, 0
	s_cmp_gt_u32 s45, 13
	s_cbranch_scc0 .LBB0_1488
	s_branch .Lpeel_exit_7
.LBB0_1488:
	ds_read_b128 v[144:147], v159
	ds_read_b128 v[148:151], v159 offset:1024
	ds_read_b128 v[152:155], v159 offset:2048
	ds_read_b128 v[166:169], v159 offset:3072
	ds_read_b128 v[170:173], v162
	ds_read_b128 v[174:177], v162 offset:1024
	ds_read_b128 v[178:181], v162 offset:2048
	ds_read_b128 v[188:191], v162 offset:3072
	s_add_u32 s22, s0, 0xfffc0080
	s_addc_u32 s23, s1, -1
	s_cmp_eq_u32 s45, 12
	s_cselect_b32 s25, s15, s23
	s_cselect_b32 s24, s41, s22
	s_cselect_b32 s23, s13, s44
	s_cselect_b32 s22, s42, s43
	v_lshl_add_u64 v[224:225], s[0:1], 0, v[136:137]
	s_add_i32 m0, s21, 0xc000
	ds_read_b128 v[192:195], v163
	ds_read_b128 v[196:199], v163 offset:1024
	ds_read_b128 v[200:203], v163 offset:2048
	ds_read_b128 v[204:207], v163 offset:3072
	ds_read_b128 v[208:211], v163 offset:4096
	ds_read_b128 v[212:215], v163 offset:5120
	ds_read_b128 v[216:219], v163 offset:6144
	ds_read_b128 v[220:223], v163 offset:7168
	global_load_lds_dwordx4 v[224:225], off
	s_add_i32 m0, s21, 0xe000
	v_lshl_add_u64 v[224:225], s[0:1], 0, v[138:139]
	global_load_lds_dwordx4 v[224:225], off
	s_waitcnt vmcnt(8) lgkmcnt(0)
	s_barrier
	v_mfma_f32_16x16x32_bf16 v[124:127], v[144:147], v[192:195], v[124:127]
	v_mfma_f32_16x16x32_bf16 v[120:123], v[152:155], v[192:195], v[120:123]
	v_mfma_f32_16x16x32_bf16 v[116:119], v[144:147], v[200:203], v[116:119]
	v_mfma_f32_16x16x32_bf16 v[104:107], v[152:155], v[200:203], v[104:107]
	v_mfma_f32_16x16x32_bf16 v[92:95], v[144:147], v[208:211], v[92:95]
	v_mfma_f32_16x16x32_bf16 v[88:91], v[152:155], v[208:211], v[88:91]
	v_mfma_f32_16x16x32_bf16 v[76:79], v[144:147], v[216:219], v[76:79]
	v_mfma_f32_16x16x32_bf16 v[72:75], v[152:155], v[216:219], v[72:75]
	v_mfma_f32_16x16x32_bf16 v[124:127], v[148:151], v[196:199], v[124:127]
	v_mfma_f32_16x16x32_bf16 v[120:123], v[166:169], v[196:199], v[120:123]
	v_mfma_f32_16x16x32_bf16 v[116:119], v[148:151], v[204:207], v[116:119]
	v_mfma_f32_16x16x32_bf16 v[104:107], v[166:169], v[204:207], v[104:107]
	v_mfma_f32_16x16x32_bf16 v[92:95], v[148:151], v[212:215], v[92:95]
	v_mfma_f32_16x16x32_bf16 v[88:91], v[166:169], v[212:215], v[88:91]
	v_mfma_f32_16x16x32_bf16 v[76:79], v[148:151], v[220:223], v[76:79]
	v_mfma_f32_16x16x32_bf16 v[72:75], v[166:169], v[220:223], v[72:75]
	v_mfma_f32_16x16x32_bf16 v[112:115], v[170:173], v[192:195], v[112:115]
	v_mfma_f32_16x16x32_bf16 v[108:111], v[178:181], v[192:195], v[108:111]
	v_mfma_f32_16x16x32_bf16 v[100:103], v[170:173], v[200:203], v[100:103]
	v_mfma_f32_16x16x32_bf16 v[96:99], v[178:181], v[200:203], v[96:99]
	v_mfma_f32_16x16x32_bf16 v[84:87], v[170:173], v[208:211], v[84:87]
	v_mfma_f32_16x16x32_bf16 v[80:83], v[178:181], v[208:211], v[80:83]
	v_mfma_f32_16x16x32_bf16 v[68:71], v[170:173], v[216:219], v[68:71]
	v_mfma_f32_16x16x32_bf16 v[64:67], v[178:181], v[216:219], v[64:67]
	v_mfma_f32_16x16x32_bf16 v[112:115], v[174:177], v[196:199], v[112:115]
	v_mfma_f32_16x16x32_bf16 v[108:111], v[188:191], v[196:199], v[108:111]
	v_mfma_f32_16x16x32_bf16 v[100:103], v[174:177], v[204:207], v[100:103]
	v_mfma_f32_16x16x32_bf16 v[96:99], v[188:191], v[204:207], v[96:99]
	v_mfma_f32_16x16x32_bf16 v[84:87], v[174:177], v[212:215], v[84:87]
	v_mfma_f32_16x16x32_bf16 v[80:83], v[188:191], v[212:215], v[80:83]
	v_mfma_f32_16x16x32_bf16 v[68:71], v[174:177], v[220:223], v[68:71]
	v_mfma_f32_16x16x32_bf16 v[64:67], v[188:191], v[220:223], v[64:67]
	s_barrier
	s_add_i32 s46, s39, s28
	v_lshl_add_u64 v[224:225], s[22:23], 0, v[132:133]
	s_mov_b32 m0, s46
	ds_read_b128 v[192:195], v163 offset:16384
	ds_read_b128 v[196:199], v163 offset:17408
	ds_read_b128 v[200:203], v163 offset:18432
	ds_read_b128 v[204:207], v163 offset:19456
	ds_read_b128 v[208:211], v163 offset:20480
	ds_read_b128 v[212:215], v163 offset:21504
	ds_read_b128 v[216:219], v163 offset:22528
	ds_read_b128 v[220:223], v163 offset:23552
	global_load_lds_dwordx4 v[224:225], off
	s_add_i32 m0, s46, 0x2000
	s_add_u32 s46, s22, 0x40000
	v_lshl_add_u64 v[226:227], s[22:23], 0, v[128:129]
	s_addc_u32 s47, s23, 0
	s_add_i32 s48, s40, s28
	global_load_lds_dwordx4 v[226:227], off
	v_lshl_add_u64 v[228:229], s[46:47], 0, v[132:133]
	s_mov_b32 m0, s48
	v_lshl_add_u64 v[230:231], s[24:25], 0, v[130:131]
	global_load_lds_dwordx4 v[228:229], off
	s_add_i32 m0, s48, 0x2000
	v_lshl_add_u64 v[228:229], s[46:47], 0, v[128:129]
	global_load_lds_dwordx4 v[228:229], off
	s_mov_b32 m0, s21
	v_lshl_add_u64 v[228:229], s[24:25], 0, v[134:135]
	global_load_lds_dwordx4 v[228:229], off
	s_mov_b32 m0, s31
	s_nop 0
	global_load_lds_dwordx4 v[230:231], off
	s_waitcnt vmcnt(8) lgkmcnt(0)
	s_barrier
	v_mfma_f32_16x16x32_bf16 v[60:63], v[144:147], v[192:195], v[60:63]
	v_mfma_f32_16x16x32_bf16 v[56:59], v[152:155], v[192:195], v[56:59]
	v_mfma_f32_16x16x32_bf16 v[44:47], v[144:147], v[200:203], v[44:47]
	v_mfma_f32_16x16x32_bf16 v[40:43], v[152:155], v[200:203], v[40:43]
	v_mfma_f32_16x16x32_bf16 v[28:31], v[144:147], v[208:211], v[28:31]
	v_mfma_f32_16x16x32_bf16 v[24:27], v[152:155], v[208:211], v[24:27]
	v_mfma_f32_16x16x32_bf16 v[12:15], v[144:147], v[216:219], v[12:15]
	v_mfma_f32_16x16x32_bf16 v[8:11], v[152:155], v[216:219], v[8:11]
	v_mfma_f32_16x16x32_bf16 v[60:63], v[148:151], v[196:199], v[60:63]
	v_mfma_f32_16x16x32_bf16 v[56:59], v[166:169], v[196:199], v[56:59]
	v_mfma_f32_16x16x32_bf16 v[44:47], v[148:151], v[204:207], v[44:47]
	v_mfma_f32_16x16x32_bf16 v[40:43], v[166:169], v[204:207], v[40:43]
	v_mfma_f32_16x16x32_bf16 v[28:31], v[148:151], v[212:215], v[28:31]
	v_mfma_f32_16x16x32_bf16 v[24:27], v[166:169], v[212:215], v[24:27]
	v_mfma_f32_16x16x32_bf16 v[12:15], v[148:151], v[220:223], v[12:15]
	v_mfma_f32_16x16x32_bf16 v[8:11], v[166:169], v[220:223], v[8:11]
	v_mfma_f32_16x16x32_bf16 v[52:55], v[170:173], v[192:195], v[52:55]
	v_mfma_f32_16x16x32_bf16 v[48:51], v[178:181], v[192:195], v[48:51]
	v_mfma_f32_16x16x32_bf16 v[36:39], v[170:173], v[200:203], v[36:39]
	v_mfma_f32_16x16x32_bf16 v[32:35], v[178:181], v[200:203], v[32:35]
	v_mfma_f32_16x16x32_bf16 v[20:23], v[170:173], v[208:211], v[20:23]
	v_mfma_f32_16x16x32_bf16 v[16:19], v[178:181], v[208:211], v[16:19]
	v_mfma_f32_16x16x32_bf16 v[4:7], v[170:173], v[216:219], v[4:7]
	v_mfma_f32_16x16x32_bf16 v[0:3], v[178:181], v[216:219], v[0:3]
	v_mfma_f32_16x16x32_bf16 v[52:55], v[174:177], v[196:199], v[52:55]
	v_mfma_f32_16x16x32_bf16 v[48:51], v[188:191], v[196:199], v[48:51]
	v_mfma_f32_16x16x32_bf16 v[36:39], v[174:177], v[204:207], v[36:39]
	v_mfma_f32_16x16x32_bf16 v[32:35], v[188:191], v[204:207], v[32:35]
	v_mfma_f32_16x16x32_bf16 v[20:23], v[174:177], v[212:215], v[20:23]
	v_mfma_f32_16x16x32_bf16 v[16:19], v[188:191], v[212:215], v[16:19]
	v_mfma_f32_16x16x32_bf16 v[4:7], v[174:177], v[220:223], v[4:7]
	v_mfma_f32_16x16x32_bf16 v[0:3], v[188:191], v[220:223], v[0:3]
	s_barrier
	s_add_i32 s46, 0, 0x18000
	v_add_u32_e32 v165, s46, v157
	s_add_i32 s47, 0, 0x1c000
	ds_read_b128 v[144:147], v165
	ds_read_b128 v[148:151], v165 offset:1024
	ds_read_b128 v[152:155], v165 offset:2048
	ds_read_b128 v[166:169], v165 offset:3072
	v_add_u32_e32 v165, s47, v157
	ds_read_b128 v[170:173], v165
	ds_read_b128 v[174:177], v165 offset:1024
	ds_read_b128 v[178:181], v165 offset:2048
	ds_read_b128 v[188:191], v165 offset:3072
	s_add_u32 s24, s24, 0x40000
	s_addc_u32 s25, s25, 0
	s_mov_b32 m0, s34
	v_lshl_add_u64 v[232:233], s[24:25], 0, v[134:135]
	ds_read_b128 v[192:195], v163 offset:32768
	ds_read_b128 v[196:199], v163 offset:33792
	ds_read_b128 v[200:203], v163 offset:34816
	ds_read_b128 v[204:207], v163 offset:35840
	ds_read_b128 v[208:211], v163 offset:36864
	ds_read_b128 v[212:215], v163 offset:37888
	ds_read_b128 v[216:219], v163 offset:38912
	ds_read_b128 v[220:223], v163 offset:39936
	global_load_lds_dwordx4 v[232:233], off
	s_mov_b32 m0, s35
	v_lshl_add_u64 v[232:233], s[24:25], 0, v[130:131]
	global_load_lds_dwordx4 v[232:233], off
	s_waitcnt vmcnt(8) lgkmcnt(0)
	s_barrier
	v_mfma_f32_16x16x32_bf16 v[124:127], v[144:147], v[192:195], v[124:127]
	v_mfma_f32_16x16x32_bf16 v[120:123], v[152:155], v[192:195], v[120:123]
	v_mfma_f32_16x16x32_bf16 v[116:119], v[144:147], v[200:203], v[116:119]
	v_mfma_f32_16x16x32_bf16 v[104:107], v[152:155], v[200:203], v[104:107]
	v_mfma_f32_16x16x32_bf16 v[92:95], v[144:147], v[208:211], v[92:95]
	v_mfma_f32_16x16x32_bf16 v[88:91], v[152:155], v[208:211], v[88:91]
	v_mfma_f32_16x16x32_bf16 v[76:79], v[144:147], v[216:219], v[76:79]
	v_mfma_f32_16x16x32_bf16 v[72:75], v[152:155], v[216:219], v[72:75]
	v_mfma_f32_16x16x32_bf16 v[124:127], v[148:151], v[196:199], v[124:127]
	v_mfma_f32_16x16x32_bf16 v[120:123], v[166:169], v[196:199], v[120:123]
	v_mfma_f32_16x16x32_bf16 v[116:119], v[148:151], v[204:207], v[116:119]
	v_mfma_f32_16x16x32_bf16 v[104:107], v[166:169], v[204:207], v[104:107]
	v_mfma_f32_16x16x32_bf16 v[92:95], v[148:151], v[212:215], v[92:95]
	v_mfma_f32_16x16x32_bf16 v[88:91], v[166:169], v[212:215], v[88:91]
	v_mfma_f32_16x16x32_bf16 v[76:79], v[148:151], v[220:223], v[76:79]
	v_mfma_f32_16x16x32_bf16 v[72:75], v[166:169], v[220:223], v[72:75]
	v_mfma_f32_16x16x32_bf16 v[112:115], v[170:173], v[192:195], v[112:115]
	v_mfma_f32_16x16x32_bf16 v[108:111], v[178:181], v[192:195], v[108:111]
	v_mfma_f32_16x16x32_bf16 v[100:103], v[170:173], v[200:203], v[100:103]
	v_mfma_f32_16x16x32_bf16 v[96:99], v[178:181], v[200:203], v[96:99]
	v_mfma_f32_16x16x32_bf16 v[84:87], v[170:173], v[208:211], v[84:87]
	v_mfma_f32_16x16x32_bf16 v[80:83], v[178:181], v[208:211], v[80:83]
	v_mfma_f32_16x16x32_bf16 v[68:71], v[170:173], v[216:219], v[68:71]
	v_mfma_f32_16x16x32_bf16 v[64:67], v[178:181], v[216:219], v[64:67]
	v_mfma_f32_16x16x32_bf16 v[112:115], v[174:177], v[196:199], v[112:115]
	v_mfma_f32_16x16x32_bf16 v[108:111], v[188:191], v[196:199], v[108:111]
	v_mfma_f32_16x16x32_bf16 v[100:103], v[174:177], v[204:207], v[100:103]
	v_mfma_f32_16x16x32_bf16 v[96:99], v[188:191], v[204:207], v[96:99]
	v_mfma_f32_16x16x32_bf16 v[84:87], v[174:177], v[212:215], v[84:87]
	v_mfma_f32_16x16x32_bf16 v[80:83], v[188:191], v[212:215], v[80:83]
	v_mfma_f32_16x16x32_bf16 v[68:71], v[174:177], v[220:223], v[68:71]
	v_mfma_f32_16x16x32_bf16 v[64:67], v[188:191], v[220:223], v[64:67]
	s_barrier
	s_add_i32 s24, s46, s28
	v_lshl_add_u64 v[224:225], v[224:225], 0, s[6:7]
	s_mov_b32 m0, s24
	ds_read_b128 v[192:195], v163 offset:49152
	ds_read_b128 v[196:199], v163 offset:50176
	ds_read_b128 v[200:203], v163 offset:51200
	ds_read_b128 v[204:207], v163 offset:52224
	ds_read_b128 v[208:211], v163 offset:53248
	ds_read_b128 v[212:215], v163 offset:54272
	ds_read_b128 v[216:219], v163 offset:55296
	ds_read_b128 v[220:223], v163 offset:56320
	global_load_lds_dwordx4 v[224:225], off
	s_add_i32 m0, s24, 0x2000
	s_add_u32 s22, s22, 0x40080
	v_lshl_add_u64 v[224:225], v[226:227], 0, s[6:7]
	s_addc_u32 s23, s23, 0
	s_add_i32 s24, s47, s28
	global_load_lds_dwordx4 v[224:225], off
	s_mov_b32 m0, s24
	v_lshl_add_u64 v[224:225], s[22:23], 0, v[132:133]
	global_load_lds_dwordx4 v[224:225], off
	s_add_i32 m0, s24, 0x2000
	v_lshl_add_u64 v[224:225], s[22:23], 0, v[128:129]
	global_load_lds_dwordx4 v[224:225], off
	s_mov_b32 m0, s37
	v_lshl_add_u64 v[224:225], v[228:229], 0, s[6:7]
	global_load_lds_dwordx4 v[224:225], off
	s_mov_b32 m0, s38
	v_lshl_add_u64 v[224:225], v[230:231], 0, s[6:7]
	global_load_lds_dwordx4 v[224:225], off
	s_waitcnt vmcnt(8) lgkmcnt(0)
	s_barrier
	v_mfma_f32_16x16x32_bf16 v[60:63], v[144:147], v[192:195], v[60:63]
	v_mfma_f32_16x16x32_bf16 v[56:59], v[152:155], v[192:195], v[56:59]
	v_mfma_f32_16x16x32_bf16 v[44:47], v[144:147], v[200:203], v[44:47]
	v_mfma_f32_16x16x32_bf16 v[40:43], v[152:155], v[200:203], v[40:43]
	v_mfma_f32_16x16x32_bf16 v[28:31], v[144:147], v[208:211], v[28:31]
	v_mfma_f32_16x16x32_bf16 v[24:27], v[152:155], v[208:211], v[24:27]
	v_mfma_f32_16x16x32_bf16 v[12:15], v[144:147], v[216:219], v[12:15]
	v_mfma_f32_16x16x32_bf16 v[8:11], v[152:155], v[216:219], v[8:11]
	v_mfma_f32_16x16x32_bf16 v[60:63], v[148:151], v[196:199], v[60:63]
	v_mfma_f32_16x16x32_bf16 v[56:59], v[166:169], v[196:199], v[56:59]
	v_mfma_f32_16x16x32_bf16 v[44:47], v[148:151], v[204:207], v[44:47]
	v_mfma_f32_16x16x32_bf16 v[40:43], v[166:169], v[204:207], v[40:43]
	v_mfma_f32_16x16x32_bf16 v[28:31], v[148:151], v[212:215], v[28:31]
	v_mfma_f32_16x16x32_bf16 v[24:27], v[166:169], v[212:215], v[24:27]
	v_mfma_f32_16x16x32_bf16 v[12:15], v[148:151], v[220:223], v[12:15]
	v_mfma_f32_16x16x32_bf16 v[8:11], v[166:169], v[220:223], v[8:11]
	v_mfma_f32_16x16x32_bf16 v[52:55], v[170:173], v[192:195], v[52:55]
	v_mfma_f32_16x16x32_bf16 v[48:51], v[178:181], v[192:195], v[48:51]
	v_mfma_f32_16x16x32_bf16 v[36:39], v[170:173], v[200:203], v[36:39]
	v_mfma_f32_16x16x32_bf16 v[32:35], v[178:181], v[200:203], v[32:35]
	v_mfma_f32_16x16x32_bf16 v[20:23], v[170:173], v[208:211], v[20:23]
	v_mfma_f32_16x16x32_bf16 v[16:19], v[178:181], v[208:211], v[16:19]
	v_mfma_f32_16x16x32_bf16 v[4:7], v[170:173], v[216:219], v[4:7]
	v_mfma_f32_16x16x32_bf16 v[0:3], v[178:181], v[216:219], v[0:3]
	v_mfma_f32_16x16x32_bf16 v[52:55], v[174:177], v[196:199], v[52:55]
	v_mfma_f32_16x16x32_bf16 v[48:51], v[188:191], v[196:199], v[48:51]
	v_mfma_f32_16x16x32_bf16 v[36:39], v[174:177], v[204:207], v[36:39]
	v_mfma_f32_16x16x32_bf16 v[32:35], v[188:191], v[204:207], v[32:35]
	v_mfma_f32_16x16x32_bf16 v[20:23], v[174:177], v[212:215], v[20:23]
	v_mfma_f32_16x16x32_bf16 v[16:19], v[188:191], v[212:215], v[16:19]
	v_mfma_f32_16x16x32_bf16 v[4:7], v[174:177], v[220:223], v[4:7]
	v_mfma_f32_16x16x32_bf16 v[0:3], v[188:191], v[220:223], v[0:3]
	s_barrier
	s_add_i32 s45, s45, 2
	s_add_u32 s0, s0, 0x100
	s_addc_u32 s1, s1, 0
	s_add_u32 s43, s43, 0x100
	s_addc_u32 s44, s44, 0
	s_cmp_gt_u32 s45, 13
	s_cbranch_scc0 .LBB0_1488

.LBB0_1562:
	s_ashr_i32 s17, s16, 31
	s_lshl_b64 s[18:19], s[16:17], 21
	s_add_u32 s18, s68, s18
	s_addc_u32 s19, s69, s19
	s_and_b64 s[20:21], s[4:5], exec
	s_cselect_b32 s17, s19, s1
	s_cselect_b32 s33, s18, s0
	s_ashr_i32 s15, s14, 31
	s_lshl_b64 s[20:21], s[14:15], 21
	s_add_u32 s20, s30, s20
	s_addc_u32 s21, s31, s21
	s_and_b64 s[28:29], s[4:5], exec
	s_cselect_b32 s15, s21, s27
	s_cselect_b32 s49, s20, s26
	s_add_u32 s0, s0, 0x100080
	s_addc_u32 s1, s1, 0
	s_add_u32 s50, s26, 0x100
	s_addc_u32 s51, s27, 0
	s_mov_b32 s52, -2
	s_waitcnt lgkmcnt(0)
	ds_read_b128 v[128:131], v193
	ds_read_b128 v[132:135], v193 offset:1024
	ds_read_b128 v[136:139], v193 offset:2048
	ds_read_b128 v[140:143], v193 offset:3072
	ds_read_b128 v[144:147], v194
	ds_read_b128 v[148:151], v194 offset:1024
	ds_read_b128 v[152:155], v194 offset:2048
	ds_read_b128 v[156:159], v194 offset:3072
	s_add_u32 s26, s0, 0xfff00080
	s_addc_u32 s27, s1, -1
	s_cmp_eq_u32 s52, 60
	s_cselect_b32 s29, s17, s27
	s_cselect_b32 s28, s33, s26
	s_cselect_b32 s27, s15, s51
	s_cselect_b32 s26, s49, s50
	v_lshl_add_u64 v[224:225], s[0:1], 0, v[170:171]
	s_add_i32 m0, s23, 0xc000
	ds_read_b128 v[178:181], v195
	ds_read_b128 v[196:199], v195 offset:1024
	ds_read_b128 v[200:203], v195 offset:2048
	ds_read_b128 v[204:207], v195 offset:3072
	ds_read_b128 v[208:211], v195 offset:4096
	ds_read_b128 v[212:215], v195 offset:5120
	ds_read_b128 v[216:219], v195 offset:6144
	ds_read_b128 v[220:223], v195 offset:7168
	global_load_lds_dwordx4 v[224:225], off
	s_add_i32 m0, s23, 0xe000
	v_lshl_add_u64 v[224:225], s[0:1], 0, v[172:173]
	global_load_lds_dwordx4 v[224:225], off
	s_waitcnt vmcnt(8) lgkmcnt(0)
	s_barrier
	v_mfma_f32_16x16x32_bf16 v[124:127], v[128:131], v[178:181], 0
	v_mfma_f32_16x16x32_bf16 v[120:123], v[136:139], v[178:181], 0
	v_mfma_f32_16x16x32_bf16 v[108:111], v[128:131], v[200:203], 0
	v_mfma_f32_16x16x32_bf16 v[104:107], v[136:139], v[200:203], 0
	v_mfma_f32_16x16x32_bf16 v[92:95], v[128:131], v[208:211], 0
	v_mfma_f32_16x16x32_bf16 v[88:91], v[136:139], v[208:211], 0
	v_mfma_f32_16x16x32_bf16 v[76:79], v[128:131], v[216:219], 0
	v_mfma_f32_16x16x32_bf16 v[72:75], v[136:139], v[216:219], 0
	v_mfma_f32_16x16x32_bf16 v[124:127], v[132:135], v[196:199], v[124:127]
	v_mfma_f32_16x16x32_bf16 v[120:123], v[140:143], v[196:199], v[120:123]
	v_mfma_f32_16x16x32_bf16 v[108:111], v[132:135], v[204:207], v[108:111]
	v_mfma_f32_16x16x32_bf16 v[104:107], v[140:143], v[204:207], v[104:107]
	v_mfma_f32_16x16x32_bf16 v[92:95], v[132:135], v[212:215], v[92:95]
	v_mfma_f32_16x16x32_bf16 v[88:91], v[140:143], v[212:215], v[88:91]
	v_mfma_f32_16x16x32_bf16 v[76:79], v[132:135], v[220:223], v[76:79]
	v_mfma_f32_16x16x32_bf16 v[72:75], v[140:143], v[220:223], v[72:75]
	v_mfma_f32_16x16x32_bf16 v[116:119], v[144:147], v[178:181], 0
	v_mfma_f32_16x16x32_bf16 v[112:115], v[152:155], v[178:181], 0
	v_mfma_f32_16x16x32_bf16 v[100:103], v[144:147], v[200:203], 0
	v_mfma_f32_16x16x32_bf16 v[96:99], v[152:155], v[200:203], 0
	v_mfma_f32_16x16x32_bf16 v[84:87], v[144:147], v[208:211], 0
	v_mfma_f32_16x16x32_bf16 v[80:83], v[152:155], v[208:211], 0
	v_mfma_f32_16x16x32_bf16 v[68:71], v[144:147], v[216:219], 0
	v_mfma_f32_16x16x32_bf16 v[64:67], v[152:155], v[216:219], 0
	v_mfma_f32_16x16x32_bf16 v[116:119], v[148:151], v[196:199], v[116:119]
	v_mfma_f32_16x16x32_bf16 v[112:115], v[156:159], v[196:199], v[112:115]
	v_mfma_f32_16x16x32_bf16 v[100:103], v[148:151], v[204:207], v[100:103]
	v_mfma_f32_16x16x32_bf16 v[96:99], v[156:159], v[204:207], v[96:99]
	v_mfma_f32_16x16x32_bf16 v[84:87], v[148:151], v[212:215], v[84:87]
	v_mfma_f32_16x16x32_bf16 v[80:83], v[156:159], v[212:215], v[80:83]
	v_mfma_f32_16x16x32_bf16 v[68:71], v[148:151], v[220:223], v[68:71]
	v_mfma_f32_16x16x32_bf16 v[64:67], v[156:159], v[220:223], v[64:67]
	s_barrier
	s_add_i32 s53, s43, s34
	v_lshl_add_u64 v[224:225], s[26:27], 0, v[164:165]
	s_mov_b32 m0, s53
	ds_read_b128 v[178:181], v195 offset:16384
	ds_read_b128 v[196:199], v195 offset:17408
	ds_read_b128 v[200:203], v195 offset:18432
	ds_read_b128 v[204:207], v195 offset:19456
	ds_read_b128 v[208:211], v195 offset:20480
	ds_read_b128 v[212:215], v195 offset:21504
	ds_read_b128 v[216:219], v195 offset:22528
	ds_read_b128 v[220:223], v195 offset:23552
	global_load_lds_dwordx4 v[224:225], off
	s_add_i32 m0, s53, 0x2000
	s_add_u32 s54, s26, 0x100000
	v_lshl_add_u64 v[226:227], s[26:27], 0, v[168:169]
	s_addc_u32 s55, s27, 0
	s_add_i32 s53, s44, s34
	global_load_lds_dwordx4 v[226:227], off
	v_lshl_add_u64 v[228:229], s[54:55], 0, v[164:165]
	s_mov_b32 m0, s53
	v_lshl_add_u64 v[230:231], s[28:29], 0, v[166:167]
	global_load_lds_dwordx4 v[228:229], off
	s_add_i32 m0, s53, 0x2000
	v_lshl_add_u64 v[228:229], s[54:55], 0, v[168:169]
	global_load_lds_dwordx4 v[228:229], off
	s_mov_b32 m0, s23
	v_lshl_add_u64 v[228:229], s[28:29], 0, v[162:163]
	global_load_lds_dwordx4 v[228:229], off
	s_mov_b32 m0, s25
	s_nop 0
	global_load_lds_dwordx4 v[230:231], off
	s_waitcnt vmcnt(8) lgkmcnt(0)
	s_barrier
	v_mfma_f32_16x16x32_bf16 v[60:63], v[128:131], v[178:181], 0
	v_mfma_f32_16x16x32_bf16 v[56:59], v[136:139], v[178:181], 0
	v_mfma_f32_16x16x32_bf16 v[44:47], v[128:131], v[200:203], 0
	v_mfma_f32_16x16x32_bf16 v[40:43], v[136:139], v[200:203], 0
	v_mfma_f32_16x16x32_bf16 v[28:31], v[128:131], v[208:211], 0
	v_mfma_f32_16x16x32_bf16 v[24:27], v[136:139], v[208:211], 0
	v_mfma_f32_16x16x32_bf16 v[12:15], v[128:131], v[216:219], 0
	v_mfma_f32_16x16x32_bf16 v[8:11], v[136:139], v[216:219], 0
	v_mfma_f32_16x16x32_bf16 v[60:63], v[132:135], v[196:199], v[60:63]
	v_mfma_f32_16x16x32_bf16 v[56:59], v[140:143], v[196:199], v[56:59]
	v_mfma_f32_16x16x32_bf16 v[44:47], v[132:135], v[204:207], v[44:47]
	v_mfma_f32_16x16x32_bf16 v[40:43], v[140:143], v[204:207], v[40:43]
	v_mfma_f32_16x16x32_bf16 v[28:31], v[132:135], v[212:215], v[28:31]
	v_mfma_f32_16x16x32_bf16 v[24:27], v[140:143], v[212:215], v[24:27]
	v_mfma_f32_16x16x32_bf16 v[12:15], v[132:135], v[220:223], v[12:15]
	v_mfma_f32_16x16x32_bf16 v[8:11], v[140:143], v[220:223], v[8:11]
	v_mfma_f32_16x16x32_bf16 v[52:55], v[144:147], v[178:181], 0
	v_mfma_f32_16x16x32_bf16 v[48:51], v[152:155], v[178:181], 0
	v_mfma_f32_16x16x32_bf16 v[36:39], v[144:147], v[200:203], 0
	v_mfma_f32_16x16x32_bf16 v[32:35], v[152:155], v[200:203], 0
	v_mfma_f32_16x16x32_bf16 v[20:23], v[144:147], v[208:211], 0
	v_mfma_f32_16x16x32_bf16 v[16:19], v[152:155], v[208:211], 0
	v_mfma_f32_16x16x32_bf16 v[4:7], v[144:147], v[216:219], 0
	v_mfma_f32_16x16x32_bf16 v[0:3], v[152:155], v[216:219], 0
	v_mfma_f32_16x16x32_bf16 v[52:55], v[148:151], v[196:199], v[52:55]
	v_mfma_f32_16x16x32_bf16 v[48:51], v[156:159], v[196:199], v[48:51]
	v_mfma_f32_16x16x32_bf16 v[36:39], v[148:151], v[204:207], v[36:39]
	v_mfma_f32_16x16x32_bf16 v[32:35], v[156:159], v[204:207], v[32:35]
	v_mfma_f32_16x16x32_bf16 v[20:23], v[148:151], v[212:215], v[20:23]
	v_mfma_f32_16x16x32_bf16 v[16:19], v[156:159], v[212:215], v[16:19]
	v_mfma_f32_16x16x32_bf16 v[4:7], v[148:151], v[220:223], v[4:7]
	v_mfma_f32_16x16x32_bf16 v[0:3], v[156:159], v[220:223], v[0:3]
	s_barrier
	s_add_i32 s53, 0, 0x18000
	s_add_i32 s54, 0, 0x1c000
	v_add_u32_e32 v140, s53, v188
	v_add_u32_e32 v156, s54, v188
	ds_read_b128 v[128:131], v140
	ds_read_b128 v[132:135], v140 offset:1024
	ds_read_b128 v[136:139], v140 offset:2048
	ds_read_b128 v[140:143], v140 offset:3072
	ds_read_b128 v[144:147], v156
	ds_read_b128 v[148:151], v156 offset:1024
	ds_read_b128 v[152:155], v156 offset:2048
	ds_read_b128 v[156:159], v156 offset:3072
	s_add_u32 s28, s28, 0x100000
	s_addc_u32 s29, s29, 0
	s_mov_b32 m0, s35
	v_lshl_add_u64 v[232:233], s[28:29], 0, v[162:163]
	ds_read_b128 v[178:181], v195 offset:32768
	ds_read_b128 v[196:199], v195 offset:33792
	ds_read_b128 v[200:203], v195 offset:34816
	ds_read_b128 v[204:207], v195 offset:35840
	ds_read_b128 v[208:211], v195 offset:36864
	ds_read_b128 v[212:215], v195 offset:37888
	ds_read_b128 v[216:219], v195 offset:38912
	ds_read_b128 v[220:223], v195 offset:39936
	global_load_lds_dwordx4 v[232:233], off
	s_mov_b32 m0, s36
	v_lshl_add_u64 v[232:233], s[28:29], 0, v[166:167]
	global_load_lds_dwordx4 v[232:233], off
	s_waitcnt vmcnt(8) lgkmcnt(0)
	s_barrier
	v_mfma_f32_16x16x32_bf16 v[124:127], v[128:131], v[178:181], v[124:127]
	v_mfma_f32_16x16x32_bf16 v[120:123], v[136:139], v[178:181], v[120:123]
	v_mfma_f32_16x16x32_bf16 v[108:111], v[128:131], v[200:203], v[108:111]
	v_mfma_f32_16x16x32_bf16 v[104:107], v[136:139], v[200:203], v[104:107]
	v_mfma_f32_16x16x32_bf16 v[92:95], v[128:131], v[208:211], v[92:95]
	v_mfma_f32_16x16x32_bf16 v[88:91], v[136:139], v[208:211], v[88:91]
	v_mfma_f32_16x16x32_bf16 v[76:79], v[128:131], v[216:219], v[76:79]
	v_mfma_f32_16x16x32_bf16 v[72:75], v[136:139], v[216:219], v[72:75]
	v_mfma_f32_16x16x32_bf16 v[124:127], v[132:135], v[196:199], v[124:127]
	v_mfma_f32_16x16x32_bf16 v[120:123], v[140:143], v[196:199], v[120:123]
	v_mfma_f32_16x16x32_bf16 v[108:111], v[132:135], v[204:207], v[108:111]
	v_mfma_f32_16x16x32_bf16 v[104:107], v[140:143], v[204:207], v[104:107]
	v_mfma_f32_16x16x32_bf16 v[92:95], v[132:135], v[212:215], v[92:95]
	v_mfma_f32_16x16x32_bf16 v[88:91], v[140:143], v[212:215], v[88:91]
	v_mfma_f32_16x16x32_bf16 v[76:79], v[132:135], v[220:223], v[76:79]
	v_mfma_f32_16x16x32_bf16 v[72:75], v[140:143], v[220:223], v[72:75]
	v_mfma_f32_16x16x32_bf16 v[116:119], v[144:147], v[178:181], v[116:119]
	v_mfma_f32_16x16x32_bf16 v[112:115], v[152:155], v[178:181], v[112:115]
	v_mfma_f32_16x16x32_bf16 v[100:103], v[144:147], v[200:203], v[100:103]
	v_mfma_f32_16x16x32_bf16 v[96:99], v[152:155], v[200:203], v[96:99]
	v_mfma_f32_16x16x32_bf16 v[84:87], v[144:147], v[208:211], v[84:87]
	v_mfma_f32_16x16x32_bf16 v[80:83], v[152:155], v[208:211], v[80:83]
	v_mfma_f32_16x16x32_bf16 v[68:71], v[144:147], v[216:219], v[68:71]
	v_mfma_f32_16x16x32_bf16 v[64:67], v[152:155], v[216:219], v[64:67]
	v_mfma_f32_16x16x32_bf16 v[116:119], v[148:151], v[196:199], v[116:119]
	v_mfma_f32_16x16x32_bf16 v[112:115], v[156:159], v[196:199], v[112:115]
	v_mfma_f32_16x16x32_bf16 v[100:103], v[148:151], v[204:207], v[100:103]
	v_mfma_f32_16x16x32_bf16 v[96:99], v[156:159], v[204:207], v[96:99]
	v_mfma_f32_16x16x32_bf16 v[84:87], v[148:151], v[212:215], v[84:87]
	v_mfma_f32_16x16x32_bf16 v[80:83], v[156:159], v[212:215], v[80:83]
	v_mfma_f32_16x16x32_bf16 v[68:71], v[148:151], v[220:223], v[68:71]
	v_mfma_f32_16x16x32_bf16 v[64:67], v[156:159], v[220:223], v[64:67]
	s_barrier
	s_add_i32 s28, s53, s34
	v_lshl_add_u64 v[224:225], v[224:225], 0, s[10:11]
	s_mov_b32 m0, s28
	ds_read_b128 v[178:181], v195 offset:49152
	ds_read_b128 v[196:199], v195 offset:50176
	ds_read_b128 v[200:203], v195 offset:51200
	ds_read_b128 v[204:207], v195 offset:52224
	ds_read_b128 v[208:211], v195 offset:53248
	ds_read_b128 v[212:215], v195 offset:54272
	ds_read_b128 v[216:219], v195 offset:55296
	ds_read_b128 v[220:223], v195 offset:56320
	global_load_lds_dwordx4 v[224:225], off
	s_add_i32 m0, s28, 0x2000
	s_add_u32 s26, s26, 0x100080
	v_lshl_add_u64 v[224:225], v[226:227], 0, s[10:11]
	s_addc_u32 s27, s27, 0
	s_add_i32 s28, s54, s34
	global_load_lds_dwordx4 v[224:225], off
	s_mov_b32 m0, s28
	v_lshl_add_u64 v[224:225], s[26:27], 0, v[164:165]
	global_load_lds_dwordx4 v[224:225], off
	s_add_i32 m0, s28, 0x2000
	v_lshl_add_u64 v[224:225], s[26:27], 0, v[168:169]
	global_load_lds_dwordx4 v[224:225], off
	s_mov_b32 m0, s39
	v_lshl_add_u64 v[224:225], v[228:229], 0, s[10:11]
	global_load_lds_dwordx4 v[224:225], off
	s_mov_b32 m0, s40
	v_lshl_add_u64 v[224:225], v[230:231], 0, s[10:11]
	global_load_lds_dwordx4 v[224:225], off
	s_waitcnt vmcnt(8) lgkmcnt(0)
	s_barrier
	v_mfma_f32_16x16x32_bf16 v[60:63], v[128:131], v[178:181], v[60:63]
	v_mfma_f32_16x16x32_bf16 v[56:59], v[136:139], v[178:181], v[56:59]
	v_mfma_f32_16x16x32_bf16 v[44:47], v[128:131], v[200:203], v[44:47]
	v_mfma_f32_16x16x32_bf16 v[40:43], v[136:139], v[200:203], v[40:43]
	v_mfma_f32_16x16x32_bf16 v[28:31], v[128:131], v[208:211], v[28:31]
	v_mfma_f32_16x16x32_bf16 v[24:27], v[136:139], v[208:211], v[24:27]
	v_mfma_f32_16x16x32_bf16 v[12:15], v[128:131], v[216:219], v[12:15]
	v_mfma_f32_16x16x32_bf16 v[8:11], v[136:139], v[216:219], v[8:11]
	v_mfma_f32_16x16x32_bf16 v[60:63], v[132:135], v[196:199], v[60:63]
	v_mfma_f32_16x16x32_bf16 v[56:59], v[140:143], v[196:199], v[56:59]
	v_mfma_f32_16x16x32_bf16 v[44:47], v[132:135], v[204:207], v[44:47]
	v_mfma_f32_16x16x32_bf16 v[40:43], v[140:143], v[204:207], v[40:43]
	v_mfma_f32_16x16x32_bf16 v[28:31], v[132:135], v[212:215], v[28:31]
	v_mfma_f32_16x16x32_bf16 v[24:27], v[140:143], v[212:215], v[24:27]
	v_mfma_f32_16x16x32_bf16 v[12:15], v[132:135], v[220:223], v[12:15]
	v_mfma_f32_16x16x32_bf16 v[8:11], v[140:143], v[220:223], v[8:11]
	v_mfma_f32_16x16x32_bf16 v[52:55], v[144:147], v[178:181], v[52:55]
	v_mfma_f32_16x16x32_bf16 v[48:51], v[152:155], v[178:181], v[48:51]
	v_mfma_f32_16x16x32_bf16 v[36:39], v[144:147], v[200:203], v[36:39]
	v_mfma_f32_16x16x32_bf16 v[32:35], v[152:155], v[200:203], v[32:35]
	v_mfma_f32_16x16x32_bf16 v[20:23], v[144:147], v[208:211], v[20:23]
	v_mfma_f32_16x16x32_bf16 v[16:19], v[152:155], v[208:211], v[16:19]
	v_mfma_f32_16x16x32_bf16 v[4:7], v[144:147], v[216:219], v[4:7]
	v_mfma_f32_16x16x32_bf16 v[0:3], v[152:155], v[216:219], v[0:3]
	v_mfma_f32_16x16x32_bf16 v[52:55], v[148:151], v[196:199], v[52:55]
	v_mfma_f32_16x16x32_bf16 v[48:51], v[156:159], v[196:199], v[48:51]
	v_mfma_f32_16x16x32_bf16 v[36:39], v[148:151], v[204:207], v[36:39]
	v_mfma_f32_16x16x32_bf16 v[32:35], v[156:159], v[204:207], v[32:35]
	v_mfma_f32_16x16x32_bf16 v[20:23], v[148:151], v[212:215], v[20:23]
	v_mfma_f32_16x16x32_bf16 v[16:19], v[156:159], v[212:215], v[16:19]
	v_mfma_f32_16x16x32_bf16 v[4:7], v[148:151], v[220:223], v[4:7]
	v_mfma_f32_16x16x32_bf16 v[0:3], v[156:159], v[220:223], v[0:3]
	s_barrier
	s_add_i32 s52, s52, 2
	s_add_u32 s0, s0, 0x100
	s_addc_u32 s1, s1, 0
	s_add_u32 s50, s50, 0x100
	s_addc_u32 s51, s51, 0
	s_cmp_gt_u32 s52, 61
	s_cbranch_scc0 .LBB0_1563
	s_branch .Lpeel_exit_8
.LBB0_1563:
	ds_read_b128 v[128:131], v193
	ds_read_b128 v[132:135], v193 offset:1024
	ds_read_b128 v[136:139], v193 offset:2048
	ds_read_b128 v[140:143], v193 offset:3072
	ds_read_b128 v[144:147], v194
	ds_read_b128 v[148:151], v194 offset:1024
	ds_read_b128 v[152:155], v194 offset:2048
	ds_read_b128 v[156:159], v194 offset:3072
	s_add_u32 s26, s0, 0xfff00080
	s_addc_u32 s27, s1, -1
	s_cmp_eq_u32 s52, 60
	s_cselect_b32 s29, s17, s27
	s_cselect_b32 s28, s33, s26
	s_cselect_b32 s27, s15, s51
	s_cselect_b32 s26, s49, s50
	v_lshl_add_u64 v[224:225], s[0:1], 0, v[170:171]
	s_add_i32 m0, s23, 0xc000
	ds_read_b128 v[178:181], v195
	ds_read_b128 v[196:199], v195 offset:1024
	ds_read_b128 v[200:203], v195 offset:2048
	ds_read_b128 v[204:207], v195 offset:3072
	ds_read_b128 v[208:211], v195 offset:4096
	ds_read_b128 v[212:215], v195 offset:5120
	ds_read_b128 v[216:219], v195 offset:6144
	ds_read_b128 v[220:223], v195 offset:7168
	global_load_lds_dwordx4 v[224:225], off
	s_add_i32 m0, s23, 0xe000
	v_lshl_add_u64 v[224:225], s[0:1], 0, v[172:173]
	global_load_lds_dwordx4 v[224:225], off
	s_waitcnt vmcnt(8) lgkmcnt(0)
	s_barrier
	v_mfma_f32_16x16x32_bf16 v[124:127], v[128:131], v[178:181], v[124:127]
	v_mfma_f32_16x16x32_bf16 v[120:123], v[136:139], v[178:181], v[120:123]
	v_mfma_f32_16x16x32_bf16 v[108:111], v[128:131], v[200:203], v[108:111]
	v_mfma_f32_16x16x32_bf16 v[104:107], v[136:139], v[200:203], v[104:107]
	v_mfma_f32_16x16x32_bf16 v[92:95], v[128:131], v[208:211], v[92:95]
	v_mfma_f32_16x16x32_bf16 v[88:91], v[136:139], v[208:211], v[88:91]
	v_mfma_f32_16x16x32_bf16 v[76:79], v[128:131], v[216:219], v[76:79]
	v_mfma_f32_16x16x32_bf16 v[72:75], v[136:139], v[216:219], v[72:75]
	v_mfma_f32_16x16x32_bf16 v[124:127], v[132:135], v[196:199], v[124:127]
	v_mfma_f32_16x16x32_bf16 v[120:123], v[140:143], v[196:199], v[120:123]
	v_mfma_f32_16x16x32_bf16 v[108:111], v[132:135], v[204:207], v[108:111]
	v_mfma_f32_16x16x32_bf16 v[104:107], v[140:143], v[204:207], v[104:107]
	v_mfma_f32_16x16x32_bf16 v[92:95], v[132:135], v[212:215], v[92:95]
	v_mfma_f32_16x16x32_bf16 v[88:91], v[140:143], v[212:215], v[88:91]
	v_mfma_f32_16x16x32_bf16 v[76:79], v[132:135], v[220:223], v[76:79]
	v_mfma_f32_16x16x32_bf16 v[72:75], v[140:143], v[220:223], v[72:75]
	v_mfma_f32_16x16x32_bf16 v[116:119], v[144:147], v[178:181], v[116:119]
	v_mfma_f32_16x16x32_bf16 v[112:115], v[152:155], v[178:181], v[112:115]
	v_mfma_f32_16x16x32_bf16 v[100:103], v[144:147], v[200:203], v[100:103]
	v_mfma_f32_16x16x32_bf16 v[96:99], v[152:155], v[200:203], v[96:99]
	v_mfma_f32_16x16x32_bf16 v[84:87], v[144:147], v[208:211], v[84:87]
	v_mfma_f32_16x16x32_bf16 v[80:83], v[152:155], v[208:211], v[80:83]
	v_mfma_f32_16x16x32_bf16 v[68:71], v[144:147], v[216:219], v[68:71]
	v_mfma_f32_16x16x32_bf16 v[64:67], v[152:155], v[216:219], v[64:67]
	v_mfma_f32_16x16x32_bf16 v[116:119], v[148:151], v[196:199], v[116:119]
	v_mfma_f32_16x16x32_bf16 v[112:115], v[156:159], v[196:199], v[112:115]
	v_mfma_f32_16x16x32_bf16 v[100:103], v[148:151], v[204:207], v[100:103]
	v_mfma_f32_16x16x32_bf16 v[96:99], v[156:159], v[204:207], v[96:99]
	v_mfma_f32_16x16x32_bf16 v[84:87], v[148:151], v[212:215], v[84:87]
	v_mfma_f32_16x16x32_bf16 v[80:83], v[156:159], v[212:215], v[80:83]
	v_mfma_f32_16x16x32_bf16 v[68:71], v[148:151], v[220:223], v[68:71]
	v_mfma_f32_16x16x32_bf16 v[64:67], v[156:159], v[220:223], v[64:67]
	s_barrier
	s_add_i32 s53, s43, s34
	v_lshl_add_u64 v[224:225], s[26:27], 0, v[164:165]
	s_mov_b32 m0, s53
	ds_read_b128 v[178:181], v195 offset:16384
	ds_read_b128 v[196:199], v195 offset:17408
	ds_read_b128 v[200:203], v195 offset:18432
	ds_read_b128 v[204:207], v195 offset:19456
	ds_read_b128 v[208:211], v195 offset:20480
	ds_read_b128 v[212:215], v195 offset:21504
	ds_read_b128 v[216:219], v195 offset:22528
	ds_read_b128 v[220:223], v195 offset:23552
	global_load_lds_dwordx4 v[224:225], off
	s_add_i32 m0, s53, 0x2000
	s_add_u32 s54, s26, 0x100000
	v_lshl_add_u64 v[226:227], s[26:27], 0, v[168:169]
	s_addc_u32 s55, s27, 0
	s_add_i32 s53, s44, s34
	global_load_lds_dwordx4 v[226:227], off
	v_lshl_add_u64 v[228:229], s[54:55], 0, v[164:165]
	s_mov_b32 m0, s53
	v_lshl_add_u64 v[230:231], s[28:29], 0, v[166:167]
	global_load_lds_dwordx4 v[228:229], off
	s_add_i32 m0, s53, 0x2000
	v_lshl_add_u64 v[228:229], s[54:55], 0, v[168:169]
	global_load_lds_dwordx4 v[228:229], off
	s_mov_b32 m0, s23
	v_lshl_add_u64 v[228:229], s[28:29], 0, v[162:163]
	global_load_lds_dwordx4 v[228:229], off
	s_mov_b32 m0, s25
	s_nop 0
	global_load_lds_dwordx4 v[230:231], off
	s_waitcnt vmcnt(8) lgkmcnt(0)
	s_barrier
	v_mfma_f32_16x16x32_bf16 v[60:63], v[128:131], v[178:181], v[60:63]
	v_mfma_f32_16x16x32_bf16 v[56:59], v[136:139], v[178:181], v[56:59]
	v_mfma_f32_16x16x32_bf16 v[44:47], v[128:131], v[200:203], v[44:47]
	v_mfma_f32_16x16x32_bf16 v[40:43], v[136:139], v[200:203], v[40:43]
	v_mfma_f32_16x16x32_bf16 v[28:31], v[128:131], v[208:211], v[28:31]
	v_mfma_f32_16x16x32_bf16 v[24:27], v[136:139], v[208:211], v[24:27]
	v_mfma_f32_16x16x32_bf16 v[12:15], v[128:131], v[216:219], v[12:15]
	v_mfma_f32_16x16x32_bf16 v[8:11], v[136:139], v[216:219], v[8:11]
	v_mfma_f32_16x16x32_bf16 v[60:63], v[132:135], v[196:199], v[60:63]
	v_mfma_f32_16x16x32_bf16 v[56:59], v[140:143], v[196:199], v[56:59]
	v_mfma_f32_16x16x32_bf16 v[44:47], v[132:135], v[204:207], v[44:47]
	v_mfma_f32_16x16x32_bf16 v[40:43], v[140:143], v[204:207], v[40:43]
	v_mfma_f32_16x16x32_bf16 v[28:31], v[132:135], v[212:215], v[28:31]
	v_mfma_f32_16x16x32_bf16 v[24:27], v[140:143], v[212:215], v[24:27]
	v_mfma_f32_16x16x32_bf16 v[12:15], v[132:135], v[220:223], v[12:15]
	v_mfma_f32_16x16x32_bf16 v[8:11], v[140:143], v[220:223], v[8:11]
	v_mfma_f32_16x16x32_bf16 v[52:55], v[144:147], v[178:181], v[52:55]
	v_mfma_f32_16x16x32_bf16 v[48:51], v[152:155], v[178:181], v[48:51]
	v_mfma_f32_16x16x32_bf16 v[36:39], v[144:147], v[200:203], v[36:39]
	v_mfma_f32_16x16x32_bf16 v[32:35], v[152:155], v[200:203], v[32:35]
	v_mfma_f32_16x16x32_bf16 v[20:23], v[144:147], v[208:211], v[20:23]
	v_mfma_f32_16x16x32_bf16 v[16:19], v[152:155], v[208:211], v[16:19]
	v_mfma_f32_16x16x32_bf16 v[4:7], v[144:147], v[216:219], v[4:7]
	v_mfma_f32_16x16x32_bf16 v[0:3], v[152:155], v[216:219], v[0:3]
	v_mfma_f32_16x16x32_bf16 v[52:55], v[148:151], v[196:199], v[52:55]
	v_mfma_f32_16x16x32_bf16 v[48:51], v[156:159], v[196:199], v[48:51]
	v_mfma_f32_16x16x32_bf16 v[36:39], v[148:151], v[204:207], v[36:39]
	v_mfma_f32_16x16x32_bf16 v[32:35], v[156:159], v[204:207], v[32:35]
	v_mfma_f32_16x16x32_bf16 v[20:23], v[148:151], v[212:215], v[20:23]
	v_mfma_f32_16x16x32_bf16 v[16:19], v[156:159], v[212:215], v[16:19]
	v_mfma_f32_16x16x32_bf16 v[4:7], v[148:151], v[220:223], v[4:7]
	v_mfma_f32_16x16x32_bf16 v[0:3], v[156:159], v[220:223], v[0:3]
	s_barrier
	s_add_i32 s53, 0, 0x18000
	s_add_i32 s54, 0, 0x1c000
	v_add_u32_e32 v140, s53, v188
	v_add_u32_e32 v156, s54, v188
	ds_read_b128 v[128:131], v140
	ds_read_b128 v[132:135], v140 offset:1024
	ds_read_b128 v[136:139], v140 offset:2048
	ds_read_b128 v[140:143], v140 offset:3072
	ds_read_b128 v[144:147], v156
	ds_read_b128 v[148:151], v156 offset:1024
	ds_read_b128 v[152:155], v156 offset:2048
	ds_read_b128 v[156:159], v156 offset:3072
	s_add_u32 s28, s28, 0x100000
	s_addc_u32 s29, s29, 0
	s_mov_b32 m0, s35
	v_lshl_add_u64 v[232:233], s[28:29], 0, v[162:163]
	ds_read_b128 v[178:181], v195 offset:32768
	ds_read_b128 v[196:199], v195 offset:33792
	ds_read_b128 v[200:203], v195 offset:34816
	ds_read_b128 v[204:207], v195 offset:35840
	ds_read_b128 v[208:211], v195 offset:36864
	ds_read_b128 v[212:215], v195 offset:37888
	ds_read_b128 v[216:219], v195 offset:38912
	ds_read_b128 v[220:223], v195 offset:39936
	global_load_lds_dwordx4 v[232:233], off
	s_mov_b32 m0, s36
	v_lshl_add_u64 v[232:233], s[28:29], 0, v[166:167]
	global_load_lds_dwordx4 v[232:233], off
	s_waitcnt vmcnt(8) lgkmcnt(0)
	s_barrier
	v_mfma_f32_16x16x32_bf16 v[124:127], v[128:131], v[178:181], v[124:127]
	v_mfma_f32_16x16x32_bf16 v[120:123], v[136:139], v[178:181], v[120:123]
	v_mfma_f32_16x16x32_bf16 v[108:111], v[128:131], v[200:203], v[108:111]
	v_mfma_f32_16x16x32_bf16 v[104:107], v[136:139], v[200:203], v[104:107]
	v_mfma_f32_16x16x32_bf16 v[92:95], v[128:131], v[208:211], v[92:95]
	v_mfma_f32_16x16x32_bf16 v[88:91], v[136:139], v[208:211], v[88:91]
	v_mfma_f32_16x16x32_bf16 v[76:79], v[128:131], v[216:219], v[76:79]
	v_mfma_f32_16x16x32_bf16 v[72:75], v[136:139], v[216:219], v[72:75]
	v_mfma_f32_16x16x32_bf16 v[124:127], v[132:135], v[196:199], v[124:127]
	v_mfma_f32_16x16x32_bf16 v[120:123], v[140:143], v[196:199], v[120:123]
	v_mfma_f32_16x16x32_bf16 v[108:111], v[132:135], v[204:207], v[108:111]
	v_mfma_f32_16x16x32_bf16 v[104:107], v[140:143], v[204:207], v[104:107]
	v_mfma_f32_16x16x32_bf16 v[92:95], v[132:135], v[212:215], v[92:95]
	v_mfma_f32_16x16x32_bf16 v[88:91], v[140:143], v[212:215], v[88:91]
	v_mfma_f32_16x16x32_bf16 v[76:79], v[132:135], v[220:223], v[76:79]
	v_mfma_f32_16x16x32_bf16 v[72:75], v[140:143], v[220:223], v[72:75]
	v_mfma_f32_16x16x32_bf16 v[116:119], v[144:147], v[178:181], v[116:119]
	v_mfma_f32_16x16x32_bf16 v[112:115], v[152:155], v[178:181], v[112:115]
	v_mfma_f32_16x16x32_bf16 v[100:103], v[144:147], v[200:203], v[100:103]
	v_mfma_f32_16x16x32_bf16 v[96:99], v[152:155], v[200:203], v[96:99]
	v_mfma_f32_16x16x32_bf16 v[84:87], v[144:147], v[208:211], v[84:87]
	v_mfma_f32_16x16x32_bf16 v[80:83], v[152:155], v[208:211], v[80:83]
	v_mfma_f32_16x16x32_bf16 v[68:71], v[144:147], v[216:219], v[68:71]
	v_mfma_f32_16x16x32_bf16 v[64:67], v[152:155], v[216:219], v[64:67]
	v_mfma_f32_16x16x32_bf16 v[116:119], v[148:151], v[196:199], v[116:119]
	v_mfma_f32_16x16x32_bf16 v[112:115], v[156:159], v[196:199], v[112:115]
	v_mfma_f32_16x16x32_bf16 v[100:103], v[148:151], v[204:207], v[100:103]
	v_mfma_f32_16x16x32_bf16 v[96:99], v[156:159], v[204:207], v[96:99]
	v_mfma_f32_16x16x32_bf16 v[84:87], v[148:151], v[212:215], v[84:87]
	v_mfma_f32_16x16x32_bf16 v[80:83], v[156:159], v[212:215], v[80:83]
	v_mfma_f32_16x16x32_bf16 v[68:71], v[148:151], v[220:223], v[68:71]
	v_mfma_f32_16x16x32_bf16 v[64:67], v[156:159], v[220:223], v[64:67]
	s_barrier
	s_add_i32 s28, s53, s34
	v_lshl_add_u64 v[224:225], v[224:225], 0, s[10:11]
	s_mov_b32 m0, s28
	ds_read_b128 v[178:181], v195 offset:49152
	ds_read_b128 v[196:199], v195 offset:50176
	ds_read_b128 v[200:203], v195 offset:51200
	ds_read_b128 v[204:207], v195 offset:52224
	ds_read_b128 v[208:211], v195 offset:53248
	ds_read_b128 v[212:215], v195 offset:54272
	ds_read_b128 v[216:219], v195 offset:55296
	ds_read_b128 v[220:223], v195 offset:56320
	global_load_lds_dwordx4 v[224:225], off
	s_add_i32 m0, s28, 0x2000
	s_add_u32 s26, s26, 0x100080
	v_lshl_add_u64 v[224:225], v[226:227], 0, s[10:11]
	s_addc_u32 s27, s27, 0
	s_add_i32 s28, s54, s34
	global_load_lds_dwordx4 v[224:225], off
	s_mov_b32 m0, s28
	v_lshl_add_u64 v[224:225], s[26:27], 0, v[164:165]
	global_load_lds_dwordx4 v[224:225], off
	s_add_i32 m0, s28, 0x2000
	v_lshl_add_u64 v[224:225], s[26:27], 0, v[168:169]
	global_load_lds_dwordx4 v[224:225], off
	s_mov_b32 m0, s39
	v_lshl_add_u64 v[224:225], v[228:229], 0, s[10:11]
	global_load_lds_dwordx4 v[224:225], off
	s_mov_b32 m0, s40
	v_lshl_add_u64 v[224:225], v[230:231], 0, s[10:11]
	global_load_lds_dwordx4 v[224:225], off
	s_waitcnt vmcnt(8) lgkmcnt(0)
	s_barrier
	v_mfma_f32_16x16x32_bf16 v[60:63], v[128:131], v[178:181], v[60:63]
	v_mfma_f32_16x16x32_bf16 v[56:59], v[136:139], v[178:181], v[56:59]
	v_mfma_f32_16x16x32_bf16 v[44:47], v[128:131], v[200:203], v[44:47]
	v_mfma_f32_16x16x32_bf16 v[40:43], v[136:139], v[200:203], v[40:43]
	v_mfma_f32_16x16x32_bf16 v[28:31], v[128:131], v[208:211], v[28:31]
	v_mfma_f32_16x16x32_bf16 v[24:27], v[136:139], v[208:211], v[24:27]
	v_mfma_f32_16x16x32_bf16 v[12:15], v[128:131], v[216:219], v[12:15]
	v_mfma_f32_16x16x32_bf16 v[8:11], v[136:139], v[216:219], v[8:11]
	v_mfma_f32_16x16x32_bf16 v[60:63], v[132:135], v[196:199], v[60:63]
	v_mfma_f32_16x16x32_bf16 v[56:59], v[140:143], v[196:199], v[56:59]
	v_mfma_f32_16x16x32_bf16 v[44:47], v[132:135], v[204:207], v[44:47]
	v_mfma_f32_16x16x32_bf16 v[40:43], v[140:143], v[204:207], v[40:43]
	v_mfma_f32_16x16x32_bf16 v[28:31], v[132:135], v[212:215], v[28:31]
	v_mfma_f32_16x16x32_bf16 v[24:27], v[140:143], v[212:215], v[24:27]
	v_mfma_f32_16x16x32_bf16 v[12:15], v[132:135], v[220:223], v[12:15]
	v_mfma_f32_16x16x32_bf16 v[8:11], v[140:143], v[220:223], v[8:11]
	v_mfma_f32_16x16x32_bf16 v[52:55], v[144:147], v[178:181], v[52:55]
	v_mfma_f32_16x16x32_bf16 v[48:51], v[152:155], v[178:181], v[48:51]
	v_mfma_f32_16x16x32_bf16 v[36:39], v[144:147], v[200:203], v[36:39]
	v_mfma_f32_16x16x32_bf16 v[32:35], v[152:155], v[200:203], v[32:35]
	v_mfma_f32_16x16x32_bf16 v[20:23], v[144:147], v[208:211], v[20:23]
	v_mfma_f32_16x16x32_bf16 v[16:19], v[152:155], v[208:211], v[16:19]
	v_mfma_f32_16x16x32_bf16 v[4:7], v[144:147], v[216:219], v[4:7]
	v_mfma_f32_16x16x32_bf16 v[0:3], v[152:155], v[216:219], v[0:3]
	v_mfma_f32_16x16x32_bf16 v[52:55], v[148:151], v[196:199], v[52:55]
	v_mfma_f32_16x16x32_bf16 v[48:51], v[156:159], v[196:199], v[48:51]
	v_mfma_f32_16x16x32_bf16 v[36:39], v[148:151], v[204:207], v[36:39]
	v_mfma_f32_16x16x32_bf16 v[32:35], v[156:159], v[204:207], v[32:35]
	v_mfma_f32_16x16x32_bf16 v[20:23], v[148:151], v[212:215], v[20:23]
	v_mfma_f32_16x16x32_bf16 v[16:19], v[156:159], v[212:215], v[16:19]
	v_mfma_f32_16x16x32_bf16 v[4:7], v[148:151], v[220:223], v[4:7]
	v_mfma_f32_16x16x32_bf16 v[0:3], v[156:159], v[220:223], v[0:3]
	s_barrier
	s_add_i32 s52, s52, 2
	s_add_u32 s0, s0, 0x100
	s_addc_u32 s1, s1, 0
	s_add_u32 s50, s50, 0x100
	s_addc_u32 s51, s51, 0
	s_cmp_gt_u32 s52, 61
	s_cbranch_scc0 .LBB0_1563
